# sc1 (agent-scope write-through) on the 16-byte bulk stores of the phases in front of grid barriers, so the L2 write-back at the barrier has little left to flush; on top of v21
# speedup vs baseline: 1.0219x; 1.0027x over previous
; template <int MODE>
; __device__ __forceinline__ void p0_transpose_item(const float* W, int K, int N, bf16* WT, LAS float* scr, int item, int lane, const float* ga, const float* gb) {
;     ...
;     for (int i = 0; i < 32; ++i) { const int kk = 2 * i + (lane >> 5), k = k0 + kk; float g = 1.0f;
;         if (MODE == 0 || MODE == 2) g = ga[k];
;         if (MODE == 1) g = (k < 512) ? ga[k] : gb[k - 512];
;         scr[kk * 33 + (lane & 31)] = W[(size_t)k * N + n0 + (lane & 31)] * g; }
.LBB0_26:
	s_lshl_b32 s6, s2, 1
	s_lshl_b32 s7, s4, 1
	v_or_b32_e32 v19, s6, v1
	v_or_b32_e32 v20, s7, v0
	s_add_i32 s9, s7, 4
	s_add_i32 s8, s6, 4
	s_add_i32 s10, s6, 8
	s_add_i32 s11, s7, 8
	s_add_i32 s12, s6, 12
	s_add_i32 s16, s6, 16
	s_add_i32 s19, s6, 20
	s_add_i32 s64, s6, 24
	s_add_i32 s6, s6, 28
	v_add_lshl_u32 v4, v19, s3, 10
	v_add_lshl_u32 v24, v20, s1, 10
	v_or_b32_e32 v43, s9, v0
	s_add_i32 s13, s7, 12
	v_or_b32_e32 v42, s8, v1
	v_or_b32_e32 v44, s10, v1
	v_or_b32_e32 v45, s11, v0
	v_or_b32_e32 v46, s12, v1
	v_or_b32_e32 v48, s16, v1
	v_or_b32_e32 v50, s19, v1
	v_or_b32_e32 v52, s64, v1
	v_or_b32_e32 v59, s6, v1
	v_or_b32_e32 v22, v3, v4
	v_or_b32_e32 v4, v18, v24
	v_add_lshl_u32 v26, v43, s1, 10
	v_mov_b32_e32 v23, v5
	s_add_i32 s17, s7, 16
	v_or_b32_e32 v47, s13, v0
	v_add_lshl_u32 v24, v42, s3, 10
	v_add_lshl_u32 v28, v44, s3, 10
	v_add_lshl_u32 v61, v45, s1, 10
	v_add_lshl_u32 v30, v46, s3, 10
	v_add_lshl_u32 v32, v48, s3, 10
	v_add_lshl_u32 v34, v50, s3, 10
	v_add_lshl_u32 v36, v52, s3, 10
	v_add_lshl_u32 v40, v59, s3, 10
	v_lshl_add_u64 v[38:39], v[4:5], 2, s[66:67]
	v_or_b32_e32 v4, v18, v26
	v_mov_b32_e32 v25, v5
	s_add_i32 s35, s7, 20
	v_or_b32_e32 v49, s17, v0
	v_add_lshl_u32 v62, v47, s1, 10
	v_lshl_add_u64 v[22:23], v[22:23], 2, s[66:67]
	v_or_b32_e32 v24, v3, v24
	v_or_b32_e32 v26, v3, v28
	v_or_b32_e32 v28, v3, v30
	v_or_b32_e32 v30, v3, v32
	v_or_b32_e32 v32, v3, v34
	v_or_b32_e32 v34, v3, v36
	v_or_b32_e32 v36, v3, v40
	v_lshl_add_u64 v[40:41], v[4:5], 2, s[66:67]
	v_or_b32_e32 v4, v18, v61
	s_add_i32 s65, s7, 24
	v_or_b32_e32 v51, s35, v0
	v_add_lshl_u32 v63, v49, s1, 10
	v_lshl_add_u64 v[24:25], v[24:25], 2, s[66:67]
	global_load_dword v61, v[38:39], off
	global_load_dword v67, v[22:23], off
	global_load_dword v68, v[40:41], off
	global_load_dword v69, v[24:25], off
	v_lshl_add_u64 v[22:23], v[4:5], 2, s[66:67]
	v_or_b32_e32 v4, v18, v62
	v_mov_b32_e32 v27, v5
	v_mov_b32_e32 v29, v5
	s_add_i32 s7, s7, 28
	v_or_b32_e32 v53, s65, v0
	v_add_lshl_u32 v64, v51, s1, 10
	v_lshl_add_u64 v[24:25], v[4:5], 2, s[66:67]
	v_or_b32_e32 v4, v18, v63
	v_or_b32_e32 v60, s7, v0
	v_add_lshl_u32 v65, v53, s1, 10
	v_lshl_add_u64 v[26:27], v[26:27], 2, s[66:67]
	v_lshl_add_u64 v[28:29], v[28:29], 2, s[66:67]
	global_load_dword v62, v[22:23], off
	global_load_dword v63, v[26:27], off
	global_load_dword v70, v[24:25], off
	global_load_dword v71, v[28:29], off
	v_lshl_add_u64 v[22:23], v[4:5], 2, s[66:67]
	v_or_b32_e32 v4, v18, v64
	v_mov_b32_e32 v31, v5
	v_mov_b32_e32 v33, v5
	v_add_lshl_u32 v66, v60, s1, 10
	v_lshl_add_u64 v[24:25], v[4:5], 2, s[66:67]
	v_or_b32_e32 v4, v18, v65
	v_mov_b32_e32 v35, v5
	v_mov_b32_e32 v37, v5
	v_lshl_add_u64 v[30:31], v[30:31], 2, s[66:67]
	v_lshl_add_u64 v[32:33], v[32:33], 2, s[66:67]
	global_load_dword v64, v[22:23], off
	global_load_dword v65, v[30:31], off
	global_load_dword v72, v[24:25], off
	global_load_dword v73, v[32:33], off
	v_lshl_add_u64 v[22:23], v[4:5], 2, s[66:67]
	v_or_b32_e32 v4, v18, v66
	v_lshl_add_u64 v[34:35], v[34:35], 2, s[66:67]
	v_lshl_add_u64 v[36:37], v[36:37], 2, s[66:67]
	v_lshl_add_u64 v[24:25], v[4:5], 2, s[66:67]
	global_load_dword v4, v[22:23], off
	global_load_dword v66, v[34:35], off
	global_load_dword v74, v[24:25], off
	global_load_dword v75, v[36:37], off
	s_add_i32 s4, s4, 16
	s_add_i32 s2, s2, 16
	s_add_i32 s5, s5, -16
	v_mad_u64_u32 v[22:23], s[6:7], v20, s14, v[2:3]
	s_cmp_lg_u32 s5, 0
	v_mad_u64_u32 v[24:25], s[6:7], v19, s14, v[2:3]
	v_mad_u64_u32 v[26:27], s[6:7], v43, s14, v[2:3]
	v_mad_u64_u32 v[28:29], s[6:7], v42, s14, v[2:3]
	v_mad_u64_u32 v[30:31], s[6:7], v45, s14, v[2:3]
	v_mad_u64_u32 v[32:33], s[6:7], v44, s14, v[2:3]
	v_mad_u64_u32 v[34:35], s[6:7], v47, s14, v[2:3]
	v_mad_u64_u32 v[36:37], s[6:7], v46, s14, v[2:3]
	v_mad_u64_u32 v[38:39], s[6:7], v49, s14, v[2:3]
	v_mad_u64_u32 v[40:41], s[6:7], v48, s14, v[2:3]
	v_mad_u64_u32 v[42:43], s[6:7], v51, s14, v[2:3]
	v_mad_u64_u32 v[44:45], s[6:7], v50, s14, v[2:3]
	v_mad_u64_u32 v[46:47], s[6:7], v53, s14, v[2:3]
	v_mad_u64_u32 v[48:49], s[6:7], v52, s14, v[2:3]
	v_mad_u64_u32 v[50:51], s[6:7], v60, s14, v[2:3]
	v_mad_u64_u32 v[52:53], s[6:7], v59, s14, v[2:3]
	s_waitcnt vmcnt(15)
	ds_write_b32 v22, v61
	s_waitcnt vmcnt(14)
	ds_write_b32 v24, v67
	s_waitcnt vmcnt(13)
	ds_write_b32 v26, v68
	s_waitcnt vmcnt(12)
	ds_write_b32 v28, v69
	s_waitcnt vmcnt(11)
	ds_write_b32 v30, v62
	s_waitcnt vmcnt(10)
	ds_write_b32 v32, v63
	s_waitcnt vmcnt(9)
	ds_write_b32 v34, v70
	s_waitcnt vmcnt(8)
	ds_write_b32 v36, v71
	s_waitcnt vmcnt(7)
	ds_write_b32 v38, v64
	s_waitcnt vmcnt(6)
	ds_write_b32 v40, v65
	s_waitcnt vmcnt(5)
	ds_write_b32 v42, v72
	s_waitcnt vmcnt(4)
	ds_write_b32 v44, v73
	s_waitcnt vmcnt(3)
	ds_write_b32 v46, v4
	s_waitcnt vmcnt(2)
	ds_write_b32 v48, v66
	s_waitcnt vmcnt(1)
	ds_write_b32 v50, v74
	s_waitcnt vmcnt(0)
	ds_write_b32 v52, v75
	s_cbranch_scc1 .LBB0_26
; #define LAS __attribute__((address_space(3)))
; #define LDS_WAIT() asm volatile("s_waitcnt lgkmcnt(0)" ::: "memory")
; __device__ __forceinline__ unsigned pk2(float lo, float hi) { return pg8::cvt_pk_bf16(lo, hi); }
; template <int MODE>
; __device__ __forceinline__ void p0_transpose_item(const float* W, int K, int N, bf16* WT, LAS float* scr, int item, int lane, const float* ga, const float* gb) {
;     ...
;     const int c = lane & 7;
; #pragma unroll
;     for (int j = 0; j < 4; ++j) { const int n = (lane >> 3) + 8 * j; const LAS float* s = scr + (8 * c) * 33 + n;
;         v4u o; o.x = pk2(s[0 * 33], s[1 * 33]); o.y = pk2(s[2 * 33], s[3 * 33]); o.z = pk2(s[4 * 33], s[5 * 33]); o.w = pk2(s[6 * 33], s[7 * 33]);
;         int nn = n0 + n;
;         if (MODE == 2) { const int up = nn >= DFF ? 1 : 0, f = nn - up * DFF; nn = (f >> 7) * 256 + up * 128 + (f & 127); }
;         *(v4u*)(WT + (size_t)nn * K + k0 + 8 * c) = o; }
;     LDS_WAIT();
	s_waitcnt lgkmcnt(0)
	ds_read2_b32 v[18:19], v55 offset1:33
	s_waitcnt lgkmcnt(0)
	v_cvt_pk_bf16_f32 v22, v18, v19
	ds_read2_b32 v[18:19], v55 offset0:66 offset1:99
	v_or_b32_e32 v3, s0, v54
	s_waitcnt lgkmcnt(0)
	v_cvt_pk_bf16_f32 v23, v18, v19
	ds_read2_b32 v[18:19], v55 offset0:132 offset1:165
	s_lshl_b32 s86, s1, 1
	v_mul_u32_u24_e32 v3, 0xb00, v3
	s_waitcnt lgkmcnt(0)
	v_cvt_pk_bf16_f32 v24, v18, v19
	ds_read2_b32 v[18:19], v55 offset0:198 offset1:231
	v_lshl_add_u64 v[26:27], v[6:7], 0, s[86:87]
	v_lshlrev_b32_e32 v4, 1, v3
	s_waitcnt lgkmcnt(0)
	v_cvt_pk_bf16_f32 v25, v18, v19
	ds_read2_b32 v[18:19], v55 offset0:8 offset1:41
	v_lshl_add_u64 v[28:29], v[26:27], 0, v[4:5]
	global_store_dwordx4 v[28:29], v[22:25], off sc1
	v_or_b32_e32 v3, s0, v56
	v_mul_u32_u24_e32 v3, 0xb00, v3
	s_waitcnt lgkmcnt(0)
	v_cvt_pk_bf16_f32 v22, v18, v19
	ds_read2_b32 v[18:19], v55 offset0:74 offset1:107
	s_waitcnt lgkmcnt(0)
	v_cvt_pk_bf16_f32 v23, v18, v19
	ds_read2_b32 v[18:19], v55 offset0:140 offset1:173
	s_waitcnt lgkmcnt(0)
	v_cvt_pk_bf16_f32 v24, v18, v19
	ds_read2_b32 v[18:19], v55 offset0:206 offset1:239
	v_lshlrev_b32_e32 v4, 1, v3
	s_waitcnt lgkmcnt(0)
	v_cvt_pk_bf16_f32 v25, v18, v19
	ds_read2_b32 v[18:19], v55 offset0:16 offset1:49
	v_lshl_add_u64 v[28:29], v[26:27], 0, v[4:5]
	global_store_dwordx4 v[28:29], v[22:25], off sc1
	v_or_b32_e32 v3, s0, v57
	v_mul_u32_u24_e32 v3, 0xb00, v3
	s_waitcnt lgkmcnt(0)
	v_cvt_pk_bf16_f32 v22, v18, v19
	ds_read2_b32 v[18:19], v55 offset0:82 offset1:115
	s_waitcnt lgkmcnt(0)
	v_cvt_pk_bf16_f32 v23, v18, v19
	ds_read2_b32 v[18:19], v55 offset0:148 offset1:181
	s_waitcnt lgkmcnt(0)
	v_cvt_pk_bf16_f32 v24, v18, v19
	ds_read2_b32 v[18:19], v55 offset0:214 offset1:247
	v_lshlrev_b32_e32 v4, 1, v3
	s_waitcnt lgkmcnt(0)
	v_cvt_pk_bf16_f32 v25, v18, v19
	ds_read2_b32 v[18:19], v55 offset0:24 offset1:57
	v_lshl_add_u64 v[28:29], v[26:27], 0, v[4:5]
	global_store_dwordx4 v[28:29], v[22:25], off sc1
	v_or_b32_e32 v3, s0, v58
	v_mul_u32_u24_e32 v3, 0xb00, v3
	s_waitcnt lgkmcnt(0)
	v_cvt_pk_bf16_f32 v22, v18, v19
	ds_read2_b32 v[18:19], v55 offset0:90 offset1:123
	s_waitcnt lgkmcnt(0)
	v_cvt_pk_bf16_f32 v23, v18, v19
	ds_read2_b32 v[18:19], v55 offset0:156 offset1:189
	s_waitcnt lgkmcnt(0)
	v_cvt_pk_bf16_f32 v24, v18, v19
	ds_read2_b32 v[18:19], v55 offset0:222 offset1:255
	v_lshlrev_b32_e32 v4, 1, v3
	s_waitcnt lgkmcnt(0)
	v_cvt_pk_bf16_f32 v25, v18, v19
	v_lshl_add_u64 v[18:19], v[26:27], 0, v[4:5]
	global_store_dwordx4 v[18:19], v[22:25], off sc1
	s_waitcnt lgkmcnt(0)
	s_mov_b64 s[0:1], 0

; template <int MODE>
; __device__ __forceinline__ void p0_transpose_item(const float* W, int K, int N, bf16* WT, LAS float* scr, int item, int lane, const float* ga, const float* gb) {
;     ...
;     for (int i = 0; i < 32; ++i) { const int kk = 2 * i + (lane >> 5), k = k0 + kk; float g = 1.0f;
;         if (MODE == 0 || MODE == 2) g = ga[k];
;         if (MODE == 1) g = (k < 512) ? ga[k] : gb[k - 512];
;         scr[kk * 33 + (lane & 31)] = W[(size_t)k * N + n0 + (lane & 31)] * g; }
.LBB0_30:
	s_lshl_b32 s6, s3, 1
	s_lshl_b32 s7, s4, 1
	v_mov_b32_e32 v23, v5
	v_or_b32_e32 v22, s6, v3
	v_or_b32_e32 v4, s7, v20
	s_add_i32 s10, s6, 4
	s_add_i32 s11, s7, 4
	v_mov_b32_e32 v25, v5
	s_add_i32 s12, s6, 8
	s_add_i32 s13, s7, 8
	v_lshl_add_u64 v[38:39], v[4:5], 2, s[62:63]
	v_lshl_add_u64 v[40:41], v[22:23], 2, s[62:63]
	v_mad_u64_u32 v[42:43], s[8:9], v4, s15, v[18:19]
	v_mad_u64_u32 v[22:23], s[8:9], v22, s15, v[18:19]
	v_or_b32_e32 v24, s10, v3
	v_or_b32_e32 v4, s11, v20
	v_mov_b32_e32 v27, v5
	s_add_i32 s16, s6, 12
	s_add_i32 s17, s7, 12
	v_or_b32_e32 v26, s12, v3
	global_load_dword v38, v[38:39], off
	s_nop 0
	global_load_dword v39, v[40:41], off
	s_nop 0
	global_load_dword v40, v[42:43], off
	global_load_dword v41, v[22:23], off
	v_lshl_add_u64 v[22:23], v[4:5], 2, s[62:63]
	v_lshl_add_u64 v[42:43], v[24:25], 2, s[62:63]
	v_mad_u64_u32 v[44:45], s[8:9], v4, s15, v[18:19]
	v_mad_u64_u32 v[24:25], s[8:9], v24, s15, v[18:19]
	v_or_b32_e32 v4, s13, v20
	v_mov_b32_e32 v29, v5
	s_add_i32 s19, s6, 16
	s_add_i32 s35, s7, 16
	v_or_b32_e32 v28, s16, v3
	v_lshl_add_u64 v[46:47], v[26:27], 2, s[62:63]
	v_mad_u64_u32 v[26:27], s[8:9], v26, s15, v[18:19]
	global_load_dword v22, v[22:23], off
	s_nop 0
	global_load_dword v23, v[42:43], off
	s_nop 0
	global_load_dword v42, v[44:45], off
	global_load_dword v43, v[24:25], off
	v_lshl_add_u64 v[24:25], v[4:5], 2, s[62:63]
	v_mad_u64_u32 v[44:45], s[8:9], v4, s15, v[18:19]
	v_or_b32_e32 v4, s17, v20
	v_mov_b32_e32 v31, v5
	s_add_i32 s64, s6, 20
	s_add_i32 s65, s7, 20
	v_or_b32_e32 v30, s19, v3
	v_lshl_add_u64 v[48:49], v[28:29], 2, s[62:63]
	v_mad_u64_u32 v[28:29], s[8:9], v28, s15, v[18:19]
	global_load_dword v24, v[24:25], off
	s_nop 0
	global_load_dword v25, v[46:47], off
	s_nop 0
	global_load_dword v44, v[44:45], off
	s_nop 0
	global_load_dword v45, v[26:27], off
	v_lshl_add_u64 v[26:27], v[4:5], 2, s[62:63]
	v_mad_u64_u32 v[46:47], s[8:9], v4, s15, v[18:19]
	v_or_b32_e32 v4, s35, v20
	v_mov_b32_e32 v33, v5
	s_add_i32 s70, s6, 24
	s_add_i32 s71, s7, 24
	v_or_b32_e32 v32, s64, v3
	v_lshl_add_u64 v[50:51], v[30:31], 2, s[62:63]
	v_mad_u64_u32 v[30:31], s[8:9], v30, s15, v[18:19]
	global_load_dword v26, v[26:27], off
	s_nop 0
	global_load_dword v27, v[48:49], off
	s_nop 0
	global_load_dword v46, v[46:47], off
	s_nop 0
	global_load_dword v47, v[28:29], off
	v_lshl_add_u64 v[28:29], v[4:5], 2, s[62:63]
	v_mad_u64_u32 v[48:49], s[8:9], v4, s15, v[18:19]
	v_or_b32_e32 v4, s65, v20
	v_mov_b32_e32 v35, v5
	s_add_i32 s78, s7, 28
	v_or_b32_e32 v34, s70, v3
	v_lshl_add_u64 v[52:53], v[32:33], 2, s[62:63]
	v_mad_u64_u32 v[32:33], s[8:9], v32, s15, v[18:19]
	global_load_dword v28, v[28:29], off
	s_nop 0
	global_load_dword v29, v[50:51], off
	s_nop 0
	global_load_dword v48, v[48:49], off
	s_nop 0
	global_load_dword v49, v[30:31], off
	v_lshl_add_u64 v[30:31], v[4:5], 2, s[62:63]
	v_mad_u64_u32 v[50:51], s[8:9], v4, s15, v[18:19]
	v_or_b32_e32 v4, s71, v20
	s_add_i32 s75, s6, 28
	v_lshl_add_u64 v[60:61], v[34:35], 2, s[62:63]
	v_mad_u64_u32 v[34:35], s[8:9], v34, s15, v[18:19]
	global_load_dword v30, v[30:31], off
	s_nop 0
	global_load_dword v31, v[52:53], off
	s_nop 0
	global_load_dword v50, v[50:51], off
	s_nop 0
	global_load_dword v51, v[32:33], off
	v_lshl_add_u64 v[32:33], v[4:5], 2, s[62:63]
	v_mad_u64_u32 v[52:53], s[8:9], v4, s15, v[18:19]
	v_or_b32_e32 v4, s78, v20
	v_mov_b32_e32 v37, v5
	v_or_b32_e32 v36, s75, v3
	global_load_dword v32, v[32:33], off
	s_nop 0
	global_load_dword v33, v[60:61], off
	s_nop 0
	global_load_dword v52, v[52:53], off
	s_nop 0
	global_load_dword v53, v[34:35], off
	v_lshl_add_u64 v[34:35], v[4:5], 2, s[62:63]
	v_mad_u64_u32 v[60:61], s[8:9], v4, s15, v[18:19]
	v_lshl_add_u64 v[62:63], v[36:37], 2, s[62:63]
	v_mad_u64_u32 v[36:37], s[8:9], v36, s15, v[18:19]
	global_load_dword v34, v[34:35], off
	s_nop 0
	global_load_dword v35, v[62:63], off
	s_nop 0
	global_load_dword v60, v[60:61], off
	s_nop 0
	global_load_dword v61, v[36:37], off
	v_or_b32_e32 v36, s7, v0
	v_or_b32_e32 v4, s6, v1
	v_mad_u64_u32 v[36:37], s[6:7], v36, s14, v[2:3]
	v_mad_u64_u32 v[62:63], s[6:7], v4, s14, v[2:3]
	v_or_b32_e32 v37, s11, v0
	v_or_b32_e32 v4, s10, v1
	v_or_b32_e32 v63, s13, v0
	v_mad_u64_u32 v[64:65], s[6:7], v37, s14, v[2:3]
	s_waitcnt vmcnt(28)
	v_pk_mul_f32 v[38:39], v[38:39], v[40:41]
	v_or_b32_e32 v59, s12, v1
	v_or_b32_e32 v72, s17, v0
	v_mad_u64_u32 v[66:67], s[6:7], v4, s14, v[2:3]
	v_mad_u64_u32 v[68:69], s[6:7], v63, s14, v[2:3]
	ds_write_b32 v36, v38
	ds_write_b32 v62, v39
	v_or_b32_e32 v74, s16, v1
	v_or_b32_e32 v76, s35, v0
	s_waitcnt vmcnt(24)
	v_pk_mul_f32 v[22:23], v[22:23], v[42:43]
	ds_write_b32 v64, v22
	ds_write_b32 v66, v23
	v_mad_u64_u32 v[70:71], s[6:7], v59, s14, v[2:3]
	v_mad_u64_u32 v[72:73], s[6:7], v72, s14, v[2:3]
	v_or_b32_e32 v78, s19, v1
	v_or_b32_e32 v80, s65, v0
	v_mad_u64_u32 v[74:75], s[6:7], v74, s14, v[2:3]
	v_mad_u64_u32 v[76:77], s[6:7], v76, s14, v[2:3]
	s_waitcnt vmcnt(20)
	v_pk_mul_f32 v[22:23], v[24:25], v[44:45]
	ds_write_b32 v68, v22
	ds_write_b32 v70, v23
	v_or_b32_e32 v82, s64, v1
	v_or_b32_e32 v84, s71, v0
	v_mad_u64_u32 v[78:79], s[6:7], v78, s14, v[2:3]
	v_mad_u64_u32 v[80:81], s[6:7], v80, s14, v[2:3]
	s_add_i32 s4, s4, 16
	s_add_i32 s3, s3, 16
	s_add_i32 s5, s5, -16
	v_or_b32_e32 v86, s70, v1
	s_waitcnt vmcnt(16)
	v_pk_mul_f32 v[22:23], v[26:27], v[46:47]
	ds_write_b32 v72, v22
	ds_write_b32 v74, v23
	v_or_b32_e32 v88, s78, v0
	v_mad_u64_u32 v[82:83], s[6:7], v82, s14, v[2:3]
	v_mad_u64_u32 v[84:85], s[6:7], v84, s14, v[2:3]
	v_or_b32_e32 v90, s75, v1
	s_cmp_lg_u32 s5, 0
	v_mad_u64_u32 v[86:87], s[6:7], v86, s14, v[2:3]
	s_waitcnt vmcnt(12)
	v_pk_mul_f32 v[22:23], v[28:29], v[48:49]
	ds_write_b32 v76, v22
	ds_write_b32 v78, v23
	v_mad_u64_u32 v[88:89], s[6:7], v88, s14, v[2:3]
	v_mad_u64_u32 v[90:91], s[6:7], v90, s14, v[2:3]
	s_waitcnt vmcnt(8)
	v_pk_mul_f32 v[22:23], v[30:31], v[50:51]
	ds_write_b32 v80, v22
	ds_write_b32 v82, v23
	s_waitcnt vmcnt(4)
	v_pk_mul_f32 v[22:23], v[32:33], v[52:53]
	ds_write_b32 v84, v22
	ds_write_b32 v86, v23
	s_waitcnt vmcnt(0)
	v_pk_mul_f32 v[22:23], v[34:35], v[60:61]
	ds_write_b32 v88, v22
	ds_write_b32 v90, v23
	s_cbranch_scc1 .LBB0_30
; #define LAS __attribute__((address_space(3)))
; #define LDS_WAIT() asm volatile("s_waitcnt lgkmcnt(0)" ::: "memory")
; __device__ __forceinline__ unsigned pk2(float lo, float hi) { return pg8::cvt_pk_bf16(lo, hi); }
; template <int MODE>
; __device__ __forceinline__ void p0_transpose_item(const float* W, int K, int N, bf16* WT, LAS float* scr, int item, int lane, const float* ga, const float* gb) {
;     ...
;     const int c = lane & 7;
; #pragma unroll
;     for (int j = 0; j < 4; ++j) { const int n = (lane >> 3) + 8 * j; const LAS float* s = scr + (8 * c) * 33 + n;
;         v4u o; o.x = pk2(s[0 * 33], s[1 * 33]); o.y = pk2(s[2 * 33], s[3 * 33]); o.z = pk2(s[4 * 33], s[5 * 33]); o.w = pk2(s[6 * 33], s[7 * 33]);
;         int nn = n0 + n;
;         if (MODE == 2) { const int up = nn >= DFF ? 1 : 0, f = nn - up * DFF; nn = (f >> 7) * 256 + up * 128 + (f & 127); }
;         *(v4u*)(WT + (size_t)nn * K + k0 + 8 * c) = o; }
;     LDS_WAIT();
	s_and_b32 s1, 0xffff, s1
	s_and_b32 s2, 0xffff, s2
	s_and_b32 s0, 0xffff, s0
	s_lshl_b32 s86, s1, 1
	s_cmpk_gt_u32 s0, 0x57
	s_cselect_b32 s0, 0xfffff500, 0
	s_waitcnt lgkmcnt(0)
	s_cselect_b32 s1, 0x80, 0
	s_add_i32 s4, s0, s2
	ds_read2_b32 v[18:19], v55 offset1:33
	s_lshl_b32 s4, s4, 1
	s_waitcnt lgkmcnt(0)
	v_cvt_pk_bf16_f32 v22, v18, v19
	ds_read2_b32 v[18:19], v55 offset0:66 offset1:99
	s_and_b32 s3, s2, 0x60
	s_and_b32 s4, s4, 0xffffff00
	s_waitcnt lgkmcnt(0)
	v_cvt_pk_bf16_f32 v23, v18, v19
	ds_read2_b32 v[18:19], v55 offset0:132 offset1:165
	s_or_b32 s3, s3, s4
	s_waitcnt lgkmcnt(0)
	v_cvt_pk_bf16_f32 v24, v18, v19
	ds_read2_b32 v[18:19], v55 offset0:198 offset1:231
	v_or_b32_e32 v3, s3, v54
	s_waitcnt lgkmcnt(0)
	v_cvt_pk_bf16_f32 v25, v18, v19
	v_or_b32_e32 v18, s1, v3
	v_ashrrev_i32_e32 v19, 31, v18
	v_or_b32_e32 v3, s2, v56
	v_lshl_add_u64 v[26:27], v[10:11], 0, s[86:87]
	v_lshlrev_b64 v[18:19], 11, v[18:19]
	v_mov_b32_e32 v4, s2
	s_movk_i32 s3, 0x6f
	v_add_lshl_u32 v3, v3, s0, 1
	ds_read2_b32 v[28:29], v55 offset0:8 offset1:41
	v_lshl_add_u64 v[18:19], v[26:27], 0, v[18:19]
	v_bitop3_b32 v20, v56, s3, v4 bitop3:0xc8
	v_and_b32_e32 v3, 0xffffff00, v3
	global_store_dwordx4 v[18:19], v[22:25], off sc1
	s_movk_i32 s3, 0x77
	s_waitcnt lgkmcnt(0)
	v_cvt_pk_bf16_f32 v22, v28, v29
	ds_read2_b32 v[18:19], v55 offset0:74 offset1:107
	v_or3_b32 v28, v20, v3, s1
	s_waitcnt lgkmcnt(0)
	v_cvt_pk_bf16_f32 v23, v18, v19
	ds_read2_b32 v[18:19], v55 offset0:140 offset1:173
	v_ashrrev_i32_e32 v29, 31, v28
	v_or_b32_e32 v3, s2, v57
	s_waitcnt lgkmcnt(0)
	v_cvt_pk_bf16_f32 v24, v18, v19
	ds_read2_b32 v[18:19], v55 offset0:206 offset1:239
	v_lshlrev_b64 v[28:29], 11, v[28:29]
	v_add_lshl_u32 v3, v3, s0, 1
	s_waitcnt lgkmcnt(0)
	v_cvt_pk_bf16_f32 v25, v18, v19
	ds_read2_b32 v[18:19], v55 offset0:16 offset1:49
	v_lshl_add_u64 v[28:29], v[26:27], 0, v[28:29]
	v_bitop3_b32 v20, v57, s3, v4 bitop3:0xc8
	v_and_b32_e32 v3, 0xffffff00, v3
	global_store_dwordx4 v[28:29], v[22:25], off sc1
	v_or3_b32 v28, v20, v3, s1
	v_ashrrev_i32_e32 v29, 31, v28
	s_waitcnt lgkmcnt(0)
	v_cvt_pk_bf16_f32 v22, v18, v19
	ds_read2_b32 v[18:19], v55 offset0:82 offset1:115
	s_waitcnt lgkmcnt(0)
	v_cvt_pk_bf16_f32 v23, v18, v19
	ds_read2_b32 v[18:19], v55 offset0:148 offset1:181
	v_or_b32_e32 v3, s2, v58
	s_waitcnt lgkmcnt(0)
	v_cvt_pk_bf16_f32 v24, v18, v19
	ds_read2_b32 v[18:19], v55 offset0:214 offset1:247
	v_lshlrev_b64 v[28:29], 11, v[28:29]
	s_movk_i32 s3, 0x7f
	v_add_lshl_u32 v3, v3, s0, 1
	s_waitcnt lgkmcnt(0)
	v_cvt_pk_bf16_f32 v25, v18, v19
	ds_read2_b32 v[18:19], v55 offset0:24 offset1:57
	v_lshl_add_u64 v[28:29], v[26:27], 0, v[28:29]
	v_bitop3_b32 v4, v58, s3, v4 bitop3:0xc8
	v_and_b32_e32 v3, 0xffffff00, v3
	global_store_dwordx4 v[28:29], v[22:25], off sc1
	v_or3_b32 v28, v4, v3, s1
	v_ashrrev_i32_e32 v29, 31, v28
	s_waitcnt lgkmcnt(0)
	v_cvt_pk_bf16_f32 v22, v18, v19
	ds_read2_b32 v[18:19], v55 offset0:90 offset1:123
	s_waitcnt lgkmcnt(0)
	v_cvt_pk_bf16_f32 v23, v18, v19
	ds_read2_b32 v[18:19], v55 offset0:156 offset1:189
	s_waitcnt lgkmcnt(0)
	v_cvt_pk_bf16_f32 v24, v18, v19
	ds_read2_b32 v[18:19], v55 offset0:222 offset1:255
	v_lshlrev_b64 v[28:29], 11, v[28:29]
	s_waitcnt lgkmcnt(0)
	v_cvt_pk_bf16_f32 v25, v18, v19
	v_lshl_add_u64 v[18:19], v[26:27], 0, v[28:29]
	global_store_dwordx4 v[18:19], v[22:25], off sc1
	s_waitcnt lgkmcnt(0)

; template <int MODE>
; __device__ __forceinline__ void p0_transpose_item(const float* W, int K, int N, bf16* WT, LAS float* scr, int item, int lane, const float* ga, const float* gb) {
;     ...
;     for (int i = 0; i < 32; ++i) { const int kk = 2 * i + (lane >> 5), k = k0 + kk; float g = 1.0f;
;         if (MODE == 0 || MODE == 2) g = ga[k];
;         if (MODE == 1) g = (k < 512) ? ga[k] : gb[k - 512];
;         scr[kk * 33 + (lane & 31)] = W[(size_t)k * N + n0 + (lane & 31)] * g; }
.LBB0_35:
	s_lshl_b32 s89, s75, 1
	s_lshl_b32 s88, s65, 1
	s_add_i32 s91, s89, 4
	v_mov_b32_e32 v37, v5
	v_mov_b32_e32 v39, v5
	v_or_b32_e32 v4, s88, v3
	v_or_b32_e32 v36, s89, v18
	s_add_i32 s95, s89, 12
	s_add_i32 s70, s89, 16
	s_add_i32 s78, s89, 20
	v_or_b32_e32 v38, s91, v18
	v_mov_b32_e32 v45, v5
	v_mov_b32_e32 v47, v5
	v_mov_b32_e32 v49, v5
	s_add_i32 s93, s89, 8
	s_add_i32 s80, s89, 24
	s_add_i32 s19, s89, 28
	v_lshlrev_b64 v[60:61], 2, v[36:37]
	v_lshlrev_b64 v[62:63], 2, v[4:5]
	v_lshlrev_b32_e32 v24, 10, v36
	v_or_b32_e32 v44, s95, v18
	v_or_b32_e32 v46, s70, v18
	v_or_b32_e32 v48, s78, v18
	v_lshlrev_b64 v[68:69], 2, v[38:39]
	v_mov_b32_e32 v43, v5
	v_mov_b32_e32 v51, v5
	v_mov_b32_e32 v53, v5
	s_add_i32 s90, s88, 4
	v_lshlrev_b32_e32 v22, 10, v4
	v_or_b32_e32 v42, s93, v18
	v_or_b32_e32 v50, s80, v18
	v_or_b32_e32 v52, s19, v18
	v_lshl_add_u64 v[64:65], s[56:57], 0, v[60:61]
	v_lshl_add_u64 v[66:67], s[56:57], 0, v[62:63]
	v_lshl_add_u64 v[62:63], s[58:59], 0, v[62:63]
	v_lshl_add_u64 v[60:61], s[58:59], 0, v[60:61]
	v_lshlrev_b64 v[72:73], 2, v[44:45]
	v_lshlrev_b64 v[74:75], 2, v[46:47]
	v_lshlrev_b64 v[76:77], 2, v[48:49]
	v_cmp_gt_u32_e32 vcc, s18, v4
	v_cmp_gt_u32_e64 s[0:1], s18, v36
	v_or_b32_e32 v4, v20, v24
	v_lshl_add_u64 v[36:37], s[58:59], 0, v[68:69]
	v_mov_b32_e32 v41, v5
	v_or_b32_e32 v40, v19, v22
	v_lshlrev_b64 v[70:71], 2, v[42:43]
	v_lshlrev_b64 v[78:79], 2, v[50:51]
	v_lshlrev_b64 v[80:81], 2, v[52:53]
	v_lshl_add_u64 v[62:63], v[62:63], 0, s[40:41]
	v_lshl_add_u64 v[60:61], v[60:61], 0, s[40:41]
	v_lshl_add_u64 v[84:85], s[56:57], 0, v[72:73]
	v_lshl_add_u64 v[72:73], s[58:59], 0, v[72:73]
	v_lshl_add_u64 v[86:87], s[56:57], 0, v[74:75]
	v_lshl_add_u64 v[74:75], s[58:59], 0, v[74:75]
	v_lshl_add_u64 v[88:89], s[56:57], 0, v[76:77]
	v_lshl_add_u64 v[76:77], s[58:59], 0, v[76:77]
	v_lshl_add_u64 v[94:95], v[36:37], 0, s[40:41]
	v_lshl_add_u64 v[36:37], v[4:5], 2, s[60:61]
	v_or_b32_e32 v4, s90, v3
	v_lshlrev_b32_e32 v22, 10, v38
	v_lshlrev_b32_e32 v26, 10, v42
	v_lshlrev_b32_e32 v28, 10, v44
	v_lshlrev_b32_e32 v59, 10, v46
	v_lshlrev_b32_e32 v98, 10, v52
	v_lshl_add_u64 v[40:41], v[40:41], 2, s[60:61]
	v_lshl_add_u64 v[82:83], s[56:57], 0, v[68:69]
	v_lshl_add_u64 v[68:69], s[56:57], 0, v[70:71]
	v_lshl_add_u64 v[70:71], s[58:59], 0, v[70:71]
	v_lshl_add_u64 v[90:91], s[56:57], 0, v[78:79]
	v_lshl_add_u64 v[78:79], s[58:59], 0, v[78:79]
	v_lshl_add_u64 v[92:93], s[56:57], 0, v[80:81]
	v_lshl_add_u64 v[80:81], s[58:59], 0, v[80:81]
	v_cmp_gt_u32_e64 s[2:3], s18, v38
	v_cmp_gt_u32_e64 s[4:5], s18, v42
	v_lshl_add_u64 v[42:43], v[72:73], 0, s[40:41]
	v_cmp_gt_u32_e64 s[6:7], s18, v44
	v_lshl_add_u64 v[44:45], v[74:75], 0, s[40:41]
	v_cmp_gt_u32_e64 s[8:9], s18, v46
	v_lshl_add_u64 v[46:47], v[76:77], 0, s[40:41]
	v_cmp_gt_u32_e64 s[10:11], s18, v48
	v_cmp_gt_u32_e64 s[16:17], s18, v52
	v_cndmask_b32_e32 v53, v63, v67, vcc
	v_cndmask_b32_e32 v52, v62, v66, vcc
	v_cndmask_b32_e64 v39, v61, v65, s[0:1]
	v_cndmask_b32_e64 v38, v60, v64, s[0:1]
	v_lshlrev_b32_e32 v24, 10, v4
	v_mov_b32_e32 v35, v5
	s_add_i32 s92, s88, 8
	v_lshlrev_b32_e32 v96, 10, v48
	v_lshlrev_b32_e32 v97, 10, v50
	v_lshl_add_u64 v[70:71], v[70:71], 0, s[40:41]
	v_lshl_add_u64 v[48:49], v[78:79], 0, s[40:41]
	v_cmp_gt_u32_e64 s[12:13], s18, v50
	v_lshl_add_u64 v[50:51], v[80:81], 0, s[40:41]
	global_load_dword v36, v[36:37], off
	s_nop 0
	global_load_dword v37, v[40:41], off
	v_lshlrev_b64 v[40:41], 2, v[4:5]
	global_load_dword v38, v[38:39], off
	s_nop 0
	global_load_dword v39, v[52:53], off
	v_cndmask_b32_e64 v53, v95, v83, s[2:3]
	v_cndmask_b32_e64 v52, v94, v82, s[2:3]
	v_cndmask_b32_e64 v42, v42, v84, s[6:7]
	v_cndmask_b32_e64 v44, v44, v86, s[8:9]
	v_cndmask_b32_e64 v63, v47, v89, s[10:11]
	v_cndmask_b32_e64 v62, v46, v88, s[10:11]
	v_or_b32_e32 v34, v19, v24
	v_cmp_gt_u32_e32 vcc, s18, v4
	v_or_b32_e32 v4, v20, v22
	v_cndmask_b32_e64 v61, v71, v69, s[4:5]
	v_cndmask_b32_e64 v60, v70, v68, s[4:5]
	v_cndmask_b32_e64 v43, v43, v85, s[6:7]
	v_cndmask_b32_e64 v45, v45, v87, s[8:9]
	v_cndmask_b32_e64 v65, v49, v91, s[12:13]
	v_cndmask_b32_e64 v64, v48, v90, s[12:13]
	v_cndmask_b32_e64 v67, v51, v93, s[16:17]
	v_cndmask_b32_e64 v66, v50, v92, s[16:17]
	v_lshl_add_u64 v[68:69], s[56:57], 0, v[40:41]
	v_lshl_add_u64 v[70:71], s[58:59], 0, v[40:41]
	global_load_dword v52, v[52:53], off
	s_nop 0
	global_load_dword v50, v[60:61], off
	global_load_dword v48, v[42:43], off
	global_load_dword v46, v[44:45], off
	s_nop 0
	global_load_dword v44, v[62:63], off
	global_load_dword v42, v[64:65], off
	global_load_dword v40, v[66:67], off
	v_lshl_add_u64 v[62:63], v[34:35], 2, s[60:61]
	v_lshl_add_u64 v[34:35], v[4:5], 2, s[60:61]
	v_or_b32_e32 v4, s92, v3
	v_lshl_add_u64 v[60:61], v[70:71], 0, s[40:41]
	v_lshlrev_b64 v[64:65], 2, v[4:5]
	v_lshlrev_b32_e32 v22, 10, v4
	v_mov_b32_e32 v33, v5
	s_add_i32 s94, s88, 12
	v_cndmask_b32_e32 v61, v61, v69, vcc
	v_cndmask_b32_e32 v60, v60, v68, vcc
	global_load_dword v34, v[34:35], off
	s_nop 0
	global_load_dword v35, v[62:63], off
	global_load_dword v53, v[60:61], off
	v_lshl_add_u64 v[62:63], s[58:59], 0, v[64:65]
	v_or_b32_e32 v32, v19, v22
	v_cmp_gt_u32_e32 vcc, s18, v4
	v_or_b32_e32 v4, v20, v26
	v_lshl_add_u64 v[60:61], s[56:57], 0, v[64:65]
	v_lshl_add_u64 v[62:63], v[62:63], 0, s[40:41]
	v_lshl_add_u64 v[64:65], v[32:33], 2, s[60:61]
	v_lshl_add_u64 v[32:33], v[4:5], 2, s[60:61]
	v_or_b32_e32 v4, s94, v3
	v_cndmask_b32_e32 v61, v63, v61, vcc
	v_cndmask_b32_e32 v60, v62, v60, vcc
	v_lshlrev_b64 v[62:63], 2, v[4:5]
	v_lshlrev_b32_e32 v22, 10, v4
	v_mov_b32_e32 v31, v5
	s_add_i32 s97, s88, 16
; template <int MODE>
; __device__ __forceinline__ void p0_transpose_item(const float* W, int K, int N, bf16* WT, LAS float* scr, int item, int lane, const float* ga, const float* gb) {
;     ...
;     for (int i = 0; i < 32; ++i) { const int kk = 2 * i + (lane >> 5), k = k0 + kk; float g = 1.0f;
;         if (MODE == 0 || MODE == 2) g = ga[k];
;         if (MODE == 1) g = (k < 512) ? ga[k] : gb[k - 512];
;         scr[kk * 33 + (lane & 31)] = W[(size_t)k * N + n0 + (lane & 31)] * g; }
	global_load_dword v32, v[32:33], off
	s_nop 0
	global_load_dword v33, v[64:65], off
	global_load_dword v51, v[60:61], off
	v_lshl_add_u64 v[60:61], s[56:57], 0, v[62:63]
	v_lshl_add_u64 v[62:63], s[58:59], 0, v[62:63]
	v_or_b32_e32 v30, v19, v22
	v_cmp_gt_u32_e32 vcc, s18, v4
	v_or_b32_e32 v4, v20, v28
	v_lshl_add_u64 v[62:63], v[62:63], 0, s[40:41]
	v_lshl_add_u64 v[64:65], v[30:31], 2, s[60:61]
	v_lshl_add_u64 v[30:31], v[4:5], 2, s[60:61]
	v_or_b32_e32 v4, s97, v3
	v_cndmask_b32_e32 v61, v63, v61, vcc
	v_cndmask_b32_e32 v60, v62, v60, vcc
	v_lshlrev_b64 v[62:63], 2, v[4:5]
	s_add_i32 s71, s88, 20
	v_lshlrev_b32_e32 v22, 10, v4
	global_load_dword v30, v[30:31], off
	s_nop 0
	global_load_dword v31, v[64:65], off
	global_load_dword v49, v[60:61], off
	v_lshl_add_u64 v[60:61], s[56:57], 0, v[62:63]
	v_lshl_add_u64 v[62:63], s[58:59], 0, v[62:63]
	v_cmp_gt_u32_e32 vcc, s18, v4
	v_or_b32_e32 v4, v20, v59
	v_lshl_add_u64 v[62:63], v[62:63], 0, s[40:41]
	v_lshl_add_u64 v[64:65], v[4:5], 2, s[60:61]
	v_or_b32_e32 v4, s71, v3
	v_mov_b32_e32 v29, v5
	v_or_b32_e32 v28, v19, v22
	v_cndmask_b32_e32 v61, v63, v61, vcc
	v_cndmask_b32_e32 v60, v62, v60, vcc
	v_lshlrev_b64 v[62:63], 2, v[4:5]
	s_add_i32 s79, s88, 24
	v_lshl_add_u64 v[28:29], v[28:29], 2, s[60:61]
	v_lshlrev_b32_e32 v22, 10, v4
	global_load_dword v64, v[64:65], off
	s_nop 0
	global_load_dword v65, v[28:29], off
	global_load_dword v47, v[60:61], off
	v_lshl_add_u64 v[60:61], s[58:59], 0, v[62:63]
	v_cmp_gt_u32_e32 vcc, s18, v4
	v_or_b32_e32 v4, v20, v96
	v_lshl_add_u64 v[28:29], s[56:57], 0, v[62:63]
	v_lshl_add_u64 v[60:61], v[60:61], 0, s[40:41]
	v_lshl_add_u64 v[62:63], v[4:5], 2, s[60:61]
	v_or_b32_e32 v4, s79, v3
	v_mov_b32_e32 v27, v5
	v_or_b32_e32 v26, v19, v22
	v_cndmask_b32_e32 v29, v61, v29, vcc
	v_cndmask_b32_e32 v28, v60, v28, vcc
	v_lshlrev_b64 v[60:61], 2, v[4:5]
	s_add_i32 s81, s88, 28
	v_lshl_add_u64 v[26:27], v[26:27], 2, s[60:61]
	v_lshlrev_b32_e32 v22, 10, v4
	global_load_dword v62, v[62:63], off
	s_nop 0
	global_load_dword v63, v[26:27], off
	global_load_dword v45, v[28:29], off
	v_lshl_add_u64 v[28:29], s[58:59], 0, v[60:61]
	v_cmp_gt_u32_e32 vcc, s18, v4
	v_or_b32_e32 v4, v20, v97
	v_lshl_add_u64 v[26:27], s[56:57], 0, v[60:61]
	v_lshl_add_u64 v[28:29], v[28:29], 0, s[40:41]
	v_lshl_add_u64 v[60:61], v[4:5], 2, s[60:61]
	v_or_b32_e32 v4, s81, v3
	v_mov_b32_e32 v25, v5
	v_or_b32_e32 v24, v19, v22
	v_cndmask_b32_e32 v27, v29, v27, vcc
	v_cndmask_b32_e32 v26, v28, v26, vcc
	v_lshlrev_b64 v[28:29], 2, v[4:5]
	v_lshl_add_u64 v[24:25], v[24:25], 2, s[60:61]
	v_lshlrev_b32_e32 v22, 10, v4
	global_load_dword v60, v[60:61], off
	s_nop 0
	global_load_dword v61, v[24:25], off
	global_load_dword v43, v[26:27], off
	v_lshl_add_u64 v[26:27], s[58:59], 0, v[28:29]
	v_cmp_gt_u32_e32 vcc, s18, v4
	v_or_b32_e32 v4, v20, v98
	v_mov_b32_e32 v23, v5
	v_lshl_add_u64 v[24:25], s[56:57], 0, v[28:29]
	v_or_b32_e32 v22, v19, v22
	v_lshl_add_u64 v[26:27], v[26:27], 0, s[40:41]
	v_lshl_add_u64 v[28:29], v[4:5], 2, s[60:61]
	v_lshl_add_u64 v[22:23], v[22:23], 2, s[60:61]
	v_cndmask_b32_e32 v25, v27, v25, vcc
	v_cndmask_b32_e32 v24, v26, v24, vcc
	global_load_dword v26, v[28:29], off
	global_load_dword v27, v[22:23], off
	global_load_dword v41, v[24:25], off
	v_or_b32_e32 v22, s89, v0
	v_mad_u64_u32 v[22:23], s[0:1], v22, s14, v[2:3]
	v_or_b32_e32 v4, s88, v1
	v_or_b32_e32 v23, s91, v0
	s_waitcnt vmcnt(28)
	v_pk_mul_f32 v[36:37], v[38:39], v[36:37]
	v_mad_u64_u32 v[24:25], s[0:1], v4, s14, v[2:3]
	v_or_b32_e32 v4, s90, v1
	v_or_b32_e32 v59, s93, v0
	v_mad_u64_u32 v[28:29], s[0:1], v23, s14, v[2:3]
	ds_write_b32 v22, v36
	ds_write_b32 v24, v37
	s_waitcnt vmcnt(18)
	v_pk_mul_f32 v[22:23], v[52:53], v[34:35]
	v_or_b32_e32 v25, s92, v1
	v_or_b32_e32 v72, s95, v0
	v_mad_u64_u32 v[66:67], s[0:1], v4, s14, v[2:3]
	v_mad_u64_u32 v[68:69], s[0:1], v59, s14, v[2:3]
	ds_write_b32 v28, v22
	ds_write_b32 v66, v23
	s_waitcnt vmcnt(15)
	v_pk_mul_f32 v[22:23], v[50:51], v[32:33]
	v_or_b32_e32 v74, s94, v1
	v_or_b32_e32 v76, s70, v0
	v_mad_u64_u32 v[70:71], s[0:1], v25, s14, v[2:3]
	v_mad_u64_u32 v[72:73], s[0:1], v72, s14, v[2:3]
	ds_write_b32 v68, v22
	ds_write_b32 v70, v23
	s_waitcnt vmcnt(12)
	v_pk_mul_f32 v[22:23], v[48:49], v[30:31]
	v_or_b32_e32 v78, s97, v1
	v_or_b32_e32 v80, s78, v0
	v_mad_u64_u32 v[74:75], s[0:1], v74, s14, v[2:3]
	v_mad_u64_u32 v[76:77], s[0:1], v76, s14, v[2:3]
	ds_write_b32 v72, v22
	ds_write_b32 v74, v23
	s_waitcnt vmcnt(9)
	v_pk_mul_f32 v[22:23], v[46:47], v[64:65]
	v_or_b32_e32 v82, s71, v1
	v_or_b32_e32 v84, s80, v0
	v_mad_u64_u32 v[78:79], s[0:1], v78, s14, v[2:3]
	v_mad_u64_u32 v[80:81], s[0:1], v80, s14, v[2:3]
	ds_write_b32 v76, v22
	ds_write_b32 v78, v23
	s_add_i32 s75, s75, 16
	s_add_i32 s65, s65, 16
	s_add_i32 s86, s86, -16
	v_or_b32_e32 v86, s79, v1
	v_or_b32_e32 v88, s19, v0
	v_mad_u64_u32 v[82:83], s[0:1], v82, s14, v[2:3]
	s_waitcnt vmcnt(6)
	v_pk_mul_f32 v[22:23], v[44:45], v[62:63]
	v_mad_u64_u32 v[84:85], s[0:1], v84, s14, v[2:3]
	ds_write_b32 v80, v22
	ds_write_b32 v82, v23
	v_or_b32_e32 v90, s81, v1
	s_cmp_lg_u32 s86, 0
	v_mad_u64_u32 v[86:87], s[0:1], v86, s14, v[2:3]
	v_mad_u64_u32 v[88:89], s[0:1], v88, s14, v[2:3]
	v_mad_u64_u32 v[90:91], s[0:1], v90, s14, v[2:3]
	s_waitcnt vmcnt(3)
	v_pk_mul_f32 v[22:23], v[42:43], v[60:61]
	ds_write_b32 v84, v22
	ds_write_b32 v86, v23
	s_waitcnt vmcnt(0)
	v_pk_mul_f32 v[22:23], v[40:41], v[26:27]
	ds_write_b32 v88, v22
	ds_write_b32 v90, v23
	s_cbranch_scc1 .LBB0_35
; #define LAS __attribute__((address_space(3)))
; #define LDS_WAIT() asm volatile("s_waitcnt lgkmcnt(0)" ::: "memory")
; __device__ __forceinline__ unsigned pk2(float lo, float hi) { return pg8::cvt_pk_bf16(lo, hi); }
; template <int MODE>
; __device__ __forceinline__ void p0_transpose_item(const float* W, int K, int N, bf16* WT, LAS float* scr, int item, int lane, const float* ga, const float* gb) {
;     ...
;     const int c = lane & 7;
; #pragma unroll
;     for (int j = 0; j < 4; ++j) { const int n = (lane >> 3) + 8 * j; const LAS float* s = scr + (8 * c) * 33 + n;
;         v4u o; o.x = pk2(s[0 * 33], s[1 * 33]); o.y = pk2(s[2 * 33], s[3 * 33]); o.z = pk2(s[4 * 33], s[5 * 33]); o.w = pk2(s[6 * 33], s[7 * 33]);
;         int nn = n0 + n;
;         if (MODE == 2) { const int up = nn >= DFF ? 1 : 0, f = nn - up * DFF; nn = (f >> 7) * 256 + up * 128 + (f & 127); }
;         *(v4u*)(WT + (size_t)nn * K + k0 + 8 * c) = o; }
;     LDS_WAIT();
	s_waitcnt lgkmcnt(0)
	ds_read2_b32 v[18:19], v55 offset1:33
	s_waitcnt lgkmcnt(0)
	v_cvt_pk_bf16_f32 v22, v18, v19
	ds_read2_b32 v[18:19], v55 offset0:66 offset1:99
	s_waitcnt lgkmcnt(0)
	v_cvt_pk_bf16_f32 v23, v18, v19
	ds_read2_b32 v[18:19], v55 offset0:132 offset1:165
	s_lshl_b32 s86, s64, 1
	v_or_b32_e32 v3, s35, v54
	s_waitcnt lgkmcnt(0)
	v_cvt_pk_bf16_f32 v24, v18, v19
	ds_read2_b32 v[18:19], v55 offset0:198 offset1:231
	v_lshl_add_u64 v[26:27], v[12:13], 0, s[86:87]
	v_lshlrev_b32_e32 v4, 11, v3
	s_waitcnt lgkmcnt(0)
	v_cvt_pk_bf16_f32 v25, v18, v19
	ds_read2_b32 v[18:19], v55 offset0:8 offset1:41
	v_lshl_add_u64 v[28:29], v[26:27], 0, v[4:5]
	global_store_dwordx4 v[28:29], v[22:25], off sc1
	v_or_b32_e32 v3, s35, v56
	v_lshlrev_b32_e32 v4, 11, v3
	s_waitcnt lgkmcnt(0)
	v_cvt_pk_bf16_f32 v22, v18, v19
	ds_read2_b32 v[18:19], v55 offset0:74 offset1:107
	s_waitcnt lgkmcnt(0)
	v_cvt_pk_bf16_f32 v23, v18, v19
	ds_read2_b32 v[18:19], v55 offset0:140 offset1:173
	s_waitcnt lgkmcnt(0)
	v_cvt_pk_bf16_f32 v24, v18, v19
	ds_read2_b32 v[18:19], v55 offset0:206 offset1:239
	s_waitcnt lgkmcnt(0)
	v_cvt_pk_bf16_f32 v25, v18, v19
	ds_read2_b32 v[18:19], v55 offset0:16 offset1:49
	v_lshl_add_u64 v[28:29], v[26:27], 0, v[4:5]
	global_store_dwordx4 v[28:29], v[22:25], off sc1
	v_or_b32_e32 v3, s35, v57
	v_lshlrev_b32_e32 v4, 11, v3
	s_waitcnt lgkmcnt(0)
	v_cvt_pk_bf16_f32 v22, v18, v19
	ds_read2_b32 v[18:19], v55 offset0:82 offset1:115
	s_waitcnt lgkmcnt(0)
	v_cvt_pk_bf16_f32 v23, v18, v19
	ds_read2_b32 v[18:19], v55 offset0:148 offset1:181
	s_waitcnt lgkmcnt(0)
	v_cvt_pk_bf16_f32 v24, v18, v19
	ds_read2_b32 v[18:19], v55 offset0:214 offset1:247
	s_waitcnt lgkmcnt(0)
	v_cvt_pk_bf16_f32 v25, v18, v19
	ds_read2_b32 v[18:19], v55 offset0:24 offset1:57
	v_lshl_add_u64 v[28:29], v[26:27], 0, v[4:5]
	global_store_dwordx4 v[28:29], v[22:25], off sc1
	v_or_b32_e32 v3, s35, v58
	v_lshlrev_b32_e32 v4, 11, v3
	s_waitcnt lgkmcnt(0)
	v_cvt_pk_bf16_f32 v22, v18, v19
	ds_read2_b32 v[18:19], v55 offset0:90 offset1:123
	s_waitcnt lgkmcnt(0)
	v_cvt_pk_bf16_f32 v23, v18, v19
	ds_read2_b32 v[18:19], v55 offset0:156 offset1:189
	s_waitcnt lgkmcnt(0)
	v_cvt_pk_bf16_f32 v24, v18, v19
	ds_read2_b32 v[18:19], v55 offset0:222 offset1:255
	s_waitcnt lgkmcnt(0)
	v_cvt_pk_bf16_f32 v25, v18, v19
	v_lshl_add_u64 v[18:19], v[26:27], 0, v[4:5]
	global_store_dwordx4 v[18:19], v[22:25], off sc1
	s_waitcnt lgkmcnt(0)

; template <int MODE>
; __device__ __forceinline__ void p0_transpose_item(const float* W, int K, int N, bf16* WT, LAS float* scr, int item, int lane, const float* ga, const float* gb) {
;     ...
;     for (int i = 0; i < 32; ++i) { const int kk = 2 * i + (lane >> 5), k = k0 + kk; float g = 1.0f;
;         if (MODE == 0 || MODE == 2) g = ga[k];
;         if (MODE == 1) g = (k < 512) ? ga[k] : gb[k - 512];
;         scr[kk * 33 + (lane & 31)] = W[(size_t)k * N + n0 + (lane & 31)] * g; }
.LBB0_39:
	s_lshl_b32 s5, s1, 1
	s_lshl_b32 s6, s3, 1
	s_add_i32 s7, s5, 4
	s_add_i32 s8, s6, 4
	s_add_i32 s9, s5, 8
	s_add_i32 s10, s6, 8
	s_add_i32 s11, s5, 12
	s_add_i32 s12, s6, 12
	s_add_i32 s13, s5, 16
	v_or_b32_e32 v22, s5, v3
	v_or_b32_e32 v24, s6, v4
	s_add_i32 s16, s6, 16
	s_add_i32 s17, s5, 20
	s_add_i32 s19, s6, 20
	s_add_i32 s35, s5, 24
	s_add_i32 s70, s6, 24
	s_add_i32 s71, s5, 28
	s_add_i32 s75, s6, 28
	v_or_b32_e32 v30, s7, v3
	v_or_b32_e32 v32, s8, v4
	v_or_b32_e32 v34, s9, v3
	v_or_b32_e32 v36, s10, v4
	v_or_b32_e32 v38, s11, v3
	v_or_b32_e32 v40, s12, v4
	v_or_b32_e32 v42, s13, v3
	v_ashrrev_i32_e32 v23, 31, v22
	v_ashrrev_i32_e32 v25, 31, v24
	v_mad_i64_i32 v[26:27], s[64:65], v24, s23, v[18:19]
	v_mad_i64_i32 v[28:29], s[64:65], v22, s23, v[18:19]
	v_or_b32_e32 v44, s16, v4
	v_or_b32_e32 v46, s17, v3
	v_or_b32_e32 v48, s19, v4
	v_or_b32_e32 v50, s35, v3
	v_or_b32_e32 v52, s70, v4
	v_or_b32_e32 v60, s71, v3
	v_or_b32_e32 v62, s75, v4
	v_ashrrev_i32_e32 v31, 31, v30
	v_ashrrev_i32_e32 v33, 31, v32
	v_ashrrev_i32_e32 v35, 31, v34
	v_ashrrev_i32_e32 v37, 31, v36
	v_ashrrev_i32_e32 v39, 31, v38
	v_ashrrev_i32_e32 v41, 31, v40
	v_ashrrev_i32_e32 v43, 31, v42
	v_lshl_add_u64 v[24:25], v[24:25], 2, s[38:39]
	v_lshl_add_u64 v[22:23], v[22:23], 2, s[38:39]
	global_load_dword v26, v[26:27], off
	s_nop 0
	global_load_dword v27, v[28:29], off
	v_mad_i64_i32 v[28:29], s[64:65], v32, s23, v[18:19]
	v_mad_i64_i32 v[64:65], s[64:65], v30, s23, v[18:19]
	v_mad_i64_i32 v[66:67], s[64:65], v36, s23, v[18:19]
	v_mad_i64_i32 v[68:69], s[64:65], v34, s23, v[18:19]
	v_mad_i64_i32 v[70:71], s[64:65], v40, s23, v[18:19]
	v_mad_i64_i32 v[72:73], s[64:65], v38, s23, v[18:19]
	v_ashrrev_i32_e32 v45, 31, v44
	v_mad_i64_i32 v[76:77], s[64:65], v42, s23, v[18:19]
	v_ashrrev_i32_e32 v47, 31, v46
	v_ashrrev_i32_e32 v49, 31, v48
	v_ashrrev_i32_e32 v51, 31, v50
	v_ashrrev_i32_e32 v53, 31, v52
	v_ashrrev_i32_e32 v61, 31, v60
	v_ashrrev_i32_e32 v63, 31, v62
	v_mad_i64_i32 v[86:87], s[64:65], v62, s23, v[18:19]
	v_lshl_add_u64 v[32:33], v[32:33], 2, s[38:39]
	v_lshl_add_u64 v[30:31], v[30:31], 2, s[38:39]
	v_lshl_add_u64 v[36:37], v[36:37], 2, s[38:39]
	v_lshl_add_u64 v[34:35], v[34:35], 2, s[38:39]
	v_lshl_add_u64 v[40:41], v[40:41], 2, s[38:39]
	v_lshl_add_u64 v[38:39], v[38:39], 2, s[38:39]
	v_lshl_add_u64 v[42:43], v[42:43], 2, s[38:39]
	v_mad_i64_i32 v[74:75], s[64:65], v44, s23, v[18:19]
	v_mad_i64_i32 v[78:79], s[64:65], v48, s23, v[18:19]
	v_mad_i64_i32 v[80:81], s[64:65], v46, s23, v[18:19]
	v_mad_i64_i32 v[82:83], s[64:65], v52, s23, v[18:19]
	v_mad_i64_i32 v[84:85], s[64:65], v50, s23, v[18:19]
	v_mad_i64_i32 v[88:89], s[64:65], v60, s23, v[18:19]
	global_load_dword v24, v[24:25], off
	s_nop 0
	global_load_dword v25, v[22:23], off
	s_nop 0
	global_load_dword v22, v[28:29], off
	global_load_dword v23, v[64:65], off
	s_nop 0
	global_load_dword v28, v[66:67], off
	global_load_dword v29, v[68:69], off
	global_load_dword v64, v[70:71], off
	global_load_dword v65, v[72:73], off
	s_nop 0
	global_load_dword v66, v[74:75], off
	global_load_dword v67, v[76:77], off
	global_load_dword v68, v[78:79], off
	global_load_dword v69, v[80:81], off
	global_load_dword v70, v[82:83], off
	global_load_dword v71, v[84:85], off
	v_lshl_add_u64 v[44:45], v[44:45], 2, s[38:39]
	v_lshl_add_u64 v[48:49], v[48:49], 2, s[38:39]
	v_lshl_add_u64 v[46:47], v[46:47], 2, s[38:39]
	v_lshl_add_u64 v[52:53], v[52:53], 2, s[38:39]
	v_lshl_add_u64 v[50:51], v[50:51], 2, s[38:39]
	v_lshl_add_u64 v[62:63], v[62:63], 2, s[38:39]
	v_lshl_add_u64 v[60:61], v[60:61], 2, s[38:39]
	global_load_dword v72, v[86:87], off
	global_load_dword v73, v[88:89], off
	s_nop 0
	global_load_dword v32, v[32:33], off
	s_nop 0
	global_load_dword v33, v[30:31], off
	s_nop 0
	global_load_dword v30, v[36:37], off
	global_load_dword v31, v[34:35], off
	s_nop 0
	global_load_dword v34, v[40:41], off
	global_load_dword v35, v[38:39], off
	global_load_dword v36, v[44:45], off
	global_load_dword v37, v[42:43], off
	s_nop 0
	global_load_dword v38, v[48:49], off
	global_load_dword v39, v[46:47], off
	global_load_dword v40, v[52:53], off
	global_load_dword v41, v[50:51], off
	global_load_dword v42, v[62:63], off
	global_load_dword v43, v[60:61], off
	v_or_b32_e32 v44, s6, v0
	v_or_b32_e32 v20, s5, v1
	v_mad_u64_u32 v[44:45], s[64:65], v44, s14, v[2:3]
	s_add_i32 s3, s3, 16
	s_add_i32 s1, s1, 16
	s_add_i32 s4, s4, -16
	v_mad_u64_u32 v[46:47], s[64:65], v20, s14, v[2:3]
	v_or_b32_e32 v45, s8, v0
	v_or_b32_e32 v20, s7, v1
	v_or_b32_e32 v47, s9, v1
	v_or_b32_e32 v52, s10, v0
	v_or_b32_e32 v59, s11, v1
	v_or_b32_e32 v62, s12, v0
	v_or_b32_e32 v78, s13, v1
	v_or_b32_e32 v76, s16, v0
	v_or_b32_e32 v82, s17, v1
	v_or_b32_e32 v80, s19, v0
	v_or_b32_e32 v86, s35, v1
	v_or_b32_e32 v84, s70, v0
	v_or_b32_e32 v90, s71, v1
	v_or_b32_e32 v88, s75, v0
	s_cmp_lg_u32 s4, 0
	v_mad_u64_u32 v[48:49], s[6:7], v45, s14, v[2:3]
	v_mad_u64_u32 v[50:51], s[6:7], v20, s14, v[2:3]
	v_mad_u64_u32 v[52:53], s[6:7], v52, s14, v[2:3]
	v_mad_u64_u32 v[60:61], s[6:7], v47, s14, v[2:3]
	v_mad_u64_u32 v[62:63], s[6:7], v62, s14, v[2:3]
	v_mad_u64_u32 v[74:75], s[6:7], v59, s14, v[2:3]
	v_mad_u64_u32 v[76:77], s[6:7], v76, s14, v[2:3]
	v_mad_u64_u32 v[78:79], s[6:7], v78, s14, v[2:3]
	v_mad_u64_u32 v[80:81], s[6:7], v80, s14, v[2:3]
	v_mad_u64_u32 v[82:83], s[6:7], v82, s14, v[2:3]
	v_mad_u64_u32 v[84:85], s[6:7], v84, s14, v[2:3]
	v_mad_u64_u32 v[86:87], s[6:7], v86, s14, v[2:3]
	v_mad_u64_u32 v[88:89], s[6:7], v88, s14, v[2:3]
	v_mad_u64_u32 v[90:91], s[6:7], v90, s14, v[2:3]
	s_waitcnt vmcnt(28)
	v_pk_mul_f32 v[24:25], v[24:25], v[26:27]
	ds_write_b32 v44, v24
	ds_write_b32 v46, v25
	s_waitcnt vmcnt(12)
	v_pk_mul_f32 v[22:23], v[32:33], v[22:23]
	s_waitcnt vmcnt(10)
	v_pk_mul_f32 v[24:25], v[30:31], v[28:29]
	s_waitcnt vmcnt(8)
	v_pk_mul_f32 v[26:27], v[34:35], v[64:65]
	s_waitcnt vmcnt(6)
	v_pk_mul_f32 v[28:29], v[36:37], v[66:67]
	s_waitcnt vmcnt(4)
	v_pk_mul_f32 v[30:31], v[38:39], v[68:69]
	s_waitcnt vmcnt(2)
	v_pk_mul_f32 v[32:33], v[40:41], v[70:71]
	s_waitcnt vmcnt(0)
	v_pk_mul_f32 v[34:35], v[42:43], v[72:73]
	ds_write_b32 v48, v22
	ds_write_b32 v50, v23
	ds_write_b32 v52, v24
	ds_write_b32 v60, v25
	ds_write_b32 v62, v26
	ds_write_b32 v74, v27
	ds_write_b32 v76, v28
	ds_write_b32 v78, v29
	ds_write_b32 v80, v30
	ds_write_b32 v82, v31
	ds_write_b32 v84, v32
	ds_write_b32 v86, v33
	ds_write_b32 v88, v34
	ds_write_b32 v90, v35
	s_cbranch_scc1 .LBB0_39
; #define LAS __attribute__((address_space(3)))
; #define LDS_WAIT() asm volatile("s_waitcnt lgkmcnt(0)" ::: "memory")
; __device__ __forceinline__ unsigned pk2(float lo, float hi) { return pg8::cvt_pk_bf16(lo, hi); }
; template <int MODE>
; __device__ __forceinline__ void p0_transpose_item(const float* W, int K, int N, bf16* WT, LAS float* scr, int item, int lane, const float* ga, const float* gb) {
;     ...
;     const int c = lane & 7;
; #pragma unroll
;     for (int j = 0; j < 4; ++j) { const int n = (lane >> 3) + 8 * j; const LAS float* s = scr + (8 * c) * 33 + n;
;         v4u o; o.x = pk2(s[0 * 33], s[1 * 33]); o.y = pk2(s[2 * 33], s[3 * 33]); o.z = pk2(s[4 * 33], s[5 * 33]); o.w = pk2(s[6 * 33], s[7 * 33]);
;         int nn = n0 + n;
;         if (MODE == 2) { const int up = nn >= DFF ? 1 : 0, f = nn - up * DFF; nn = (f >> 7) * 256 + up * 128 + (f & 127); }
;         *(v4u*)(WT + (size_t)nn * K + k0 + 8 * c) = o; }
;     LDS_WAIT();
	s_waitcnt lgkmcnt(0)
	ds_read2_b32 v[18:19], v55 offset1:33
	s_waitcnt lgkmcnt(0)
	v_cvt_pk_bf16_f32 v22, v18, v19
	ds_read2_b32 v[18:19], v55 offset0:66 offset1:99
	v_or_b32_e32 v26, s0, v54
	s_waitcnt lgkmcnt(0)
	v_cvt_pk_bf16_f32 v23, v18, v19
	ds_read2_b32 v[18:19], v55 offset0:132 offset1:165
	s_ashr_i32 s3, s2, 31
	v_ashrrev_i32_e32 v27, 31, v26
	s_waitcnt lgkmcnt(0)
	v_cvt_pk_bf16_f32 v24, v18, v19
	ds_read2_b32 v[18:19], v55 offset0:198 offset1:231
	v_lshl_add_u64 v[28:29], s[2:3], 1, v[16:17]
	v_lshlrev_b64 v[26:27], 11, v[26:27]
	s_waitcnt lgkmcnt(0)
	v_cvt_pk_bf16_f32 v25, v18, v19
	ds_read2_b32 v[18:19], v55 offset0:8 offset1:41
	v_lshl_add_u64 v[26:27], v[28:29], 0, v[26:27]
	global_store_dwordx4 v[26:27], v[22:25], off sc1
	v_or_b32_e32 v26, s0, v56
	v_ashrrev_i32_e32 v27, 31, v26
	s_waitcnt lgkmcnt(0)
	v_cvt_pk_bf16_f32 v22, v18, v19
	ds_read2_b32 v[18:19], v55 offset0:74 offset1:107
	s_waitcnt lgkmcnt(0)
	v_cvt_pk_bf16_f32 v23, v18, v19
	ds_read2_b32 v[18:19], v55 offset0:140 offset1:173
	s_waitcnt lgkmcnt(0)
	v_cvt_pk_bf16_f32 v24, v18, v19
	ds_read2_b32 v[18:19], v55 offset0:206 offset1:239
	v_lshlrev_b64 v[26:27], 11, v[26:27]
	s_waitcnt lgkmcnt(0)
	v_cvt_pk_bf16_f32 v25, v18, v19
	ds_read2_b32 v[18:19], v55 offset0:16 offset1:49
	v_lshl_add_u64 v[26:27], v[28:29], 0, v[26:27]
	global_store_dwordx4 v[26:27], v[22:25], off sc1
	v_or_b32_e32 v26, s0, v57
	v_ashrrev_i32_e32 v27, 31, v26
	s_waitcnt lgkmcnt(0)
	v_cvt_pk_bf16_f32 v22, v18, v19
	ds_read2_b32 v[18:19], v55 offset0:82 offset1:115
	s_waitcnt lgkmcnt(0)
	v_cvt_pk_bf16_f32 v23, v18, v19
	ds_read2_b32 v[18:19], v55 offset0:148 offset1:181
	s_waitcnt lgkmcnt(0)
	v_cvt_pk_bf16_f32 v24, v18, v19
	ds_read2_b32 v[18:19], v55 offset0:214 offset1:247
	v_lshlrev_b64 v[26:27], 11, v[26:27]
	s_waitcnt lgkmcnt(0)
	v_cvt_pk_bf16_f32 v25, v18, v19
	ds_read2_b32 v[18:19], v55 offset0:24 offset1:57
	v_lshl_add_u64 v[26:27], v[28:29], 0, v[26:27]
	global_store_dwordx4 v[26:27], v[22:25], off sc1
	v_or_b32_e32 v26, s0, v58
	v_ashrrev_i32_e32 v27, 31, v26
	s_waitcnt lgkmcnt(0)
	v_cvt_pk_bf16_f32 v22, v18, v19
	ds_read2_b32 v[18:19], v55 offset0:90 offset1:123
	s_waitcnt lgkmcnt(0)
	v_cvt_pk_bf16_f32 v23, v18, v19
	ds_read2_b32 v[18:19], v55 offset0:156 offset1:189
	s_waitcnt lgkmcnt(0)
	v_cvt_pk_bf16_f32 v24, v18, v19
	ds_read2_b32 v[18:19], v55 offset0:222 offset1:255
	v_lshlrev_b64 v[26:27], 11, v[26:27]
	s_waitcnt lgkmcnt(0)
	v_cvt_pk_bf16_f32 v25, v18, v19
	v_lshl_add_u64 v[18:19], v[28:29], 0, v[26:27]
	global_store_dwordx4 v[18:19], v[22:25], off sc1
	s_waitcnt lgkmcnt(0)
	s_branch .LBB0_20

; __device__ __forceinline__ unsigned cvt_pk_bf16(float lo, float hi) { unsigned r; asm volatile("v_cvt_pk_bf16_f32 %0, %1, %2" : "=v"(r) : "v"(lo), "v"(hi)); return r; }
;     __device__ __forceinline__ void operator()(const f32x4 (&acc)[2][2][4][2], const Unit& u, int wr, int wc, int fr, int fq) const {
;     ...
;             for (int m = 0; m < 4; ++m) { bf16_t* rowp = base + (size_t)(row0 + ai * HALF + m * 16) * ldc + col0;
; #pragma unroll
;                 for (int bj = 0; bj < 2; ++bj) { f32x4 v0 = acc[ai][bj][m][0] + bv[bj][0], v1 = acc[ai][bj][m][1] + bv[bj][1];
;                     if (ACT == 1) { f32x2 a = gelu_pk((f32x2){v0[0], v0[1]}), b = gelu_pk((f32x2){v0[2], v0[3]}), c = gelu_pk((f32x2){v1[0], v1[1]}), d = gelu_pk((f32x2){v1[2], v1[3]});
;                         v0 = (f32x4){a.x, a.y, b.x, b.y}; v1 = (f32x4){c.x, c.y, d.x, d.y}; }
;                     v0 = v0 * sc; v1 = v1 * sc; u32x4 w; w.x = cvt_pk_bf16(v0[0], v0[1]); w.y = cvt_pk_bf16(v0[2], v0[3]); w.z = cvt_pk_bf16(v1[0], v1[1]); w.w = cvt_pk_bf16(v1[2], v1[3]);
;                     *(u32x4*)(rowp + bj * HALF) = w; } }
.LBB0_131:
	v_lshl_add_u32 v160, s56, 8, v154
	v_lshl_or_b32 v144, s88, 8, v156
	v_ashrrev_i32_e32 v145, 31, v144
	v_ashrrev_i32_e32 v161, 31, v160
	v_lshl_add_u64 v[162:163], v[144:145], 1, s[38:39]
	v_lshlrev_b64 v[144:145], 12, v[160:161]
	v_lshl_add_u64 v[144:145], v[162:163], 0, v[144:145]
	v_pk_add_f32 v[126:127], v[126:127], 0 op_sel_hi:[1,0]
	v_pk_add_f32 v[124:125], v[124:125], 0 op_sel_hi:[1,0]
	v_pk_add_f32 v[164:165], v[122:123], 0 op_sel_hi:[1,0]
	v_pk_add_f32 v[122:123], v[120:121], 0 op_sel_hi:[1,0]
	v_cvt_pk_bf16_f32 v120, v124, v125
	v_cvt_pk_bf16_f32 v121, v126, v127
	v_pk_add_f32 v[116:117], v[116:117], 0 op_sel_hi:[1,0]
	v_cvt_pk_bf16_f32 v122, v122, v123
	v_cvt_pk_bf16_f32 v123, v164, v165
	global_store_dwordx4 v[144:145], v[120:123], off sc1
	v_pk_add_f32 v[118:119], v[118:119], 0 op_sel_hi:[1,0]
	v_pk_add_f32 v[112:113], v[112:113], 0 op_sel_hi:[1,0]
	v_pk_add_f32 v[120:121], v[110:111], 0 op_sel_hi:[1,0]
	v_pk_add_f32 v[110:111], v[108:109], 0 op_sel_hi:[1,0]
	v_cvt_pk_bf16_f32 v108, v116, v117
	v_cvt_pk_bf16_f32 v109, v118, v119
	v_pk_add_f32 v[100:101], v[100:101], 0 op_sel_hi:[1,0]
	v_cvt_pk_bf16_f32 v110, v110, v111
	v_cvt_pk_bf16_f32 v111, v120, v121
	global_store_dwordx4 v[144:145], v[108:111], off offset:256 sc1
	v_pk_add_f32 v[102:103], v[102:103], 0 op_sel_hi:[1,0]
	v_pk_add_f32 v[96:97], v[96:97], 0 op_sel_hi:[1,0]
	v_or_b32_e32 v108, 16, v160
	v_ashrrev_i32_e32 v109, 31, v108
	v_lshlrev_b64 v[108:109], 12, v[108:109]
	v_lshl_add_u64 v[108:109], v[162:163], 0, v[108:109]
	v_pk_add_f32 v[110:111], v[114:115], 0 op_sel_hi:[1,0]
	v_pk_add_f32 v[114:115], v[106:107], 0 op_sel_hi:[1,0]
	v_pk_add_f32 v[106:107], v[104:105], 0 op_sel_hi:[1,0]
	v_cvt_pk_bf16_f32 v104, v112, v113
	v_cvt_pk_bf16_f32 v105, v110, v111
	v_pk_add_f32 v[84:85], v[84:85], 0 op_sel_hi:[1,0]
	v_cvt_pk_bf16_f32 v106, v106, v107
	v_cvt_pk_bf16_f32 v107, v114, v115
	global_store_dwordx4 v[108:109], v[104:107], off sc1
	v_pk_add_f32 v[86:87], v[86:87], 0 op_sel_hi:[1,0]
	v_pk_add_f32 v[80:81], v[80:81], 0 op_sel_hi:[1,0]
	v_pk_add_f32 v[104:105], v[94:95], 0 op_sel_hi:[1,0]
	v_pk_add_f32 v[94:95], v[92:93], 0 op_sel_hi:[1,0]
	v_cvt_pk_bf16_f32 v92, v100, v101
	v_cvt_pk_bf16_f32 v93, v102, v103
	v_pk_add_f32 v[70:71], v[70:71], 0 op_sel_hi:[1,0]
	v_cvt_pk_bf16_f32 v94, v94, v95
	v_cvt_pk_bf16_f32 v95, v104, v105
	global_store_dwordx4 v[108:109], v[92:95], off offset:256 sc1
	v_pk_add_f32 v[68:69], v[68:69], 0 op_sel_hi:[1,0]
	v_pk_add_f32 v[60:61], v[60:61], 0 op_sel_hi:[1,0]
	v_or_b32_e32 v92, 32, v160
	v_ashrrev_i32_e32 v93, 31, v92
	v_lshlrev_b64 v[92:93], 12, v[92:93]
	v_lshl_add_u64 v[92:93], v[162:163], 0, v[92:93]
	v_pk_add_f32 v[94:95], v[98:99], 0 op_sel_hi:[1,0]
	v_pk_add_f32 v[98:99], v[90:91], 0 op_sel_hi:[1,0]
	v_pk_add_f32 v[90:91], v[88:89], 0 op_sel_hi:[1,0]
	v_cvt_pk_bf16_f32 v88, v96, v97
	v_cvt_pk_bf16_f32 v89, v94, v95
	s_mov_b32 s19, 0x80000
	v_cvt_pk_bf16_f32 v90, v90, v91
	v_cvt_pk_bf16_f32 v91, v98, v99
	global_store_dwordx4 v[92:93], v[88:91], off sc1
	v_pk_add_f32 v[62:63], v[62:63], 0 op_sel_hi:[1,0]
	s_mov_b64 s[58:59], 0x80000
	v_pk_add_f32 v[88:89], v[78:79], 0 op_sel_hi:[1,0]
	v_pk_add_f32 v[78:79], v[76:77], 0 op_sel_hi:[1,0]
	v_cvt_pk_bf16_f32 v76, v84, v85
	v_cvt_pk_bf16_f32 v77, v86, v87
	v_pk_add_f32 v[54:55], v[54:55], 0 op_sel_hi:[1,0]
	v_cvt_pk_bf16_f32 v78, v78, v79
	v_cvt_pk_bf16_f32 v79, v88, v89
	global_store_dwordx4 v[92:93], v[76:79], off offset:256 sc1
	v_pk_add_f32 v[52:53], v[52:53], 0 op_sel_hi:[1,0]
	v_pk_add_f32 v[48:49], v[48:49], 0 op_sel_hi:[1,0]
	v_or_b32_e32 v76, 48, v160
	v_ashrrev_i32_e32 v77, 31, v76
	v_lshlrev_b64 v[76:77], 12, v[76:77]
	v_lshl_add_u64 v[76:77], v[162:163], 0, v[76:77]
	v_pk_add_f32 v[78:79], v[82:83], 0 op_sel_hi:[1,0]
	v_pk_add_f32 v[82:83], v[74:75], 0 op_sel_hi:[1,0]
	v_pk_add_f32 v[74:75], v[72:73], 0 op_sel_hi:[1,0]
	v_cvt_pk_bf16_f32 v72, v80, v81
	v_cvt_pk_bf16_f32 v73, v78, v79
	v_pk_add_f32 v[38:39], v[38:39], 0 op_sel_hi:[1,0]
	v_cvt_pk_bf16_f32 v74, v74, v75
; __device__ __forceinline__ unsigned cvt_pk_bf16(float lo, float hi) { unsigned r; asm volatile("v_cvt_pk_bf16_f32 %0, %1, %2" : "=v"(r) : "v"(lo), "v"(hi)); return r; }
;     __device__ __forceinline__ void operator()(const f32x4 (&acc)[2][2][4][2], const Unit& u, int wr, int wc, int fr, int fq) const {
;     ...
;             for (int m = 0; m < 4; ++m) { bf16_t* rowp = base + (size_t)(row0 + ai * HALF + m * 16) * ldc + col0;
; #pragma unroll
;                 for (int bj = 0; bj < 2; ++bj) { f32x4 v0 = acc[ai][bj][m][0] + bv[bj][0], v1 = acc[ai][bj][m][1] + bv[bj][1];
;                     if (ACT == 1) { f32x2 a = gelu_pk((f32x2){v0[0], v0[1]}), b = gelu_pk((f32x2){v0[2], v0[3]}), c = gelu_pk((f32x2){v1[0], v1[1]}), d = gelu_pk((f32x2){v1[2], v1[3]});
;                         v0 = (f32x4){a.x, a.y, b.x, b.y}; v1 = (f32x4){c.x, c.y, d.x, d.y}; }
;                     v0 = v0 * sc; v1 = v1 * sc; u32x4 w; w.x = cvt_pk_bf16(v0[0], v0[1]); w.y = cvt_pk_bf16(v0[2], v0[3]); w.z = cvt_pk_bf16(v1[0], v1[1]); w.w = cvt_pk_bf16(v1[2], v1[3]);
;                     *(u32x4*)(rowp + bj * HALF) = w; } }
	v_cvt_pk_bf16_f32 v75, v82, v83
	global_store_dwordx4 v[76:77], v[72:75], off sc1
	v_pk_add_f32 v[36:37], v[36:37], 0 op_sel_hi:[1,0]
	v_pk_add_f32 v[32:33], v[32:33], 0 op_sel_hi:[1,0]
	v_pk_add_f32 v[72:73], v[66:67], 0 op_sel_hi:[1,0]
	v_pk_add_f32 v[66:67], v[64:65], 0 op_sel_hi:[1,0]
	v_cvt_pk_bf16_f32 v64, v68, v69
	v_cvt_pk_bf16_f32 v65, v70, v71
	v_pk_add_f32 v[22:23], v[22:23], 0 op_sel_hi:[1,0]
	v_cvt_pk_bf16_f32 v66, v66, v67
	v_cvt_pk_bf16_f32 v67, v72, v73
	global_store_dwordx4 v[76:77], v[64:67], off offset:256 sc1
	v_pk_add_f32 v[20:21], v[20:21], 0 op_sel_hi:[1,0]
	v_pk_add_f32 v[16:17], v[16:17], 0 op_sel_hi:[1,0]
	v_pk_add_f32 v[66:67], v[58:59], 0 op_sel_hi:[1,0]
	v_pk_add_f32 v[58:59], v[56:57], 0 op_sel_hi:[1,0]
	v_cvt_pk_bf16_f32 v56, v60, v61
	v_add_co_u32_e32 v60, vcc, s19, v144
	v_cvt_pk_bf16_f32 v57, v62, v63
	v_cvt_pk_bf16_f32 v58, v58, v59
	v_cvt_pk_bf16_f32 v59, v66, v67
	v_lshl_add_u64 v[64:65], v[144:145], 0, s[58:59]
	s_nop 0
	v_addc_co_u32_e32 v61, vcc, 0, v145, vcc
	global_store_dwordx4 v[60:61], v[56:59], off sc1
	s_mov_b64 s[58:59], 0x90000
	v_pk_add_f32 v[6:7], v[6:7], 0 op_sel_hi:[1,0]
	v_pk_add_f32 v[56:57], v[46:47], 0 op_sel_hi:[1,0]
	v_pk_add_f32 v[46:47], v[44:45], 0 op_sel_hi:[1,0]
	v_cvt_pk_bf16_f32 v44, v52, v53
	v_cvt_pk_bf16_f32 v45, v54, v55
	v_pk_add_f32 v[4:5], v[4:5], 0 op_sel_hi:[1,0]
	v_cvt_pk_bf16_f32 v46, v46, v47
	v_cvt_pk_bf16_f32 v47, v56, v57
	global_store_dwordx4 v[64:65], v[44:47], off offset:256 sc1
	s_nop 1
	v_pk_add_f32 v[46:47], v[50:51], 0 op_sel_hi:[1,0]
	v_pk_add_f32 v[50:51], v[42:43], 0 op_sel_hi:[1,0]
	v_pk_add_f32 v[42:43], v[40:41], 0 op_sel_hi:[1,0]
	v_cvt_pk_bf16_f32 v40, v48, v49
	v_cvt_pk_bf16_f32 v41, v46, v47
	v_add_co_u32_e32 v46, vcc, s85, v144
	v_cvt_pk_bf16_f32 v42, v42, v43
	v_cvt_pk_bf16_f32 v43, v50, v51
	v_lshl_add_u64 v[44:45], v[144:145], 0, s[58:59]
	s_nop 0
	v_addc_co_u32_e32 v47, vcc, 0, v145, vcc
	global_store_dwordx4 v[46:47], v[40:43], off sc1
	s_nop 1
	v_pk_add_f32 v[40:41], v[30:31], 0 op_sel_hi:[1,0]
	v_pk_add_f32 v[30:31], v[28:29], 0 op_sel_hi:[1,0]
	v_cvt_pk_bf16_f32 v28, v36, v37
	v_cvt_pk_bf16_f32 v29, v38, v39
	s_nop 0
	v_cvt_pk_bf16_f32 v30, v30, v31
	v_cvt_pk_bf16_f32 v31, v40, v41
	global_store_dwordx4 v[44:45], v[28:31], off offset:256 sc1
	s_nop 1
	v_pk_add_f32 v[30:31], v[34:35], 0 op_sel_hi:[1,0]
	v_pk_add_f32 v[34:35], v[26:27], 0 op_sel_hi:[1,0]
	v_pk_add_f32 v[26:27], v[24:25], 0 op_sel_hi:[1,0]
	v_cvt_pk_bf16_f32 v24, v32, v33
	v_cvt_pk_bf16_f32 v25, v30, v31
	v_add_co_u32_e32 v30, vcc, s86, v144
	v_cvt_pk_bf16_f32 v26, v26, v27
	v_cvt_pk_bf16_f32 v27, v34, v35
	v_lshl_add_u64 v[28:29], v[144:145], 0, s[12:13]
	s_nop 0
	v_addc_co_u32_e32 v31, vcc, 0, v145, vcc
	global_store_dwordx4 v[30:31], v[24:27], off sc1
	s_nop 1
	v_pk_add_f32 v[24:25], v[14:15], 0 op_sel_hi:[1,0]
	v_pk_add_f32 v[14:15], v[12:13], 0 op_sel_hi:[1,0]
	v_cvt_pk_bf16_f32 v12, v20, v21
	v_cvt_pk_bf16_f32 v13, v22, v23
	s_nop 0
	v_cvt_pk_bf16_f32 v14, v14, v15
	v_cvt_pk_bf16_f32 v15, v24, v25
	global_store_dwordx4 v[28:29], v[12:15], off offset:256 sc1
	s_nop 1
	v_pk_add_f32 v[14:15], v[18:19], 0 op_sel_hi:[1,0]
	v_pk_add_f32 v[18:19], v[10:11], 0 op_sel_hi:[1,0]
	v_pk_add_f32 v[10:11], v[8:9], 0 op_sel_hi:[1,0]
	v_cvt_pk_bf16_f32 v8, v16, v17
	v_cvt_pk_bf16_f32 v9, v14, v15
	v_add_co_u32_e32 v14, vcc, s87, v144
	v_lshl_add_u64 v[12:13], v[144:145], 0, s[16:17]
	s_nop 0
	v_addc_co_u32_e32 v15, vcc, 0, v145, vcc
	v_cvt_pk_bf16_f32 v10, v10, v11
	v_cvt_pk_bf16_f32 v11, v18, v19
	global_store_dwordx4 v[14:15], v[8:11], off sc1
	s_andn2_b64 vcc, exec, s[2:3]
	s_mov_b64 s[2:3], -1
	v_pk_add_f32 v[8:9], v[2:3], 0 op_sel_hi:[1,0]
	v_pk_add_f32 v[2:3], v[0:1], 0 op_sel_hi:[1,0]
	v_cvt_pk_bf16_f32 v0, v4, v5
	v_cvt_pk_bf16_f32 v1, v6, v7
	s_nop 0
	v_cvt_pk_bf16_f32 v2, v2, v3
	v_cvt_pk_bf16_f32 v3, v8, v9
	global_store_dwordx4 v[12:13], v[0:3], off offset:256 sc1
	s_cbranch_vccnz .LBB0_120
	s_andn2_b64 vcc, exec, s[6:7]
	s_cbranch_vccnz .LBB0_119
	s_barrier
	s_branch .LBB0_119

; __device__ __forceinline__ unsigned cvt_pk_bf16(float lo, float hi) { unsigned r; asm volatile("v_cvt_pk_bf16_f32 %0, %1, %2" : "=v"(r) : "v"(lo), "v"(hi)); return r; }
;     __device__ __forceinline__ void operator()(const f32x4 (&acc)[2][2][4][2], const Unit& u, int wr, int wc, int fr, int fq) const {
;         const int row0 = u.pm * BM + wr * 64 + fr; int colt = u.pn * BM; bf16_t* base = O;
;         float sc = 1.f; if (split_cols) { const int t = colt / split_cols; base += (size_t)t * split_stride; colt -= t * split_cols; if (t == 0) sc = scale0; }
;         const int col0 = colt + wc * 32 + 8 * fq, bcol0 = u.pn * BM + wc * 32 + 8 * fq;
;         f32x4 bv[2][2];
; #pragma unroll
;         for (int bj = 0; bj < 2; ++bj)
; #pragma unroll
;             for (int n = 0; n < 2; ++n) bv[bj][n] = bias ? *(const f32x4*)(bias + bcol0 + bj * HALF + 4 * n) : (f32x4){0.f, 0.f, 0.f, 0.f};
; #pragma unroll
;         for (int ai = 0; ai < 2; ++ai)
; #pragma unroll
;             for (int m = 0; m < 4; ++m) { bf16_t* rowp = base + (size_t)(row0 + ai * HALF + m * 16) * ldc + col0;
; #pragma unroll
;                 for (int bj = 0; bj < 2; ++bj) { f32x4 v0 = acc[ai][bj][m][0] + bv[bj][0], v1 = acc[ai][bj][m][1] + bv[bj][1];
;                     if (ACT == 1) { f32x2 a = gelu_pk((f32x2){v0[0], v0[1]}), b = gelu_pk((f32x2){v0[2], v0[3]}), c = gelu_pk((f32x2){v1[0], v1[1]}), d = gelu_pk((f32x2){v1[2], v1[3]});
;                         v0 = (f32x4){a.x, a.y, b.x, b.y}; v1 = (f32x4){c.x, c.y, d.x, d.y}; }
;                     v0 = v0 * sc; v1 = v1 * sc; u32x4 w; w.x = cvt_pk_bf16(v0[0], v0[1]); w.y = cvt_pk_bf16(v0[2], v0[3]); w.z = cvt_pk_bf16(v1[0], v1[1]); w.w = cvt_pk_bf16(v1[2], v1[3]);
;                     *(u32x4*)(rowp + bj * HALF) = w; } }
.LBB0_155:
	s_ashr_i32 s41, s88, 31
	s_lshr_b32 s41, s41, 27
	s_add_i32 s41, s88, s41
	s_ashr_i32 s58, s41, 5
	s_ashr_i32 s59, s58, 31
	s_lshl_b32 s19, s88, 8
	s_lshl_b64 s[60:61], s[58:59], 23
	s_add_u32 s60, s0, s60
	s_addc_u32 s61, s1, s61
	s_lshl_b32 s41, s58, 13
	s_sub_i32 s19, s19, s41
	v_lshl_add_u32 v152, s56, 8, v154
	v_or_b32_e32 v144, s19, v149
	v_ashrrev_i32_e32 v145, 31, v144
	v_ashrrev_i32_e32 v153, 31, v152
	v_lshl_add_u64 v[156:157], v[144:145], 1, s[60:61]
	v_lshlrev_b64 v[144:145], 14, v[152:153]
	v_lshl_add_u64 v[144:145], v[156:157], 0, v[144:145]
	v_pk_add_f32 v[126:127], v[126:127], 0 op_sel_hi:[1,0]
	v_pk_add_f32 v[124:125], v[124:125], 0 op_sel_hi:[1,0]
	v_pk_add_f32 v[158:159], v[122:123], 0 op_sel_hi:[1,0]
	v_pk_add_f32 v[122:123], v[120:121], 0 op_sel_hi:[1,0]
	v_cvt_pk_bf16_f32 v120, v124, v125
	v_cvt_pk_bf16_f32 v121, v126, v127
	v_pk_add_f32 v[116:117], v[116:117], 0 op_sel_hi:[1,0]
	v_cvt_pk_bf16_f32 v122, v122, v123
	v_cvt_pk_bf16_f32 v123, v158, v159
	global_store_dwordx4 v[144:145], v[120:123], off sc1
	v_pk_add_f32 v[118:119], v[118:119], 0 op_sel_hi:[1,0]
	v_pk_add_f32 v[112:113], v[112:113], 0 op_sel_hi:[1,0]
	v_pk_add_f32 v[120:121], v[110:111], 0 op_sel_hi:[1,0]
	v_pk_add_f32 v[110:111], v[108:109], 0 op_sel_hi:[1,0]
	v_cvt_pk_bf16_f32 v108, v116, v117
	v_cvt_pk_bf16_f32 v109, v118, v119
	v_pk_add_f32 v[100:101], v[100:101], 0 op_sel_hi:[1,0]
	v_cvt_pk_bf16_f32 v110, v110, v111
	v_cvt_pk_bf16_f32 v111, v120, v121
	global_store_dwordx4 v[144:145], v[108:111], off offset:256 sc1
	v_pk_add_f32 v[102:103], v[102:103], 0 op_sel_hi:[1,0]
	v_pk_add_f32 v[96:97], v[96:97], 0 op_sel_hi:[1,0]
	v_or_b32_e32 v108, 16, v152
	v_ashrrev_i32_e32 v109, 31, v108
	v_lshlrev_b64 v[108:109], 14, v[108:109]
	v_lshl_add_u64 v[108:109], v[156:157], 0, v[108:109]
	v_pk_add_f32 v[110:111], v[114:115], 0 op_sel_hi:[1,0]
	v_pk_add_f32 v[114:115], v[106:107], 0 op_sel_hi:[1,0]
	v_pk_add_f32 v[106:107], v[104:105], 0 op_sel_hi:[1,0]
	v_cvt_pk_bf16_f32 v104, v112, v113
	v_cvt_pk_bf16_f32 v105, v110, v111
	v_pk_add_f32 v[84:85], v[84:85], 0 op_sel_hi:[1,0]
	v_cvt_pk_bf16_f32 v106, v106, v107
	v_cvt_pk_bf16_f32 v107, v114, v115
	global_store_dwordx4 v[108:109], v[104:107], off sc1
	v_pk_add_f32 v[86:87], v[86:87], 0 op_sel_hi:[1,0]
	v_pk_add_f32 v[80:81], v[80:81], 0 op_sel_hi:[1,0]
	v_pk_add_f32 v[104:105], v[94:95], 0 op_sel_hi:[1,0]
	v_pk_add_f32 v[94:95], v[92:93], 0 op_sel_hi:[1,0]
	v_cvt_pk_bf16_f32 v92, v100, v101
	v_cvt_pk_bf16_f32 v93, v102, v103
	v_pk_add_f32 v[70:71], v[70:71], 0 op_sel_hi:[1,0]
	v_cvt_pk_bf16_f32 v94, v94, v95
	v_cvt_pk_bf16_f32 v95, v104, v105
	global_store_dwordx4 v[108:109], v[92:95], off offset:256 sc1
	v_pk_add_f32 v[68:69], v[68:69], 0 op_sel_hi:[1,0]
	v_pk_add_f32 v[60:61], v[60:61], 0 op_sel_hi:[1,0]
	v_or_b32_e32 v92, 32, v152
	v_ashrrev_i32_e32 v93, 31, v92
	v_lshlrev_b64 v[92:93], 14, v[92:93]
	v_lshl_add_u64 v[92:93], v[156:157], 0, v[92:93]
	v_pk_add_f32 v[94:95], v[98:99], 0 op_sel_hi:[1,0]
	v_pk_add_f32 v[98:99], v[90:91], 0 op_sel_hi:[1,0]
	v_pk_add_f32 v[90:91], v[88:89], 0 op_sel_hi:[1,0]
	v_cvt_pk_bf16_f32 v88, v96, v97
	v_cvt_pk_bf16_f32 v89, v94, v95
	s_mov_b32 s19, 0x200000
	v_cvt_pk_bf16_f32 v90, v90, v91
	v_cvt_pk_bf16_f32 v91, v98, v99
	global_store_dwordx4 v[92:93], v[88:91], off sc1
	v_pk_add_f32 v[62:63], v[62:63], 0 op_sel_hi:[1,0]
	s_mov_b64 s[58:59], 0x200000
	v_pk_add_f32 v[88:89], v[78:79], 0 op_sel_hi:[1,0]
	v_pk_add_f32 v[78:79], v[76:77], 0 op_sel_hi:[1,0]
	v_cvt_pk_bf16_f32 v76, v84, v85
	v_cvt_pk_bf16_f32 v77, v86, v87
	v_pk_add_f32 v[54:55], v[54:55], 0 op_sel_hi:[1,0]
	v_cvt_pk_bf16_f32 v78, v78, v79
	v_cvt_pk_bf16_f32 v79, v88, v89
	global_store_dwordx4 v[92:93], v[76:79], off offset:256 sc1
	v_pk_add_f32 v[52:53], v[52:53], 0 op_sel_hi:[1,0]
	v_pk_add_f32 v[48:49], v[48:49], 0 op_sel_hi:[1,0]
	v_or_b32_e32 v76, 48, v152
	v_ashrrev_i32_e32 v77, 31, v76
	v_lshlrev_b64 v[76:77], 14, v[76:77]
	v_lshl_add_u64 v[76:77], v[156:157], 0, v[76:77]
	v_pk_add_f32 v[78:79], v[82:83], 0 op_sel_hi:[1,0]
	v_pk_add_f32 v[82:83], v[74:75], 0 op_sel_hi:[1,0]
	v_pk_add_f32 v[74:75], v[72:73], 0 op_sel_hi:[1,0]
; __device__ __forceinline__ unsigned cvt_pk_bf16(float lo, float hi) { unsigned r; asm volatile("v_cvt_pk_bf16_f32 %0, %1, %2" : "=v"(r) : "v"(lo), "v"(hi)); return r; }
;     __device__ __forceinline__ void operator()(const f32x4 (&acc)[2][2][4][2], const Unit& u, int wr, int wc, int fr, int fq) const {
;     ...
;             for (int m = 0; m < 4; ++m) { bf16_t* rowp = base + (size_t)(row0 + ai * HALF + m * 16) * ldc + col0;
; #pragma unroll
;                 for (int bj = 0; bj < 2; ++bj) { f32x4 v0 = acc[ai][bj][m][0] + bv[bj][0], v1 = acc[ai][bj][m][1] + bv[bj][1];
;                     if (ACT == 1) { f32x2 a = gelu_pk((f32x2){v0[0], v0[1]}), b = gelu_pk((f32x2){v0[2], v0[3]}), c = gelu_pk((f32x2){v1[0], v1[1]}), d = gelu_pk((f32x2){v1[2], v1[3]});
;                         v0 = (f32x4){a.x, a.y, b.x, b.y}; v1 = (f32x4){c.x, c.y, d.x, d.y}; }
;                     v0 = v0 * sc; v1 = v1 * sc; u32x4 w; w.x = cvt_pk_bf16(v0[0], v0[1]); w.y = cvt_pk_bf16(v0[2], v0[3]); w.z = cvt_pk_bf16(v1[0], v1[1]); w.w = cvt_pk_bf16(v1[2], v1[3]);
;                     *(u32x4*)(rowp + bj * HALF) = w; } }
	v_cvt_pk_bf16_f32 v72, v80, v81
	v_cvt_pk_bf16_f32 v73, v78, v79
	v_pk_add_f32 v[38:39], v[38:39], 0 op_sel_hi:[1,0]
	v_cvt_pk_bf16_f32 v74, v74, v75
	v_cvt_pk_bf16_f32 v75, v82, v83
	global_store_dwordx4 v[76:77], v[72:75], off sc1
	v_pk_add_f32 v[36:37], v[36:37], 0 op_sel_hi:[1,0]
	v_pk_add_f32 v[32:33], v[32:33], 0 op_sel_hi:[1,0]
	v_pk_add_f32 v[72:73], v[66:67], 0 op_sel_hi:[1,0]
	v_pk_add_f32 v[66:67], v[64:65], 0 op_sel_hi:[1,0]
	v_cvt_pk_bf16_f32 v64, v68, v69
	v_cvt_pk_bf16_f32 v65, v70, v71
	v_pk_add_f32 v[22:23], v[22:23], 0 op_sel_hi:[1,0]
	v_cvt_pk_bf16_f32 v66, v66, v67
	v_cvt_pk_bf16_f32 v67, v72, v73
	global_store_dwordx4 v[76:77], v[64:67], off offset:256 sc1
	v_pk_add_f32 v[20:21], v[20:21], 0 op_sel_hi:[1,0]
	v_pk_add_f32 v[16:17], v[16:17], 0 op_sel_hi:[1,0]
	v_pk_add_f32 v[66:67], v[58:59], 0 op_sel_hi:[1,0]
	v_pk_add_f32 v[58:59], v[56:57], 0 op_sel_hi:[1,0]
	v_cvt_pk_bf16_f32 v56, v60, v61
	v_add_co_u32_e32 v60, vcc, s19, v144
	v_cvt_pk_bf16_f32 v57, v62, v63
	v_cvt_pk_bf16_f32 v58, v58, v59
	v_cvt_pk_bf16_f32 v59, v66, v67
	v_lshl_add_u64 v[64:65], v[144:145], 0, s[58:59]
	s_nop 0
	v_addc_co_u32_e32 v61, vcc, 0, v145, vcc
	global_store_dwordx4 v[60:61], v[56:59], off sc1
	s_mov_b64 s[58:59], 0x240000
	v_pk_add_f32 v[6:7], v[6:7], 0 op_sel_hi:[1,0]
	v_pk_add_f32 v[56:57], v[46:47], 0 op_sel_hi:[1,0]
	v_pk_add_f32 v[46:47], v[44:45], 0 op_sel_hi:[1,0]
	v_cvt_pk_bf16_f32 v44, v52, v53
	v_cvt_pk_bf16_f32 v45, v54, v55
	v_pk_add_f32 v[4:5], v[4:5], 0 op_sel_hi:[1,0]
	v_cvt_pk_bf16_f32 v46, v46, v47
	v_cvt_pk_bf16_f32 v47, v56, v57
	global_store_dwordx4 v[64:65], v[44:47], off offset:256 sc1
	s_nop 1
	v_pk_add_f32 v[46:47], v[50:51], 0 op_sel_hi:[1,0]
	v_pk_add_f32 v[50:51], v[42:43], 0 op_sel_hi:[1,0]
	v_pk_add_f32 v[42:43], v[40:41], 0 op_sel_hi:[1,0]
	v_cvt_pk_bf16_f32 v40, v48, v49
	v_cvt_pk_bf16_f32 v41, v46, v47
	v_add_co_u32_e32 v46, vcc, s85, v144
	v_cvt_pk_bf16_f32 v42, v42, v43
	v_cvt_pk_bf16_f32 v43, v50, v51
	v_lshl_add_u64 v[44:45], v[144:145], 0, s[58:59]
	s_nop 0
	v_addc_co_u32_e32 v47, vcc, 0, v145, vcc
	global_store_dwordx4 v[46:47], v[40:43], off sc1
	s_nop 1
	v_pk_add_f32 v[40:41], v[30:31], 0 op_sel_hi:[1,0]
	v_pk_add_f32 v[30:31], v[28:29], 0 op_sel_hi:[1,0]
	v_cvt_pk_bf16_f32 v28, v36, v37
	v_cvt_pk_bf16_f32 v29, v38, v39
	s_nop 0
	v_cvt_pk_bf16_f32 v30, v30, v31
	v_cvt_pk_bf16_f32 v31, v40, v41
	global_store_dwordx4 v[44:45], v[28:31], off offset:256 sc1
	s_nop 1
	v_pk_add_f32 v[30:31], v[34:35], 0 op_sel_hi:[1,0]
	v_pk_add_f32 v[34:35], v[26:27], 0 op_sel_hi:[1,0]
	v_pk_add_f32 v[26:27], v[24:25], 0 op_sel_hi:[1,0]
	v_cvt_pk_bf16_f32 v24, v32, v33
	v_cvt_pk_bf16_f32 v25, v30, v31
	v_add_co_u32_e32 v30, vcc, s86, v144
	v_cvt_pk_bf16_f32 v26, v26, v27
	v_cvt_pk_bf16_f32 v27, v34, v35
	v_lshl_add_u64 v[28:29], v[144:145], 0, s[12:13]
	s_nop 0
	v_addc_co_u32_e32 v31, vcc, 0, v145, vcc
	global_store_dwordx4 v[30:31], v[24:27], off sc1
	s_nop 1
	v_pk_add_f32 v[24:25], v[14:15], 0 op_sel_hi:[1,0]
	v_pk_add_f32 v[14:15], v[12:13], 0 op_sel_hi:[1,0]
	v_cvt_pk_bf16_f32 v12, v20, v21
	v_cvt_pk_bf16_f32 v13, v22, v23
	s_nop 0
	v_cvt_pk_bf16_f32 v14, v14, v15
	v_cvt_pk_bf16_f32 v15, v24, v25
	global_store_dwordx4 v[28:29], v[12:15], off offset:256 sc1
	s_nop 1
	v_pk_add_f32 v[14:15], v[18:19], 0 op_sel_hi:[1,0]
	v_pk_add_f32 v[18:19], v[10:11], 0 op_sel_hi:[1,0]
	v_pk_add_f32 v[10:11], v[8:9], 0 op_sel_hi:[1,0]
	v_cvt_pk_bf16_f32 v8, v16, v17
	v_cvt_pk_bf16_f32 v9, v14, v15
	v_add_co_u32_e32 v14, vcc, s87, v144
	v_lshl_add_u64 v[12:13], v[144:145], 0, s[16:17]
	s_nop 0
	v_addc_co_u32_e32 v15, vcc, 0, v145, vcc
	v_cvt_pk_bf16_f32 v10, v10, v11
	v_cvt_pk_bf16_f32 v11, v18, v19
	global_store_dwordx4 v[14:15], v[8:11], off sc1
	s_andn2_b64 vcc, exec, s[2:3]
	s_mov_b64 s[2:3], -1
	v_pk_add_f32 v[8:9], v[2:3], 0 op_sel_hi:[1,0]
	v_pk_add_f32 v[2:3], v[0:1], 0 op_sel_hi:[1,0]
	v_cvt_pk_bf16_f32 v0, v4, v5
	v_cvt_pk_bf16_f32 v1, v6, v7
	s_nop 0
	v_cvt_pk_bf16_f32 v2, v2, v3
	v_cvt_pk_bf16_f32 v3, v8, v9
	global_store_dwordx4 v[12:13], v[0:3], off offset:256 sc1
	s_cbranch_vccnz .LBB0_144
	s_andn2_b64 vcc, exec, s[6:7]
	s_cbranch_vccnz .LBB0_143
	s_barrier
	s_branch .LBB0_143

; __device__ __forceinline__ float fexp(float x) { return __builtin_amdgcn_exp2f(x * 1.4426950408889634f); }
; #define LAS __attribute__((address_space(3)))
; __device__ __forceinline__ float fexp(float x) { return __builtin_amdgcn_exp2f(x * 1.4426950408889634f); }
; __device__ __forceinline__ float fsigmoid(float x) { return __builtin_amdgcn_rcpf(1.0f + fexp(-x)); }
; template <int PASS>
; __device__ __forceinline__ void lru_unit(const LruP& P, const LruInv& V, int b, int c, LAS unsigned char* wl, LAS float* red, int wave, int lane, int pairpos) {
;     ...
;         for (int ks = 0; ks < 2; ++ks) Xf[ks] = *(const LAS bf16x8*)(xc + (16 * m + fr) * 72 + 32 * ks + 8 * fq);
; #pragma unroll
;         for (int n = 0; n < 4; ++n) {
;             f32x4 R = (f32x4){0.f, 0.f, 0.f, 0.f}, I = (f32x4){0.f, 0.f, 0.f, 0.f};
; #pragma unroll
;             for (int ks = 0; ks < 2; ++ks) {
;                 R = __builtin_amdgcn_mfma_f32_16x16x32_bf16(V.Wr[n][ks], Xf[ks], R, 0, 0, 0);
;                 I = __builtin_amdgcn_mfma_f32_16x16x32_bf16(V.Wi[n][ks], Xf[ks], I, 0, 0, 0); }
;             const f32x4 br = V.br[n], bi = V.bi[n], sl = V.sl[n];
;             const v2u xw = *(const LAS v2u*)(xc + (16 * m + fr) * 72 + 16 * n + 4 * fq);
;             const float xv[4] = {bflo(xw.x), bfhi(xw.x), bflo(xw.y), bfhi(xw.y)};
;             const v2u gw = gcur[n];
;             const float gv[4] = {bflo(gw.x), bfhi(gw.x), bflo(gw.y), bfhi(gw.y)};
;             float av[4], bv[4], laraw[4], braw[4];
; #pragma unroll
;             for (int j = 0; j < 4; ++j) {
;                 const float r = fsigmoid(R[j] + br[j]), ig = fsigmoid(I[j] + bi[j]);
;                 const float la = r * sl[j];
;                 const float a = fexp(la);
;                 const float bt = __builtin_amdgcn_sqrtf(fmaxf(1.0f - a * a, 0.f)) * (ig * xv[j]);
;                 laraw[j] = la; braw[j] = bt;
;                 const float cin = row_ror1(hin[n][j]);
;                 bv[j] = fmaf(a, lane0 ? cin : 0.f, bt);
;                 if (PASS == 1) { const float ain = row_ror1(arun[n][j]); av[j] = lane0 ? a * ain : a; } else av[j] = a;
.LBB0_334:
	v_add_u32_e32 v123, s6, v195
	ds_read_b128 v[184:187], v123
	ds_read_b128 v[160:163], v123 offset:64
	v_mov_b32_e32 v142, 0
	v_mov_b32_e32 v151, 0
	v_mov_b32_e32 v131, 0
	s_waitcnt lgkmcnt(1)
	v_mfma_f32_16x16x32_bf16 v[188:191], v[0:3], v[184:187], 0
	v_mov_b32_dpp v142, v183 row_ror:1 row_mask:0xf bank_mask:0xf
	v_mov_b32_dpp v151, v182 row_ror:1 row_mask:0xf bank_mask:0xf
	v_mov_b32_e32 v146, 0
	v_mfma_f32_16x16x32_bf16 v[202:205], v[4:7], v[184:187], 0
	v_mov_b32_e32 v155, 0
	v_mov_b32_e32 v122, 0
	v_mov_b32_e32 v130, 0
	v_mfma_f32_16x16x32_bf16 v[208:211], v[16:19], v[184:187], 0
	v_mov_b32_e32 v138, 0
	v_mov_b32_e32 v139, 0
	v_mov_b32_e32 v143, 0
	v_mfma_f32_16x16x32_bf16 v[212:215], v[20:23], v[184:187], 0
	v_mov_b32_e32 v158, 0
	v_mov_b32_dpp v131, v152 row_ror:1 row_mask:0xf bank_mask:0xf
	v_mov_b32_dpp v146, v132 row_ror:1 row_mask:0xf bank_mask:0xf
	v_mfma_f32_16x16x32_bf16 v[216:219], v[32:35], v[184:187], 0
	v_mov_b32_dpp v155, v112 row_ror:1 row_mask:0xf bank_mask:0xf
	v_mov_b32_e32 v228, 0
	v_mov_b32_dpp v122, v148 row_ror:1 row_mask:0xf bank_mask:0xf
	v_mfma_f32_16x16x32_bf16 v[220:223], v[36:39], v[184:187], 0
	v_mov_b32_dpp v130, v144 row_ror:1 row_mask:0xf bank_mask:0xf
	v_mov_b32_dpp v138, v134 row_ror:1 row_mask:0xf bank_mask:0xf
	v_mov_b32_dpp v139, v136 row_ror:1 row_mask:0xf bank_mask:0xf
	v_mfma_f32_16x16x32_bf16 v[224:227], v[48:51], v[184:187], 0
	v_mov_b32_dpp v143, v140 row_ror:1 row_mask:0xf bank_mask:0xf
	v_mov_b32_dpp v158, v120 row_ror:1 row_mask:0xf bank_mask:0xf
	v_cndmask_b32_e32 v120, 0, v131, vcc
	v_mfma_f32_16x16x32_bf16 v[182:185], v[52:55], v[184:187], 0
	v_cndmask_b32_e32 v131, 0, v146, vcc
	v_cndmask_b32_e32 v146, 0, v155, vcc
	v_mov_b32_dpp v228, v180 row_ror:1 row_mask:0xf bank_mask:0xf
	s_waitcnt lgkmcnt(0)
	v_mfma_f32_16x16x32_bf16 v[186:189], v[8:11], v[160:163], v[188:191]
	v_mov_b32_e32 v150, 0
	v_mov_b32_e32 v156, 0
	v_add_u32_e32 v116, s6, v196
	v_mfma_f32_16x16x32_bf16 v[190:193], v[12:15], v[160:163], v[202:205]
	v_mov_b32_dpp v150, v124 row_ror:1 row_mask:0xf bank_mask:0xf
	s_nop 2
	v_add_f32_e32 v134, v108, v186
	v_add_f32_e32 v140, v109, v187
	v_mfma_f32_16x16x32_bf16 v[202:205], v[24:27], v[160:163], v[208:211]
	v_add_f32_e32 v148, v110, v188
	v_add_f32_e32 v136, v100, v190
	v_add_f32_e32 v144, v101, v191
	v_mfma_f32_16x16x32_bf16 v[208:211], v[28:31], v[160:163], v[212:215]
	v_add_f32_e32 v155, v111, v189
	v_add_f32_e32 v152, v102, v192
	v_mul_f32_e32 v134, 0xbfb8aa3b, v134
	v_mfma_f32_16x16x32_bf16 v[212:215], v[40:43], v[160:163], v[216:219]
	v_mul_f32_e32 v136, 0xbfb8aa3b, v136
	s_nop 2
	v_add_f32_e32 v180, v96, v208
	v_mul_f32_e32 v140, 0xbfb8aa3b, v140
	v_mfma_f32_16x16x32_bf16 v[216:219], v[44:47], v[160:163], v[220:223]
	v_mul_f32_e32 v144, 0xbfb8aa3b, v144
	v_mul_f32_e32 v148, 0xbfb8aa3b, v148
	v_mul_f32_e32 v155, 0xbfb8aa3b, v155
	v_mfma_f32_16x16x32_bf16 v[220:223], v[56:59], v[160:163], v[224:227]
	v_mul_f32_e32 v152, 0xbfb8aa3b, v152
	v_exp_f32_e32 v134, v134
	v_exp_f32_e32 v136, v136
	v_mfma_f32_16x16x32_bf16 v[160:163], v[60:63], v[160:163], v[182:185]
	v_exp_f32_e32 v140, v140
	s_nop 2
	v_add_f32_e32 v208, v83, v223
	v_mul_f32_e32 v208, 0xbfb8aa3b, v208
	v_add_f32_e32 v183, v106, v204
	v_add_f32_e32 v185, v107, v205
	v_add_f32_e32 v160, v72, v160
	v_add_f32_e32 v204, v81, v221
	v_add_f32_e32 v161, v73, v161
	v_add_f32_e32 v205, v82, v222
	v_add_f32_e32 v162, v74, v162
	v_mul_f32_e32 v160, 0xbfb8aa3b, v160
	v_mul_f32_e32 v204, 0xbfb8aa3b, v204
	v_mul_f32_e32 v161, 0xbfb8aa3b, v161
	v_mul_f32_e32 v205, 0xbfb8aa3b, v205
	v_mul_f32_e32 v162, 0xbfb8aa3b, v162
	v_exp_f32_e32 v144, v144
	v_exp_f32_e32 v148, v148
	v_exp_f32_e32 v155, v155
	v_mov_b32_dpp v156, v181 row_ror:1 row_mask:0xf bank_mask:0xf
	v_exp_f32_e32 v152, v152
	v_exp_f32_e32 v160, v160
	v_exp_f32_e32 v204, v204
	v_exp_f32_e32 v161, v161
	v_exp_f32_e32 v205, v205
	v_exp_f32_e32 v162, v162
	v_exp_f32_e32 v208, v208
	v_cndmask_b32_e32 v112, 0, v122, vcc
	v_cndmask_b32_e32 v122, 0, v138, vcc
	v_cndmask_b32_e32 v124, 0, v139, vcc
	v_cndmask_b32_e32 v138, 0, v150, vcc
	v_cndmask_b32_e32 v139, 0, v151, vcc
	v_cndmask_b32_e32 v150, 0, v156, vcc
	v_cndmask_b32_e32 v151, 0, v158, vcc
	v_add_f32_e32 v156, v103, v193
	v_add_f32_e32 v158, v104, v202
	v_add_f32_e32 v181, v105, v203
	v_add_f32_e32 v187, v84, v212
	ds_read_b64 v[126:127], v116
	v_add_f32_e32 v189, v85, v213
	v_add_f32_e32 v191, v86, v214
	v_add_f32_e32 v193, v87, v215
	v_add_f32_e32 v203, v80, v220
	v_add_f32_e32 v163, v75, v163
	v_mul_f32_e32 v156, 0xbfb8aa3b, v156
	v_mul_f32_e32 v158, 0xbfb8aa3b, v158
	v_mul_f32_e32 v181, 0xbfb8aa3b, v181
	v_mul_f32_e32 v185, 0xbfb8aa3b, v185
	v_mul_f32_e32 v187, 0xbfb8aa3b, v187
	v_mul_f32_e32 v183, 0xbfb8aa3b, v183
	v_mul_f32_e32 v189, 0xbfb8aa3b, v189
	v_mul_f32_e32 v191, 0xbfb8aa3b, v191
	v_mul_f32_e32 v193, 0xbfb8aa3b, v193
	v_mul_f32_e32 v203, 0xbfb8aa3b, v203
	v_mul_f32_e32 v163, 0xbfb8aa3b, v163
	v_exp_f32_e32 v156, v156
	v_exp_f32_e32 v158, v158
	v_exp_f32_e32 v181, v181
	v_exp_f32_e32 v185, v185
	v_exp_f32_e32 v187, v187
	v_add_f32_e32 v134, 1.0, v134
	v_add_f32_e32 v136, 1.0, v136
	v_add_f32_e32 v140, 1.0, v140
	v_add_f32_e32 v144, 1.0, v144
	v_add_f32_e32 v148, 1.0, v148
	v_add_f32_e32 v155, 1.0, v155
	v_exp_f32_e32 v183, v183
	v_exp_f32_e32 v189, v189
	v_exp_f32_e32 v191, v191
	v_exp_f32_e32 v193, v193
	v_exp_f32_e32 v203, v203
	v_exp_f32_e32 v163, v163
	v_add_f32_e32 v152, 1.0, v152
	v_add_f32_e32 v160, 1.0, v160
	v_add_f32_e32 v204, 1.0, v204
	v_add_f32_e32 v161, 1.0, v161
	v_add_f32_e32 v205, 1.0, v205
	v_add_f32_e32 v162, 1.0, v162
	v_add_f32_e32 v208, 1.0, v208
	v_rcp_f32_e32 v134, v134
	v_rcp_f32_e32 v136, v136
	v_rcp_f32_e32 v140, v140
	v_rcp_f32_e32 v144, v144
	v_rcp_f32_e32 v148, v148
	v_rcp_f32_e32 v155, v155
	v_mov_b32_e32 v123, 0
	v_add_f32_e32 v182, v97, v209
	v_rcp_f32_e32 v152, v152
	v_rcp_f32_e32 v209, v160
	v_rcp_f32_e32 v160, v204
	v_rcp_f32_e32 v204, v161
	v_rcp_f32_e32 v161, v205
	v_rcp_f32_e32 v205, v162
	v_rcp_f32_e32 v162, v208
	v_mov_b32_dpp v123, v128 row_ror:1 row_mask:0xf bank_mask:0xf
	v_cndmask_b32_e32 v128, 0, v142, vcc
	v_cndmask_b32_e32 v142, 0, v123, vcc
	s_waitcnt lgkmcnt(0)
; __device__ __forceinline__ float fexp(float x) { return __builtin_amdgcn_exp2f(x * 1.4426950408889634f); }
; #define LAS __attribute__((address_space(3)))
; __device__ __forceinline__ unsigned pk2(float lo, float hi) { return pg8::cvt_pk_bf16(lo, hi); }
; __device__ __forceinline__ float fexp(float x) { return __builtin_amdgcn_exp2f(x * 1.4426950408889634f); }
; __device__ __forceinline__ float fsigmoid(float x) { return __builtin_amdgcn_rcpf(1.0f + fexp(-x)); }
; template <int PASS>
; __device__ __forceinline__ void lru_unit(const LruP& P, const LruInv& V, int b, int c, LAS unsigned char* wl, LAS float* red, int wave, int lane, int pairpos) {
;     ...
;             const f32x4 br = V.br[n], bi = V.bi[n], sl = V.sl[n];
;             const v2u xw = *(const LAS v2u*)(xc + (16 * m + fr) * 72 + 16 * n + 4 * fq);
;             const float xv[4] = {bflo(xw.x), bfhi(xw.x), bflo(xw.y), bfhi(xw.y)};
;             const v2u gw = gcur[n];
;             const float gv[4] = {bflo(gw.x), bfhi(gw.x), bflo(gw.y), bfhi(gw.y)};
;             float av[4], bv[4], laraw[4], braw[4];
; #pragma unroll
;             for (int j = 0; j < 4; ++j) {
;                 const float r = fsigmoid(R[j] + br[j]), ig = fsigmoid(I[j] + bi[j]);
;                 const float la = r * sl[j];
;                 const float a = fexp(la);
;                 const float bt = __builtin_amdgcn_sqrtf(fmaxf(1.0f - a * a, 0.f)) * (ig * xv[j]);
;                 laraw[j] = la; braw[j] = bt;
;                 const float cin = row_ror1(hin[n][j]);
;                 bv[j] = fmaf(a, lane0 ? cin : 0.f, bt);
;                 if (PASS == 1) { const float ain = row_ror1(arun[n][j]); av[j] = lane0 ? a * ain : a; } else av[j] = a;
;             }
;             if (PASS == 1) { v4u w; w.x = pk2(laraw[0], laraw[1]); w.y = pk2(laraw[2], laraw[3]); w.z = pk2(braw[0], braw[1]); w.w = pk2(braw[2], braw[3]);
;                 ((v4u*)P.AB)[((((size_t)(b * NCH + c) * 8 + wave) * 4 + m) * 4 + n) * 64 + lane] = w; }
;             scan4(av, bv);
; #pragma unroll
;             for (int j = 0; j < 4; ++j) {
;                 hin[n][j] = bv[j];
;                 if (PASS == 1) arun[n][j] = av[j];
	v_lshlrev_b32_e32 v123, 16, v126
	v_and_b32_e32 v126, 0xffff0000, v126
	v_add_f32_e32 v156, 1.0, v156
	v_add_f32_e32 v158, 1.0, v158
	v_add_f32_e32 v181, 1.0, v181
	v_add_f32_e32 v185, 1.0, v185
	v_add_f32_e32 v187, 1.0, v187
	v_lshlrev_b32_e32 v132, 16, v127
	v_add_f32_e32 v183, 1.0, v183
	v_add_f32_e32 v189, 1.0, v189
	v_add_f32_e32 v191, 1.0, v191
	v_add_f32_e32 v193, 1.0, v193
	v_add_f32_e32 v203, 1.0, v203
	v_add_f32_e32 v163, 1.0, v163
	v_rcp_f32_e32 v156, v156
	v_rcp_f32_e32 v158, v158
	v_rcp_f32_e32 v181, v181
	v_rcp_f32_e32 v185, v185
	v_rcp_f32_e32 v187, v187
	v_mul_f32_e32 v134, v92, v134
	v_mul_f32_e32 v123, v136, v123
	v_mul_f32_e32 v136, v93, v140
	v_mul_f32_e32 v126, v144, v126
	v_mul_f32_e32 v140, v94, v148
	v_mul_f32_e32 v144, v95, v155
	v_add_f32_e32 v186, v99, v211
	v_rcp_f32_e32 v183, v183
	v_rcp_f32_e32 v189, v189
	v_rcp_f32_e32 v191, v191
	v_rcp_f32_e32 v193, v193
	v_rcp_f32_e32 v203, v203
	v_rcp_f32_e32 v208, v163
	v_mul_f32_e32 v132, v152, v132
	v_mul_f32_e32 v211, v67, v162
	v_mul_f32_e32 v148, 0x3fb8aa3b, v134
	v_mul_f32_e32 v152, 0x3fb8aa3b, v136
	v_mul_f32_e32 v162, 0x3fb8aa3b, v140
	v_mul_f32_e32 v163, 0x3fb8aa3b, v144
	v_exp_f32_e32 v148, v148
	v_exp_f32_e32 v152, v152
	v_exp_f32_e32 v162, v162
	v_exp_f32_e32 v163, v163
	v_and_b32_e32 v127, 0xffff0000, v127
	v_mul_f32_e32 v127, v156, v127
	v_mul_f32_e32 v155, v88, v158
	v_mul_f32_e32 v156, v89, v181
	v_mul_f32_e32 v181, v91, v185
	v_mul_f32_e32 v185, v68, v187
	v_add_f32_e32 v184, v98, v210
	v_mul_f32_e32 v158, v90, v183
	v_mul_f32_e32 v187, v69, v189
	v_mul_f32_e32 v189, v70, v191
	v_mul_f32_e32 v191, v71, v193
	v_mul_f32_e32 v193, v64, v203
	v_mul_f32_e32 v203, v65, v160
	v_mul_f32_e32 v210, v66, v161
	v_cvt_pk_bf16_f32 v160, v134, v136
	v_cvt_pk_bf16_f32 v161, v140, v144
	v_mul_f32_e32 v134, 0x3fb8aa3b, v155
	v_mul_f32_e32 v136, 0x3fb8aa3b, v156
	v_mul_f32_e32 v144, 0x3fb8aa3b, v181
	v_mul_f32_e32 v183, 0x3fb8aa3b, v185
	v_add_f32_e32 v202, v79, v219
	v_exp_f32_e32 v219, v134
	v_exp_f32_e32 v220, v136
	v_exp_f32_e32 v221, v144
	v_exp_f32_e32 v222, v183
	v_fma_f32 v134, -v148, v148, 1.0
	v_mul_f32_dpp v136, v149, v148 row_ror:1 row_mask:0xf bank_mask:0xf bound_ctrl:1
	v_fma_f32 v144, -v152, v152, 1.0
	v_fma_f32 v183, -v162, v162, 1.0
	v_fma_f32 v223, -v163, v163, 1.0
	v_max_f32_e32 v134, 0, v134
	v_cndmask_b32_e32 v149, v148, v136, vcc
	v_max_f32_e32 v136, 0, v144
	v_max_f32_e32 v144, 0, v183
	v_max_f32_e32 v183, 0, v223
	v_sqrt_f32_e32 v134, v134
	v_sqrt_f32_e32 v136, v136
	v_sqrt_f32_e32 v144, v144
	v_sqrt_f32_e32 v183, v183
	v_mul_f32_e32 v180, 0xbfb8aa3b, v180
	v_mul_f32_e32 v182, 0xbfb8aa3b, v182
	v_mul_f32_e32 v184, 0xbfb8aa3b, v184
	v_mul_f32_e32 v186, 0xbfb8aa3b, v186
	v_mul_f32_e32 v140, 0x3fb8aa3b, v158
	v_mov_b32_e32 v154, 0
	v_exp_f32_e32 v180, v180
	v_exp_f32_e32 v182, v182
	v_exp_f32_e32 v184, v184
	v_exp_f32_e32 v186, v186
	v_exp_f32_e32 v140, v140
	v_mov_b32_dpp v154, v118 row_ror:1 row_mask:0xf bank_mask:0xf
	v_cndmask_b32_e32 v118, 0, v130, vcc
	v_mul_f32_dpp v157, v157, v152 row_ror:1 row_mask:0xf bank_mask:0xf bound_ctrl:1
	v_mul_f32_dpp v153, v153, v162 row_ror:1 row_mask:0xf bank_mask:0xf bound_ctrl:1
	v_mul_f32_dpp v159, v159, v163 row_ror:1 row_mask:0xf bank_mask:0xf bound_ctrl:1
	v_mul_f32_e32 v123, v123, v134
	v_mul_f32_e32 v126, v126, v136
	v_mul_f32_e32 v132, v132, v144
	v_mul_f32_e32 v127, v127, v183
	v_cndmask_b32_e32 v157, v152, v157, vcc
	v_cndmask_b32_e32 v153, v162, v153, vcc
	v_cndmask_b32_e32 v159, v163, v159, vcc
	v_fma_f32 v148, v148, v112, v123
	v_fma_f32 v144, v152, v118, v126
	v_fma_f32 v152, v162, v120, v132
	v_fma_f32 v134, v163, v122, v127
	v_cvt_pk_bf16_f32 v162, v123, v126
	v_cvt_pk_bf16_f32 v163, v132, v127
	global_store_dwordx4 v[114:115], v[160:163], off offset:-2048 sc1
	s_nop 1
	v_fmac_f32_dpp v148, v148, v149 row_shr:1 row_mask:0xf bank_mask:0xf
	v_fmac_f32_dpp v144, v144, v157 row_shr:1 row_mask:0xf bank_mask:0xf
	v_fmac_f32_dpp v152, v152, v153 row_shr:1 row_mask:0xf bank_mask:0xf
	v_fmac_f32_dpp v134, v134, v159 row_shr:1 row_mask:0xf bank_mask:0xf
	v_mul_f32_dpp v149, v149, v149 row_shr:1 row_mask:0xf bank_mask:0xf
	v_mul_f32_dpp v157, v157, v157 row_shr:1 row_mask:0xf bank_mask:0xf
	v_mul_f32_dpp v153, v153, v153 row_shr:1 row_mask:0xf bank_mask:0xf
	v_mul_f32_dpp v159, v159, v159 row_shr:1 row_mask:0xf bank_mask:0xf
	v_fmac_f32_dpp v148, v148, v149 row_shr:2 row_mask:0xf bank_mask:0xf
	v_fmac_f32_dpp v144, v144, v157 row_shr:2 row_mask:0xf bank_mask:0xf
	v_fmac_f32_dpp v152, v152, v153 row_shr:2 row_mask:0xf bank_mask:0xf
	v_fmac_f32_dpp v134, v134, v159 row_shr:2 row_mask:0xf bank_mask:0xf
	v_mul_f32_dpp v149, v149, v149 row_shr:2 row_mask:0xf bank_mask:0xf
	v_mul_f32_dpp v157, v157, v157 row_shr:2 row_mask:0xf bank_mask:0xf
	v_mul_f32_dpp v153, v153, v153 row_shr:2 row_mask:0xf bank_mask:0xf
	v_mul_f32_dpp v159, v159, v159 row_shr:2 row_mask:0xf bank_mask:0xf
	v_fmac_f32_dpp v148, v148, v149 row_shr:4 row_mask:0xf bank_mask:0xf
	v_fmac_f32_dpp v144, v144, v157 row_shr:4 row_mask:0xf bank_mask:0xf
	v_fmac_f32_dpp v152, v152, v153 row_shr:4 row_mask:0xf bank_mask:0xf
	v_fmac_f32_dpp v134, v134, v159 row_shr:4 row_mask:0xf bank_mask:0xf
	v_mul_f32_dpp v149, v149, v149 row_shr:4 row_mask:0xf bank_mask:0xf
	v_mul_f32_dpp v157, v157, v157 row_shr:4 row_mask:0xf bank_mask:0xf
	v_mul_f32_dpp v153, v153, v153 row_shr:4 row_mask:0xf bank_mask:0xf
	v_mul_f32_dpp v159, v159, v159 row_shr:4 row_mask:0xf bank_mask:0xf
	v_fmac_f32_dpp v148, v148, v149 row_shr:8 row_mask:0xf bank_mask:0xf
	v_fmac_f32_dpp v144, v144, v157 row_shr:8 row_mask:0xf bank_mask:0xf
	v_fmac_f32_dpp v152, v152, v153 row_shr:8 row_mask:0xf bank_mask:0xf
	v_fmac_f32_dpp v134, v134, v159 row_shr:8 row_mask:0xf bank_mask:0xf
	v_mul_f32_dpp v149, v149, v149 row_shr:8 row_mask:0xf bank_mask:0xf
	v_mul_f32_dpp v157, v157, v157 row_shr:8 row_mask:0xf bank_mask:0xf
	v_mul_f32_dpp v153, v153, v153 row_shr:8 row_mask:0xf bank_mask:0xf
	v_mul_f32_dpp v159, v159, v159 row_shr:8 row_mask:0xf bank_mask:0xf

; __device__ __forceinline__ float fexp(float x) { return __builtin_amdgcn_exp2f(x * 1.4426950408889634f); }
; #define LAS __attribute__((address_space(3)))
; __device__ __forceinline__ unsigned pk2(float lo, float hi) { return pg8::cvt_pk_bf16(lo, hi); }
; __device__ __forceinline__ float fexp(float x) { return __builtin_amdgcn_exp2f(x * 1.4426950408889634f); }
; __device__ __forceinline__ float fsigmoid(float x) { return __builtin_amdgcn_rcpf(1.0f + fexp(-x)); }
; template <int PASS>
; __device__ __forceinline__ void lru_unit(const LruP& P, const LruInv& V, int b, int c, LAS unsigned char* wl, LAS float* red, int wave, int lane, int pairpos) {
;     ...
;             const f32x4 br = V.br[n], bi = V.bi[n], sl = V.sl[n];
;             const v2u xw = *(const LAS v2u*)(xc + (16 * m + fr) * 72 + 16 * n + 4 * fq);
;             const float xv[4] = {bflo(xw.x), bfhi(xw.x), bflo(xw.y), bfhi(xw.y)};
;             const v2u gw = gcur[n];
;             const float gv[4] = {bflo(gw.x), bfhi(gw.x), bflo(gw.y), bfhi(gw.y)};
;             float av[4], bv[4], laraw[4], braw[4];
; #pragma unroll
;             for (int j = 0; j < 4; ++j) {
;                 const float r = fsigmoid(R[j] + br[j]), ig = fsigmoid(I[j] + bi[j]);
;                 const float la = r * sl[j];
;                 const float a = fexp(la);
;                 const float bt = __builtin_amdgcn_sqrtf(fmaxf(1.0f - a * a, 0.f)) * (ig * xv[j]);
;                 laraw[j] = la; braw[j] = bt;
;                 const float cin = row_ror1(hin[n][j]);
;                 bv[j] = fmaf(a, lane0 ? cin : 0.f, bt);
;                 if (PASS == 1) { const float ain = row_ror1(arun[n][j]); av[j] = lane0 ? a * ain : a; } else av[j] = a;
;             }
;             if (PASS == 1) { v4u w; w.x = pk2(laraw[0], laraw[1]); w.y = pk2(laraw[2], laraw[3]); w.z = pk2(braw[0], braw[1]); w.w = pk2(braw[2], braw[3]);
;                 ((v4u*)P.AB)[((((size_t)(b * NCH + c) * 8 + wave) * 4 + m) * 4 + n) * 64 + lane] = w; }
;             scan4(av, bv);
; #pragma unroll
;             for (int j = 0; j < 4; ++j) {
;                 hin[n][j] = bv[j];
;                 if (PASS == 1) arun[n][j] = av[j];
	ds_read_b64 v[122:123], v116 offset:32
	v_add_f32_e32 v180, 1.0, v180
	v_add_f32_e32 v182, 1.0, v182
	v_add_f32_e32 v184, 1.0, v184
	v_add_f32_e32 v186, 1.0, v186
	v_fma_f32 v224, -v219, v219, 1.0
	v_fma_f32 v225, -v220, v220, 1.0
	v_fma_f32 v226, -v140, v140, 1.0
	v_fma_f32 v227, -v221, v221, 1.0
	v_rcp_f32_e32 v180, v180
	v_rcp_f32_e32 v182, v182
	v_rcp_f32_e32 v184, v184
	v_rcp_f32_e32 v186, v186
	v_max_f32_e32 v223, 0, v224
	v_max_f32_e32 v224, 0, v225
	v_max_f32_e32 v225, 0, v226
	v_max_f32_e32 v226, 0, v227
	v_sqrt_f32_e32 v223, v223
	v_sqrt_f32_e32 v224, v224
	v_sqrt_f32_e32 v225, v225
	v_sqrt_f32_e32 v226, v226
	v_add_f32_e32 v188, v76, v216
	v_add_f32_e32 v190, v77, v217
	v_add_f32_e32 v192, v78, v218
	v_mul_f32_e32 v188, 0xbfb8aa3b, v188
	v_mul_f32_e32 v190, 0xbfb8aa3b, v190
	v_mul_f32_e32 v192, 0xbfb8aa3b, v192
	v_mul_f32_e32 v202, 0xbfb8aa3b, v202
	v_mul_f32_e32 v212, 0x3fb8aa3b, v187
	v_mul_f32_e32 v213, 0x3fb8aa3b, v189
	v_mul_f32_e32 v214, 0x3fb8aa3b, v191
	s_waitcnt lgkmcnt(0)
	v_lshlrev_b32_e32 v112, 16, v122
	v_and_b32_e32 v118, 0xffff0000, v122
	v_lshlrev_b32_e32 v120, 16, v123
	v_and_b32_e32 v122, 0xffff0000, v123
	v_exp_f32_e32 v188, v188
	v_exp_f32_e32 v190, v190
	v_exp_f32_e32 v192, v192
	v_exp_f32_e32 v202, v202
	v_exp_f32_e32 v212, v212
	v_exp_f32_e32 v213, v213
	v_exp_f32_e32 v214, v214
	v_mul_f32_e32 v112, v180, v112
	v_mul_f32_e32 v118, v182, v118
	v_mul_f32_e32 v120, v184, v120
	v_mul_f32_e32 v122, v186, v122
	v_cndmask_b32_e32 v130, 0, v143, vcc
	v_mul_f32_dpp v137, v137, v219 row_ror:1 row_mask:0xf bank_mask:0xf bound_ctrl:1
	v_mul_f32_dpp v145, v145, v220 row_ror:1 row_mask:0xf bank_mask:0xf bound_ctrl:1
	v_mul_f32_dpp v141, v141, v140 row_ror:1 row_mask:0xf bank_mask:0xf bound_ctrl:1
	v_mul_f32_dpp v147, v147, v221 row_ror:1 row_mask:0xf bank_mask:0xf bound_ctrl:1
	v_mul_f32_e32 v112, v112, v223
	v_mul_f32_e32 v118, v118, v224
	v_mul_f32_e32 v120, v120, v225
	v_mul_f32_e32 v122, v122, v226
	v_cndmask_b32_e32 v137, v219, v137, vcc
	v_cndmask_b32_e32 v145, v220, v145, vcc
	v_cndmask_b32_e32 v141, v140, v141, vcc
	v_cndmask_b32_e32 v147, v221, v147, vcc
	v_fma_f32 v136, v219, v124, v112
	v_fma_f32 v183, v220, v128, v118
	v_fma_f32 v140, v140, v130, v120
	v_fma_f32 v132, v221, v131, v122
	v_cvt_pk_bf16_f32 v160, v155, v156
	v_cvt_pk_bf16_f32 v161, v158, v181
	v_cvt_pk_bf16_f32 v162, v112, v118
	v_cvt_pk_bf16_f32 v163, v120, v122
	global_store_dwordx4 v[114:115], v[160:163], off offset:-1024 sc1
	s_nop 1
	v_fmac_f32_dpp v136, v136, v137 row_shr:1 row_mask:0xf bank_mask:0xf
	v_fmac_f32_dpp v183, v183, v145 row_shr:1 row_mask:0xf bank_mask:0xf
	v_fmac_f32_dpp v140, v140, v141 row_shr:1 row_mask:0xf bank_mask:0xf
	v_fmac_f32_dpp v132, v132, v147 row_shr:1 row_mask:0xf bank_mask:0xf
	v_mul_f32_dpp v137, v137, v137 row_shr:1 row_mask:0xf bank_mask:0xf
	v_mul_f32_dpp v145, v145, v145 row_shr:1 row_mask:0xf bank_mask:0xf
	v_mul_f32_dpp v141, v141, v141 row_shr:1 row_mask:0xf bank_mask:0xf
	v_mul_f32_dpp v147, v147, v147 row_shr:1 row_mask:0xf bank_mask:0xf
	v_fmac_f32_dpp v136, v136, v137 row_shr:2 row_mask:0xf bank_mask:0xf
	v_fmac_f32_dpp v183, v183, v145 row_shr:2 row_mask:0xf bank_mask:0xf
	v_fmac_f32_dpp v140, v140, v141 row_shr:2 row_mask:0xf bank_mask:0xf
	v_fmac_f32_dpp v132, v132, v147 row_shr:2 row_mask:0xf bank_mask:0xf
	v_mul_f32_dpp v137, v137, v137 row_shr:2 row_mask:0xf bank_mask:0xf
	v_mul_f32_dpp v145, v145, v145 row_shr:2 row_mask:0xf bank_mask:0xf
	v_mul_f32_dpp v141, v141, v141 row_shr:2 row_mask:0xf bank_mask:0xf
	v_mul_f32_dpp v147, v147, v147 row_shr:2 row_mask:0xf bank_mask:0xf
	v_fmac_f32_dpp v136, v136, v137 row_shr:4 row_mask:0xf bank_mask:0xf
	v_fmac_f32_dpp v183, v183, v145 row_shr:4 row_mask:0xf bank_mask:0xf
	v_fmac_f32_dpp v140, v140, v141 row_shr:4 row_mask:0xf bank_mask:0xf
	v_fmac_f32_dpp v132, v132, v147 row_shr:4 row_mask:0xf bank_mask:0xf
	v_mul_f32_dpp v137, v137, v137 row_shr:4 row_mask:0xf bank_mask:0xf
	v_mul_f32_dpp v145, v145, v145 row_shr:4 row_mask:0xf bank_mask:0xf
	v_mul_f32_dpp v141, v141, v141 row_shr:4 row_mask:0xf bank_mask:0xf
	v_mul_f32_dpp v147, v147, v147 row_shr:4 row_mask:0xf bank_mask:0xf
	v_fmac_f32_dpp v136, v136, v137 row_shr:8 row_mask:0xf bank_mask:0xf
	v_fmac_f32_dpp v183, v183, v145 row_shr:8 row_mask:0xf bank_mask:0xf
	v_fmac_f32_dpp v140, v140, v141 row_shr:8 row_mask:0xf bank_mask:0xf
	v_fmac_f32_dpp v132, v132, v147 row_shr:8 row_mask:0xf bank_mask:0xf
	v_mul_f32_dpp v137, v137, v137 row_shr:8 row_mask:0xf bank_mask:0xf
	v_mul_f32_dpp v145, v145, v145 row_shr:8 row_mask:0xf bank_mask:0xf
	v_mul_f32_dpp v141, v141, v141 row_shr:8 row_mask:0xf bank_mask:0xf
	v_mul_f32_dpp v147, v147, v147 row_shr:8 row_mask:0xf bank_mask:0xf

; __device__ __forceinline__ float fexp(float x) { return __builtin_amdgcn_exp2f(x * 1.4426950408889634f); }
; #define LAS __attribute__((address_space(3)))
; __device__ __forceinline__ unsigned pk2(float lo, float hi) { return pg8::cvt_pk_bf16(lo, hi); }
; __device__ __forceinline__ float fexp(float x) { return __builtin_amdgcn_exp2f(x * 1.4426950408889634f); }
; __device__ __forceinline__ float fsigmoid(float x) { return __builtin_amdgcn_rcpf(1.0f + fexp(-x)); }
; template <int PASS>
; __device__ __forceinline__ void lru_unit(const LruP& P, const LruInv& V, int b, int c, LAS unsigned char* wl, LAS float* red, int wave, int lane, int pairpos) {
;     ...
;             const f32x4 br = V.br[n], bi = V.bi[n], sl = V.sl[n];
;             const v2u xw = *(const LAS v2u*)(xc + (16 * m + fr) * 72 + 16 * n + 4 * fq);
;             const float xv[4] = {bflo(xw.x), bfhi(xw.x), bflo(xw.y), bfhi(xw.y)};
;             const v2u gw = gcur[n];
;             const float gv[4] = {bflo(gw.x), bfhi(gw.x), bflo(gw.y), bfhi(gw.y)};
;             float av[4], bv[4], laraw[4], braw[4];
; #pragma unroll
;             for (int j = 0; j < 4; ++j) {
;                 const float r = fsigmoid(R[j] + br[j]), ig = fsigmoid(I[j] + bi[j]);
;                 const float la = r * sl[j];
;                 const float a = fexp(la);
;                 const float bt = __builtin_amdgcn_sqrtf(fmaxf(1.0f - a * a, 0.f)) * (ig * xv[j]);
;                 laraw[j] = la; braw[j] = bt;
;                 const float cin = row_ror1(hin[n][j]);
;                 bv[j] = fmaf(a, lane0 ? cin : 0.f, bt);
;                 if (PASS == 1) { const float ain = row_ror1(arun[n][j]); av[j] = lane0 ? a * ain : a; } else av[j] = a;
;             }
;             if (PASS == 1) { v4u w; w.x = pk2(laraw[0], laraw[1]); w.y = pk2(laraw[2], laraw[3]); w.z = pk2(braw[0], braw[1]); w.w = pk2(braw[2], braw[3]);
;                 ((v4u*)P.AB)[((((size_t)(b * NCH + c) * 8 + wave) * 4 + m) * 4 + n) * 64 + lane] = w; }
;             scan4(av, bv);
; #pragma unroll
;             for (int j = 0; j < 4; ++j) {
;                 hin[n][j] = bv[j];
;                 if (PASS == 1) arun[n][j] = av[j];
	ds_read_b64 v[122:123], v116 offset:64
	v_cndmask_b32_e32 v143, 0, v154, vcc
	v_cndmask_b32_e32 v154, 0, v228, vcc
	v_add_f32_e32 v188, 1.0, v188
	v_add_f32_e32 v190, 1.0, v190
	v_add_f32_e32 v192, 1.0, v192
	v_add_f32_e32 v202, 1.0, v202
	v_fma_f32 v228, -v222, v222, 1.0
	v_fma_f32 v229, -v212, v212, 1.0
	v_fma_f32 v230, -v213, v213, 1.0
	v_fma_f32 v231, -v214, v214, 1.0
	v_rcp_f32_e32 v188, v188
	v_rcp_f32_e32 v190, v190
	v_rcp_f32_e32 v192, v192
	v_rcp_f32_e32 v202, v202
	v_max_f32_e32 v227, 0, v228
	v_max_f32_e32 v228, 0, v229
	v_max_f32_e32 v229, 0, v230
	v_max_f32_e32 v230, 0, v231
	v_sqrt_f32_e32 v227, v227
	v_sqrt_f32_e32 v228, v228
	v_sqrt_f32_e32 v229, v229
	v_sqrt_f32_e32 v230, v230
	v_mul_f32_e32 v215, 0x3fb8aa3b, v193
	v_mul_f32_e32 v216, 0x3fb8aa3b, v203
	v_mul_f32_e32 v217, 0x3fb8aa3b, v210
	v_mul_f32_e32 v218, 0x3fb8aa3b, v211
	s_waitcnt lgkmcnt(0)
	v_lshlrev_b32_e32 v112, 16, v122
	v_and_b32_e32 v118, 0xffff0000, v122
	v_lshlrev_b32_e32 v120, 16, v123
	v_and_b32_e32 v122, 0xffff0000, v123
	v_exp_f32_e32 v215, v215
	v_exp_f32_e32 v216, v216
	v_exp_f32_e32 v217, v217
	v_exp_f32_e32 v218, v218
	v_mul_f32_e32 v112, v188, v112
	v_mul_f32_e32 v118, v190, v118
	v_mul_f32_e32 v120, v192, v120
	v_mul_f32_e32 v122, v202, v122
	v_mul_f32_dpp v125, v125, v222 row_ror:1 row_mask:0xf bank_mask:0xf bound_ctrl:1
	v_mul_f32_dpp v133, v133, v212 row_ror:1 row_mask:0xf bank_mask:0xf bound_ctrl:1
	v_mul_f32_dpp v129, v129, v213 row_ror:1 row_mask:0xf bank_mask:0xf bound_ctrl:1
	v_mul_f32_dpp v135, v135, v214 row_ror:1 row_mask:0xf bank_mask:0xf bound_ctrl:1
	v_mul_f32_e32 v112, v112, v227
	v_mul_f32_e32 v123, v118, v228
	v_mul_f32_e32 v120, v120, v229
	v_mul_f32_e32 v122, v122, v230
	v_cndmask_b32_e32 v125, v222, v125, vcc
	v_cndmask_b32_e32 v133, v212, v133, vcc
	v_cndmask_b32_e32 v129, v213, v129, vcc
	v_cndmask_b32_e32 v135, v214, v135, vcc
	v_fma_f32 v124, v222, v138, v112
	v_fma_f32 v182, v212, v139, v123
	v_fma_f32 v128, v213, v142, v120
	v_fma_f32 v118, v214, v143, v122
	v_cvt_pk_bf16_f32 v160, v185, v187
	v_cvt_pk_bf16_f32 v161, v189, v191
	v_cvt_pk_bf16_f32 v162, v112, v123
	v_cvt_pk_bf16_f32 v163, v120, v122
	global_store_dwordx4 v[114:115], v[160:163], off sc1
	s_nop 1
	v_fmac_f32_dpp v124, v124, v125 row_shr:1 row_mask:0xf bank_mask:0xf
	v_fmac_f32_dpp v182, v182, v133 row_shr:1 row_mask:0xf bank_mask:0xf
	v_fmac_f32_dpp v128, v128, v129 row_shr:1 row_mask:0xf bank_mask:0xf
	v_fmac_f32_dpp v118, v118, v135 row_shr:1 row_mask:0xf bank_mask:0xf
	v_mul_f32_dpp v125, v125, v125 row_shr:1 row_mask:0xf bank_mask:0xf
	v_mul_f32_dpp v133, v133, v133 row_shr:1 row_mask:0xf bank_mask:0xf
	v_mul_f32_dpp v129, v129, v129 row_shr:1 row_mask:0xf bank_mask:0xf
	v_mul_f32_dpp v135, v135, v135 row_shr:1 row_mask:0xf bank_mask:0xf
	v_fmac_f32_dpp v124, v124, v125 row_shr:2 row_mask:0xf bank_mask:0xf
	v_fmac_f32_dpp v182, v182, v133 row_shr:2 row_mask:0xf bank_mask:0xf
	v_fmac_f32_dpp v128, v128, v129 row_shr:2 row_mask:0xf bank_mask:0xf
	v_fmac_f32_dpp v118, v118, v135 row_shr:2 row_mask:0xf bank_mask:0xf
	v_mul_f32_dpp v125, v125, v125 row_shr:2 row_mask:0xf bank_mask:0xf
	v_mul_f32_dpp v133, v133, v133 row_shr:2 row_mask:0xf bank_mask:0xf
	v_mul_f32_dpp v129, v129, v129 row_shr:2 row_mask:0xf bank_mask:0xf
	v_mul_f32_dpp v135, v135, v135 row_shr:2 row_mask:0xf bank_mask:0xf
	v_fmac_f32_dpp v124, v124, v125 row_shr:4 row_mask:0xf bank_mask:0xf
	v_fmac_f32_dpp v182, v182, v133 row_shr:4 row_mask:0xf bank_mask:0xf
	v_fmac_f32_dpp v128, v128, v129 row_shr:4 row_mask:0xf bank_mask:0xf
	v_fmac_f32_dpp v118, v118, v135 row_shr:4 row_mask:0xf bank_mask:0xf
	v_mul_f32_dpp v125, v125, v125 row_shr:4 row_mask:0xf bank_mask:0xf
	v_mul_f32_dpp v133, v133, v133 row_shr:4 row_mask:0xf bank_mask:0xf
	v_mul_f32_dpp v129, v129, v129 row_shr:4 row_mask:0xf bank_mask:0xf
	v_mul_f32_dpp v135, v135, v135 row_shr:4 row_mask:0xf bank_mask:0xf
	v_fmac_f32_dpp v124, v124, v125 row_shr:8 row_mask:0xf bank_mask:0xf
	v_fmac_f32_dpp v182, v182, v133 row_shr:8 row_mask:0xf bank_mask:0xf
	v_fmac_f32_dpp v128, v128, v129 row_shr:8 row_mask:0xf bank_mask:0xf
	v_fmac_f32_dpp v118, v118, v135 row_shr:8 row_mask:0xf bank_mask:0xf
	v_mul_f32_dpp v125, v125, v125 row_shr:8 row_mask:0xf bank_mask:0xf
	v_mul_f32_dpp v133, v133, v133 row_shr:8 row_mask:0xf bank_mask:0xf
	v_mul_f32_dpp v129, v129, v129 row_shr:8 row_mask:0xf bank_mask:0xf
	v_mul_f32_dpp v135, v135, v135 row_shr:8 row_mask:0xf bank_mask:0xf

; __device__ __forceinline__ float fexp(float x) { return __builtin_amdgcn_exp2f(x * 1.4426950408889634f); }
; #define LAS __attribute__((address_space(3)))
; __device__ __forceinline__ unsigned pk2(float lo, float hi) { return pg8::cvt_pk_bf16(lo, hi); }
; __device__ __forceinline__ float fexp(float x) { return __builtin_amdgcn_exp2f(x * 1.4426950408889634f); }
; __device__ __forceinline__ float fsigmoid(float x) { return __builtin_amdgcn_rcpf(1.0f + fexp(-x)); }
; template <int PASS>
; __device__ __forceinline__ void lru_unit(const LruP& P, const LruInv& V, int b, int c, LAS unsigned char* wl, LAS float* red, int wave, int lane, int pairpos) {
;     ...
;             const f32x4 br = V.br[n], bi = V.bi[n], sl = V.sl[n];
;             const v2u xw = *(const LAS v2u*)(xc + (16 * m + fr) * 72 + 16 * n + 4 * fq);
;             const float xv[4] = {bflo(xw.x), bfhi(xw.x), bflo(xw.y), bfhi(xw.y)};
;             const v2u gw = gcur[n];
;             const float gv[4] = {bflo(gw.x), bfhi(gw.x), bflo(gw.y), bfhi(gw.y)};
;             float av[4], bv[4], laraw[4], braw[4];
; #pragma unroll
;             for (int j = 0; j < 4; ++j) {
;                 const float r = fsigmoid(R[j] + br[j]), ig = fsigmoid(I[j] + bi[j]);
;                 const float la = r * sl[j];
;                 const float a = fexp(la);
;                 const float bt = __builtin_amdgcn_sqrtf(fmaxf(1.0f - a * a, 0.f)) * (ig * xv[j]);
;                 laraw[j] = la; braw[j] = bt;
;                 const float cin = row_ror1(hin[n][j]);
;                 bv[j] = fmaf(a, lane0 ? cin : 0.f, bt);
;                 if (PASS == 1) { const float ain = row_ror1(arun[n][j]); av[j] = lane0 ? a * ain : a; } else av[j] = a;
;             }
;             if (PASS == 1) { v4u w; w.x = pk2(laraw[0], laraw[1]); w.y = pk2(laraw[2], laraw[3]); w.z = pk2(braw[0], braw[1]); w.w = pk2(braw[2], braw[3]);
;                 ((v4u*)P.AB)[((((size_t)(b * NCH + c) * 8 + wave) * 4 + m) * 4 + n) * 64 + lane] = w; }
;             scan4(av, bv);
; #pragma unroll
;             for (int j = 0; j < 4; ++j) {
;                 hin[n][j] = bv[j];
;                 if (PASS == 1) arun[n][j] = av[j];
	ds_read_b64 v[122:123], v116 offset:96
	v_fma_f32 v232, -v215, v215, 1.0
	v_fma_f32 v233, -v216, v216, 1.0
	v_fma_f32 v234, -v217, v217, 1.0
	v_fma_f32 v235, -v218, v218, 1.0
	v_max_f32_e32 v231, 0, v232
	v_max_f32_e32 v232, 0, v233
	v_max_f32_e32 v233, 0, v234
	v_max_f32_e32 v234, 0, v235
	v_sqrt_f32_e32 v231, v231
	v_sqrt_f32_e32 v232, v232
	v_sqrt_f32_e32 v233, v233
	v_sqrt_f32_e32 v234, v234
	s_waitcnt lgkmcnt(0)
	v_lshlrev_b32_e32 v112, 16, v122
	v_and_b32_e32 v116, 0xffff0000, v122
	v_lshlrev_b32_e32 v120, 16, v123
	v_and_b32_e32 v122, 0xffff0000, v123
	v_mul_f32_e32 v112, v209, v112
	v_mul_f32_e32 v116, v204, v116
	v_mul_f32_e32 v120, v205, v120
	v_mul_f32_e32 v122, v208, v122
	s_addk_i32 s6, 0x900
	v_mul_f32_dpp v113, v113, v215 row_ror:1 row_mask:0xf bank_mask:0xf bound_ctrl:1
	v_mul_f32_dpp v117, v117, v216 row_ror:1 row_mask:0xf bank_mask:0xf bound_ctrl:1
	v_mul_f32_dpp v121, v121, v217 row_ror:1 row_mask:0xf bank_mask:0xf bound_ctrl:1
	v_mul_f32_dpp v119, v119, v218 row_ror:1 row_mask:0xf bank_mask:0xf bound_ctrl:1
	v_mul_f32_e32 v123, v112, v231
	v_mul_f32_e32 v116, v116, v232
	v_mul_f32_e32 v126, v120, v233
	v_mul_f32_e32 v122, v122, v234
	s_cmpk_lg_i32 s6, 0x2400
	v_cndmask_b32_e32 v113, v215, v113, vcc
	v_cndmask_b32_e32 v117, v216, v117, vcc
	v_cndmask_b32_e32 v121, v217, v121, vcc
	v_cndmask_b32_e32 v119, v218, v119, vcc
	v_cvt_pk_bf16_f32 v160, v193, v203
	v_cvt_pk_bf16_f32 v161, v210, v211
	v_fma_f32 v112, v215, v146, v123
	v_fma_f32 v181, v216, v150, v116
	v_fma_f32 v120, v217, v151, v126
	v_fma_f32 v180, v218, v154, v122
	v_cvt_pk_bf16_f32 v162, v123, v116
	v_cvt_pk_bf16_f32 v163, v126, v122
	global_store_dwordx4 v[114:115], v[160:163], off offset:1024 sc1
	v_lshl_add_u64 v[114:115], v[114:115], 0, s[12:13]
	s_nop 1
	v_fmac_f32_dpp v112, v112, v113 row_shr:1 row_mask:0xf bank_mask:0xf
	v_fmac_f32_dpp v181, v181, v117 row_shr:1 row_mask:0xf bank_mask:0xf
	v_fmac_f32_dpp v120, v120, v121 row_shr:1 row_mask:0xf bank_mask:0xf
	v_fmac_f32_dpp v180, v180, v119 row_shr:1 row_mask:0xf bank_mask:0xf
	v_mul_f32_dpp v113, v113, v113 row_shr:1 row_mask:0xf bank_mask:0xf
	v_mul_f32_dpp v117, v117, v117 row_shr:1 row_mask:0xf bank_mask:0xf
	v_mul_f32_dpp v121, v121, v121 row_shr:1 row_mask:0xf bank_mask:0xf
	v_mul_f32_dpp v119, v119, v119 row_shr:1 row_mask:0xf bank_mask:0xf
	v_fmac_f32_dpp v112, v112, v113 row_shr:2 row_mask:0xf bank_mask:0xf
	v_fmac_f32_dpp v181, v181, v117 row_shr:2 row_mask:0xf bank_mask:0xf
	v_fmac_f32_dpp v120, v120, v121 row_shr:2 row_mask:0xf bank_mask:0xf
	v_fmac_f32_dpp v180, v180, v119 row_shr:2 row_mask:0xf bank_mask:0xf
	v_mul_f32_dpp v113, v113, v113 row_shr:2 row_mask:0xf bank_mask:0xf
	v_mul_f32_dpp v117, v117, v117 row_shr:2 row_mask:0xf bank_mask:0xf
	v_mul_f32_dpp v121, v121, v121 row_shr:2 row_mask:0xf bank_mask:0xf
	v_mul_f32_dpp v119, v119, v119 row_shr:2 row_mask:0xf bank_mask:0xf
	v_fmac_f32_dpp v112, v112, v113 row_shr:4 row_mask:0xf bank_mask:0xf
	v_fmac_f32_dpp v181, v181, v117 row_shr:4 row_mask:0xf bank_mask:0xf
	v_fmac_f32_dpp v120, v120, v121 row_shr:4 row_mask:0xf bank_mask:0xf
	v_fmac_f32_dpp v180, v180, v119 row_shr:4 row_mask:0xf bank_mask:0xf
	v_mul_f32_dpp v113, v113, v113 row_shr:4 row_mask:0xf bank_mask:0xf
	v_mul_f32_dpp v117, v117, v117 row_shr:4 row_mask:0xf bank_mask:0xf
	v_mul_f32_dpp v121, v121, v121 row_shr:4 row_mask:0xf bank_mask:0xf
	v_mul_f32_dpp v119, v119, v119 row_shr:4 row_mask:0xf bank_mask:0xf
	v_fmac_f32_dpp v112, v112, v113 row_shr:8 row_mask:0xf bank_mask:0xf
	v_fmac_f32_dpp v181, v181, v117 row_shr:8 row_mask:0xf bank_mask:0xf
	v_fmac_f32_dpp v120, v120, v121 row_shr:8 row_mask:0xf bank_mask:0xf
	v_fmac_f32_dpp v180, v180, v119 row_shr:8 row_mask:0xf bank_mask:0xf
	v_mul_f32_dpp v113, v113, v113 row_shr:8 row_mask:0xf bank_mask:0xf
	v_mul_f32_dpp v117, v117, v117 row_shr:8 row_mask:0xf bank_mask:0xf
	v_mul_f32_dpp v121, v121, v121 row_shr:8 row_mask:0xf bank_mask:0xf
	v_mul_f32_dpp v119, v119, v119 row_shr:8 row_mask:0xf bank_mask:0xf

; template <int PASS>
; __device__ __forceinline__ void lru_unit(const LruP& P, const LruInv& V, int b, int c, LAS unsigned char* wl, LAS float* red, int wave, int lane, int pairpos) {
;     ...
;     if (PASS == 1) {
;         if (fr == 15) {
;             if (pairpos == 0) {
; #pragma unroll
;                 for (int n = 0; n < 4; ++n)
; #pragma unroll
;                     for (int j = 0; j < 4; ++j) { stash[(n * 4 + j) * 2] = hin[n][j]; stash[(n * 4 + j) * 2 + 1] = arun[n][j]; } }
; #pragma unroll
;             for (int n = 0; n < 4; ++n) { const size_t o = ((size_t)(b * NCH + c)) * 512 + chl + 16 * n;
;                 *(f32x4*)(P.AgA + o) = (f32x4){arun[n][0], arun[n][1], arun[n][2], arun[n][3]};
;                 *(f32x4*)(P.AgH + o) = (f32x4){hin[n][0], hin[n][1], hin[n][2], hin[n][3]}; }
	s_cbranch_scc1 .LBB0_334
	s_and_saveexec_b64 s[6:7], s[2:3]
	s_cbranch_execz .LBB0_337
	v_mov_b32_e32 v114, v181
	v_mov_b32_e32 v115, v117
	s_lshl_b64 s[0:1], s[0:1], 9
	ds_write_b128 v201, v[112:115] offset:9312
	v_mov_b32_e32 v122, v180
	v_mov_b32_e32 v123, v119
	v_lshl_add_u64 v[114:115], s[0:1], 0, v[164:165]
	ds_write_b128 v201, v[120:123] offset:9328
	v_lshlrev_b64 v[122:123], 2, v[114:115]
	v_mov_b32_e32 v150, v144
	v_mov_b32_e32 v151, v157
	v_lshl_add_u64 v[114:115], s[46:47], 0, v[122:123]
	v_mov_b32_e32 v156, v149
	v_mov_b32_e32 v158, v153
	ds_write_b128 v201, v[148:151] offset:9216
	global_store_dwordx4 v[114:115], v[156:159], off sc1
	v_mov_b32_e32 v149, v144
	v_mov_b32_e32 v150, v152
	v_mov_b32_e32 v151, v134
	v_lshl_add_u64 v[114:115], s[50:51], 0, v[122:123]
	v_mov_b32_e32 v138, v183
	v_mov_b32_e32 v139, v145
	v_mov_b32_e32 v126, v182
	v_mov_b32_e32 v127, v133
	global_store_dwordx4 v[114:115], v[148:151], off sc1
	v_or_b32_e32 v114, 64, v122
	v_mov_b32_e32 v115, v123
	ds_write_b128 v201, v[136:139] offset:9248
	ds_write_b128 v201, v[124:127] offset:9280
	v_lshl_add_u64 v[126:127], s[46:47], 0, v[114:115]
	v_mov_b32_e32 v144, v137
	v_mov_b32_e32 v137, v183
	v_mov_b32_e32 v138, v140
	v_mov_b32_e32 v139, v132
	v_lshl_add_u64 v[114:115], s[50:51], 0, v[114:115]
	v_mov_b32_e32 v146, v141
	global_store_dwordx4 v[114:115], v[136:139], off sc1
	v_or_b32_e32 v114, 0x80, v122
	v_mov_b32_e32 v115, v123
	v_mov_b32_e32 v154, v134
	v_mov_b32_e32 v142, v132
	global_store_dwordx4 v[126:127], v[144:147], off sc1
	v_lshl_add_u64 v[126:127], s[46:47], 0, v[114:115]
	v_mov_b32_e32 v132, v125
	v_mov_b32_e32 v134, v129
	global_store_dwordx4 v[126:127], v[132:135], off sc1
	v_mov_b32_e32 v125, v182
	v_mov_b32_e32 v126, v128
	v_mov_b32_e32 v127, v118
	v_lshl_add_u64 v[114:115], s[50:51], 0, v[114:115]
	v_or_b32_e32 v122, 0xc0, v122
	v_mov_b32_e32 v130, v118
	global_store_dwordx4 v[114:115], v[124:127], off sc1
	v_lshl_add_u64 v[114:115], s[46:47], 0, v[122:123]
	v_mov_b32_e32 v116, v113
	v_mov_b32_e32 v118, v121
	v_mov_b32_e32 v155, v159
	v_mov_b32_e32 v143, v147
	v_mov_b32_e32 v131, v135
	global_store_dwordx4 v[114:115], v[116:119], off sc1
	v_mov_b32_e32 v113, v181
	v_mov_b32_e32 v114, v120
	v_mov_b32_e32 v115, v180
	v_lshl_add_u64 v[116:117], s[50:51], 0, v[122:123]
	ds_write_b128 v201, v[152:155] offset:9232
	ds_write_b128 v201, v[140:143] offset:9264
	ds_write_b128 v201, v[128:131] offset:9296
	global_store_dwordx4 v[116:117], v[112:115], off sc1

; __device__ __forceinline__ float fexp(float x) { return __builtin_amdgcn_exp2f(x * 1.4426950408889634f); }
; #define LAS __attribute__((address_space(3)))
; __device__ __forceinline__ float fexp(float x) { return __builtin_amdgcn_exp2f(x * 1.4426950408889634f); }
; __device__ __forceinline__ float fsigmoid(float x) { return __builtin_amdgcn_rcpf(1.0f + fexp(-x)); }
; template <int PASS>
; __device__ __forceinline__ void lru_unit(const LruP& P, const LruInv& V, int b, int c, LAS unsigned char* wl, LAS float* red, int wave, int lane, int pairpos) {
;     ...
;         for (int ks = 0; ks < 2; ++ks) Xf[ks] = *(const LAS bf16x8*)(xc + (16 * m + fr) * 72 + 32 * ks + 8 * fq);
; #pragma unroll
;         for (int n = 0; n < 4; ++n) {
;             f32x4 R = (f32x4){0.f, 0.f, 0.f, 0.f}, I = (f32x4){0.f, 0.f, 0.f, 0.f};
; #pragma unroll
;             for (int ks = 0; ks < 2; ++ks) {
;                 R = __builtin_amdgcn_mfma_f32_16x16x32_bf16(V.Wr[n][ks], Xf[ks], R, 0, 0, 0);
;                 I = __builtin_amdgcn_mfma_f32_16x16x32_bf16(V.Wi[n][ks], Xf[ks], I, 0, 0, 0); }
;             const f32x4 br = V.br[n], bi = V.bi[n], sl = V.sl[n];
;             const v2u xw = *(const LAS v2u*)(xc + (16 * m + fr) * 72 + 16 * n + 4 * fq);
;             const float xv[4] = {bflo(xw.x), bfhi(xw.x), bflo(xw.y), bfhi(xw.y)};
;             const v2u gw = gcur[n];
;             const float gv[4] = {bflo(gw.x), bfhi(gw.x), bflo(gw.y), bfhi(gw.y)};
;             float av[4], bv[4], laraw[4], braw[4];
; #pragma unroll
;             for (int j = 0; j < 4; ++j) {
;                 const float r = fsigmoid(R[j] + br[j]), ig = fsigmoid(I[j] + bi[j]);
;                 const float la = r * sl[j];
;                 const float a = fexp(la);
;                 const float bt = __builtin_amdgcn_sqrtf(fmaxf(1.0f - a * a, 0.f)) * (ig * xv[j]);
;                 laraw[j] = la; braw[j] = bt;
;                 const float cin = row_ror1(hin[n][j]);
;                 bv[j] = fmaf(a, lane0 ? cin : 0.f, bt);
;                 if (PASS == 1) { const float ain = row_ror1(arun[n][j]); av[j] = lane0 ? a * ain : a; } else av[j] = a;
.LBB0_338:
	v_add_u32_e32 v133, s0, v195
	ds_read_b128 v[158:161], v133
	ds_read_b128 v[152:155], v133 offset:64
	v_mov_b32_e32 v213, 0
	v_mov_b32_e32 v214, 0
	v_mov_b32_e32 v215, 0
	v_mov_b32_e32 v216, 0
	s_waitcnt lgkmcnt(1)
	v_mfma_f32_16x16x32_bf16 v[180:183], v[0:3], v[158:161], 0
	v_mov_b32_e32 v219, 0
	v_mov_b32_e32 v220, 0
	v_mov_b32_dpp v213, v136 row_ror:1 row_mask:0xf bank_mask:0xf
	v_mfma_f32_16x16x32_bf16 v[184:187], v[4:7], v[158:161], 0
	v_mov_b32_dpp v214, v138 row_ror:1 row_mask:0xf bank_mask:0xf
	v_mov_b32_dpp v215, v140 row_ror:1 row_mask:0xf bank_mask:0xf
	v_mov_b32_dpp v216, v142 row_ror:1 row_mask:0xf bank_mask:0xf
	v_mfma_f32_16x16x32_bf16 v[188:191], v[16:19], v[158:161], 0
	v_mov_b32_dpp v219, v132 row_ror:1 row_mask:0xf bank_mask:0xf
	v_mov_b32_dpp v220, v134 row_ror:1 row_mask:0xf bank_mask:0xf
	v_add_u32_e32 v121, s0, v196
	v_mfma_f32_16x16x32_bf16 v[202:205], v[20:23], v[158:161], 0
	ds_read_b64 v[162:163], v121
	v_mov_b32_e32 v123, 0
	v_mov_b32_e32 v192, 0
	v_mfma_f32_16x16x32_bf16 v[208:211], v[32:35], v[158:161], 0
	v_mov_b32_e32 v193, 0
	v_mov_b32_e32 v212, 0
	v_mov_b32_dpp v123, v120 row_ror:1 row_mask:0xf bank_mask:0xf
	v_mfma_f32_16x16x32_bf16 v[136:139], v[36:39], v[158:161], 0
	v_mov_b32_dpp v192, v122 row_ror:1 row_mask:0xf bank_mask:0xf
	v_mov_b32_dpp v193, v124 row_ror:1 row_mask:0xf bank_mask:0xf
	v_mov_b32_dpp v212, v126 row_ror:1 row_mask:0xf bank_mask:0xf
	v_mfma_f32_16x16x32_bf16 v[140:143], v[48:51], v[158:161], 0
	s_waitcnt lgkmcnt(0)
	v_lshlrev_b32_e32 v120, 16, v162
	v_and_b32_e32 v122, 0xffff0000, v162
	v_lshlrev_b32_e32 v124, 16, v163
	v_mfma_f32_16x16x32_bf16 v[132:135], v[52:55], v[158:161], 0
	v_and_b32_e32 v126, 0xffff0000, v163
	v_mov_b32_e32 v221, 0
	v_mov_b32_e32 v222, 0
	v_mfma_f32_16x16x32_bf16 v[158:161], v[8:11], v[152:155], v[180:183]
	v_mov_b32_dpp v221, v112 row_ror:1 row_mask:0xf bank_mask:0xf
	v_mov_b32_dpp v222, v114 row_ror:1 row_mask:0xf bank_mask:0xf
	v_cndmask_b32_e32 v112, 0, v123, vcc
	v_mfma_f32_16x16x32_bf16 v[180:183], v[12:15], v[152:155], v[184:187]
	v_cndmask_b32_e32 v123, 0, v213, vcc
	v_cndmask_b32_e32 v213, 0, v219, vcc
	v_mov_b32_e32 v223, 0
	v_mfma_f32_16x16x32_bf16 v[184:187], v[24:27], v[152:155], v[188:191]
	v_mov_b32_e32 v224, 0
	v_mov_b32_dpp v223, v116 row_ror:1 row_mask:0xf bank_mask:0xf
	v_cndmask_b32_e32 v114, 0, v192, vcc
	v_mfma_f32_16x16x32_bf16 v[188:191], v[28:31], v[152:155], v[202:205]
	v_mov_b32_dpp v224, v118 row_ror:1 row_mask:0xf bank_mask:0xf
	s_nop 2
	v_add_f32_e32 v162, v104, v184
	v_add_f32_e32 v184, v107, v187
	v_mfma_f32_16x16x32_bf16 v[202:205], v[40:43], v[152:155], v[208:211]
	v_mul_f32_e32 v162, 0xbfb8aa3b, v162
	v_add_f32_e32 v163, v96, v188
	v_exp_f32_e32 v162, v162
	v_mfma_f32_16x16x32_bf16 v[136:139], v[44:47], v[152:155], v[136:139]
	v_mul_f32_e32 v184, 0xbfb8aa3b, v184
	s_nop 2
	v_add_f32_e32 v187, v85, v203
	v_add_f32_e32 v188, v86, v204
	v_mfma_f32_16x16x32_bf16 v[140:143], v[56:59], v[152:155], v[140:143]
	v_mul_f32_e32 v187, 0xbfb8aa3b, v187
	v_add_f32_e32 v136, v76, v136
	v_add_f32_e32 v138, v78, v138
	v_mfma_f32_16x16x32_bf16 v[132:135], v[60:63], v[152:155], v[132:135]
	v_add_f32_e32 v152, v108, v158
	v_add_f32_e32 v153, v100, v180
	v_add_f32_e32 v154, v109, v159
	v_add_f32_e32 v158, v110, v160
	v_add_f32_e32 v160, v111, v161
	v_add_f32_e32 v155, v101, v181
	v_add_f32_e32 v159, v102, v182
	v_add_f32_e32 v161, v103, v183
	v_add_f32_e32 v180, v105, v185
	v_add_f32_e32 v181, v97, v189
	v_add_f32_e32 v182, v106, v186
	v_add_f32_e32 v189, v87, v205
	v_add_f32_e32 v140, v80, v140
	v_add_f32_e32 v134, v74, v134
	v_add_f32_e32 v143, v83, v143
	v_mul_f32_e32 v152, 0xbfb8aa3b, v152
	v_mul_f32_e32 v153, 0xbfb8aa3b, v153
	v_mul_f32_e32 v154, 0xbfb8aa3b, v154
	v_mul_f32_e32 v158, 0xbfb8aa3b, v158
	v_mul_f32_e32 v160, 0xbfb8aa3b, v160
	v_mul_f32_e32 v155, 0xbfb8aa3b, v155
	v_mul_f32_e32 v161, 0xbfb8aa3b, v161
	v_mul_f32_e32 v180, 0xbfb8aa3b, v180
	v_mul_f32_e32 v182, 0xbfb8aa3b, v182
	v_mul_f32_e32 v136, 0xbfb8aa3b, v136
	v_mul_f32_e32 v188, 0xbfb8aa3b, v188
	v_mul_f32_e32 v138, 0xbfb8aa3b, v138
	v_mul_f32_e32 v189, 0xbfb8aa3b, v189
	v_mul_f32_e32 v140, 0xbfb8aa3b, v140
	v_mul_f32_e32 v134, 0xbfb8aa3b, v134
	v_mul_f32_e32 v143, 0xbfb8aa3b, v143
	v_exp_f32_e32 v152, v152
	v_exp_f32_e32 v153, v153
	v_exp_f32_e32 v154, v154
	v_exp_f32_e32 v158, v158
	v_exp_f32_e32 v160, v160
	v_exp_f32_e32 v155, v155
	v_exp_f32_e32 v161, v161
	v_exp_f32_e32 v180, v180
	v_exp_f32_e32 v182, v182
	v_exp_f32_e32 v136, v136
	v_exp_f32_e32 v187, v187
	v_exp_f32_e32 v188, v188
	v_exp_f32_e32 v138, v138
	v_exp_f32_e32 v189, v189
	v_exp_f32_e32 v140, v140
	v_exp_f32_e32 v134, v134
	v_exp_f32_e32 v143, v143
	v_add_f32_e32 v132, v72, v132
	v_add_f32_e32 v141, v81, v141
	v_add_f32_e32 v133, v73, v133
	v_add_f32_e32 v142, v82, v142
	v_add_f32_e32 v135, v75, v135
	v_mul_f32_e32 v132, 0xbfb8aa3b, v132
	v_mul_f32_e32 v141, 0xbfb8aa3b, v141
	v_mul_f32_e32 v133, 0xbfb8aa3b, v133
	v_mul_f32_e32 v142, 0xbfb8aa3b, v142
	v_mul_f32_e32 v135, 0xbfb8aa3b, v135
	v_mul_f32_e32 v159, 0xbfb8aa3b, v159
	v_exp_f32_e32 v132, v132
	v_exp_f32_e32 v141, v141
	v_exp_f32_e32 v133, v133
	v_exp_f32_e32 v142, v142
	v_exp_f32_e32 v135, v135
	v_add_f32_e32 v152, 1.0, v152
	v_add_f32_e32 v153, 1.0, v153
	v_add_f32_e32 v154, 1.0, v154
	v_add_f32_e32 v158, 1.0, v158
	v_add_f32_e32 v160, 1.0, v160
	v_exp_f32_e32 v159, v159
	v_exp_f32_e32 v184, v184
	v_add_f32_e32 v155, 1.0, v155
	v_add_f32_e32 v161, 1.0, v161
	v_add_f32_e32 v162, 1.0, v162
	v_add_f32_e32 v180, 1.0, v180
	v_add_f32_e32 v182, 1.0, v182
	v_add_f32_e32 v136, 1.0, v136
	v_add_f32_e32 v187, 1.0, v187
	v_add_f32_e32 v188, 1.0, v188
; __device__ __forceinline__ float fexp(float x) { return __builtin_amdgcn_exp2f(x * 1.4426950408889634f); }
; #define LAS __attribute__((address_space(3)))
; __device__ __forceinline__ unsigned pk2(float lo, float hi) { return pg8::cvt_pk_bf16(lo, hi); }
; __device__ __forceinline__ float fexp(float x) { return __builtin_amdgcn_exp2f(x * 1.4426950408889634f); }
; __device__ __forceinline__ float fsigmoid(float x) { return __builtin_amdgcn_rcpf(1.0f + fexp(-x)); }
; template <int PASS>
; __device__ __forceinline__ void lru_unit(const LruP& P, const LruInv& V, int b, int c, LAS unsigned char* wl, LAS float* red, int wave, int lane, int pairpos) {
;     ...
;             const f32x4 br = V.br[n], bi = V.bi[n], sl = V.sl[n];
;             const v2u xw = *(const LAS v2u*)(xc + (16 * m + fr) * 72 + 16 * n + 4 * fq);
;             const float xv[4] = {bflo(xw.x), bfhi(xw.x), bflo(xw.y), bfhi(xw.y)};
;             const v2u gw = gcur[n];
;             const float gv[4] = {bflo(gw.x), bfhi(gw.x), bflo(gw.y), bfhi(gw.y)};
;             float av[4], bv[4], laraw[4], braw[4];
; #pragma unroll
;             for (int j = 0; j < 4; ++j) {
;                 const float r = fsigmoid(R[j] + br[j]), ig = fsigmoid(I[j] + bi[j]);
;                 const float la = r * sl[j];
;                 const float a = fexp(la);
;                 const float bt = __builtin_amdgcn_sqrtf(fmaxf(1.0f - a * a, 0.f)) * (ig * xv[j]);
;                 laraw[j] = la; braw[j] = bt;
;                 const float cin = row_ror1(hin[n][j]);
;                 bv[j] = fmaf(a, lane0 ? cin : 0.f, bt);
;                 if (PASS == 1) { const float ain = row_ror1(arun[n][j]); av[j] = lane0 ? a * ain : a; } else av[j] = a;
;             }
;             if (PASS == 1) { v4u w; w.x = pk2(laraw[0], laraw[1]); w.y = pk2(laraw[2], laraw[3]); w.z = pk2(braw[0], braw[1]); w.w = pk2(braw[2], braw[3]);
;                 ((v4u*)P.AB)[((((size_t)(b * NCH + c) * 8 + wave) * 4 + m) * 4 + n) * 64 + lane] = w; }
;             scan4(av, bv);
; #pragma unroll
;             for (int j = 0; j < 4; ++j) {
;                 hin[n][j] = bv[j];
;                 if (PASS == 1) arun[n][j] = av[j];
	v_add_f32_e32 v138, 1.0, v138
	v_add_f32_e32 v189, 1.0, v189
	v_add_f32_e32 v140, 1.0, v140
	v_add_f32_e32 v134, 1.0, v134
	v_add_f32_e32 v143, 1.0, v143
	v_rcp_f32_e32 v152, v152
	v_rcp_f32_e32 v153, v153
	v_rcp_f32_e32 v154, v154
	v_rcp_f32_e32 v158, v158
	v_rcp_f32_e32 v160, v160
	v_add_f32_e32 v183, v98, v190
	v_add_f32_e32 v185, v99, v191
	v_rcp_f32_e32 v155, v155
	v_rcp_f32_e32 v161, v161
	v_rcp_f32_e32 v162, v162
	v_rcp_f32_e32 v180, v180
	v_rcp_f32_e32 v182, v182
	v_rcp_f32_e32 v190, v136
	v_rcp_f32_e32 v136, v187
	v_rcp_f32_e32 v187, v188
	v_rcp_f32_e32 v188, v138
	v_rcp_f32_e32 v138, v189
	v_rcp_f32_e32 v140, v140
	v_rcp_f32_e32 v191, v134
	v_rcp_f32_e32 v134, v143
	v_add_f32_e32 v186, v84, v202
	v_add_f32_e32 v132, 1.0, v132
	v_add_f32_e32 v141, 1.0, v141
	v_add_f32_e32 v133, 1.0, v133
	v_add_f32_e32 v142, 1.0, v142
	v_add_f32_e32 v135, 1.0, v135
	v_mul_f32_e32 v186, 0xbfb8aa3b, v186
	v_add_f32_e32 v159, 1.0, v159
	v_add_f32_e32 v184, 1.0, v184
	v_rcp_f32_e32 v189, v132
	v_rcp_f32_e32 v132, v141
	v_rcp_f32_e32 v141, v133
	v_rcp_f32_e32 v133, v142
	v_rcp_f32_e32 v143, v135
	v_mul_f32_e32 v135, v92, v152
	v_mul_f32_e32 v120, v153, v120
	v_mul_f32_e32 v142, v93, v154
	v_mul_f32_e32 v152, v94, v158
	v_mul_f32_e32 v153, v95, v160
	v_exp_f32_e32 v186, v186
	v_rcp_f32_e32 v159, v159
	v_rcp_f32_e32 v184, v184
	v_mul_f32_e32 v122, v155, v122
	v_mul_f32_e32 v126, v161, v126
	v_mul_f32_e32 v154, v88, v162
	v_mul_f32_e32 v155, v89, v180
	v_mul_f32_e32 v158, v90, v182
	v_mul_f32_e32 v161, v69, v136
	v_mul_f32_e32 v162, v70, v187
	v_mul_f32_e32 v180, v71, v138
	v_mul_f32_e32 v182, v64, v140
	v_mul_f32_e32 v187, v67, v134
	v_mul_f32_e32 v134, 0x3fb8aa3b, v135
	v_mul_f32_e32 v136, 0x3fb8aa3b, v142
	v_mul_f32_e32 v138, 0x3fb8aa3b, v152
	v_mul_f32_e32 v140, 0x3fb8aa3b, v153
	v_exp_f32_e32 v134, v134
	v_exp_f32_e32 v136, v136
	v_exp_f32_e32 v138, v138
	v_exp_f32_e32 v140, v140
	v_add_f32_e32 v186, 1.0, v186
	v_mul_f32_e32 v124, v159, v124
	v_mul_f32_e32 v159, v91, v184
	v_mul_f32_e32 v184, v65, v132
	v_cvt_pk_bf16_f32 v132, v135, v142
	v_mul_f32_e32 v135, 0x3fb8aa3b, v154
	v_cndmask_b32_e32 v208, 0, v220, vcc
	v_cndmask_b32_e32 v209, 0, v221, vcc
	v_cndmask_b32_e32 v210, 0, v222, vcc
	v_rcp_f32_e32 v186, v186
	v_exp_f32_e32 v219, v135
	v_fma_f32 v135, -v134, v134, 1.0
	v_fma_f32 v220, -v136, v136, 1.0
	v_fma_f32 v221, -v138, v138, 1.0
	v_fma_f32 v222, -v140, v140, 1.0
	v_max_f32_e32 v135, 0, v135
	v_max_f32_e32 v220, 0, v220
	v_max_f32_e32 v221, 0, v221
	v_max_f32_e32 v222, 0, v222
	v_sqrt_f32_e32 v135, v135
	v_sqrt_f32_e32 v220, v220
	v_sqrt_f32_e32 v221, v221
	v_sqrt_f32_e32 v222, v222
	v_mul_f32_e32 v163, 0xbfb8aa3b, v163
	v_mul_f32_e32 v181, 0xbfb8aa3b, v181
	v_mul_f32_e32 v183, 0xbfb8aa3b, v183
	v_mul_f32_e32 v185, 0xbfb8aa3b, v185
	v_mul_f32_e32 v160, v68, v186
	v_mul_f32_e32 v186, v66, v133
	v_cvt_pk_bf16_f32 v133, v152, v153
	v_mul_f32_e32 v142, 0x3fb8aa3b, v155
	v_mul_f32_e32 v152, 0x3fb8aa3b, v158
	v_mul_f32_e32 v153, 0x3fb8aa3b, v159
	v_exp_f32_e32 v163, v163
	v_exp_f32_e32 v181, v181
	v_exp_f32_e32 v183, v183
	v_exp_f32_e32 v185, v185
	v_exp_f32_e32 v142, v142
	v_exp_f32_e32 v152, v152
	v_exp_f32_e32 v153, v153
	v_cndmask_b32_e32 v116, 0, v193, vcc
	v_cndmask_b32_e32 v118, 0, v212, vcc
	v_mul_f32_dpp v150, v150, v134 row_ror:1 row_mask:0xf bank_mask:0xf bound_ctrl:1
	v_mul_f32_dpp v151, v151, v136 row_ror:1 row_mask:0xf bank_mask:0xf bound_ctrl:1
	v_mul_f32_dpp v125, v125, v138 row_ror:1 row_mask:0xf bank_mask:0xf bound_ctrl:1
	v_mul_f32_dpp v127, v127, v140 row_ror:1 row_mask:0xf bank_mask:0xf bound_ctrl:1
	v_mul_f32_e32 v135, v120, v135
	v_mul_f32_e32 v220, v122, v220
	v_mul_f32_e32 v221, v124, v221
	v_mul_f32_e32 v222, v126, v222
	v_cndmask_b32_e32 v150, v134, v150, vcc
	v_cndmask_b32_e32 v151, v136, v151, vcc
	v_cndmask_b32_e32 v125, v138, v125, vcc
	v_cndmask_b32_e32 v127, v140, v127, vcc
	v_fma_f32 v120, v134, v112, v135
	v_fma_f32 v122, v136, v114, v220
	v_fma_f32 v124, v138, v116, v221
	v_fma_f32 v126, v140, v118, v222
	v_cvt_pk_bf16_f32 v134, v135, v220
	v_cvt_pk_bf16_f32 v135, v221, v222
	v_mov_b32_e32 v217, 0
	global_store_dwordx4 v[156:157], v[132:135], off offset:-2048 sc1
	s_nop 1
	v_fmac_f32_dpp v120, v120, v150 row_shr:1 row_mask:0xf bank_mask:0xf
	v_fmac_f32_dpp v122, v122, v151 row_shr:1 row_mask:0xf bank_mask:0xf
	v_fmac_f32_dpp v124, v124, v125 row_shr:1 row_mask:0xf bank_mask:0xf
	v_fmac_f32_dpp v126, v126, v127 row_shr:1 row_mask:0xf bank_mask:0xf
	v_mul_f32_dpp v150, v150, v150 row_shr:1 row_mask:0xf bank_mask:0xf
	v_mul_f32_dpp v151, v151, v151 row_shr:1 row_mask:0xf bank_mask:0xf
	v_mul_f32_dpp v125, v125, v125 row_shr:1 row_mask:0xf bank_mask:0xf
	v_mul_f32_dpp v127, v127, v127 row_shr:1 row_mask:0xf bank_mask:0xf
	v_fmac_f32_dpp v120, v120, v150 row_shr:2 row_mask:0xf bank_mask:0xf
	v_fmac_f32_dpp v122, v122, v151 row_shr:2 row_mask:0xf bank_mask:0xf
	v_fmac_f32_dpp v124, v124, v125 row_shr:2 row_mask:0xf bank_mask:0xf
	v_fmac_f32_dpp v126, v126, v127 row_shr:2 row_mask:0xf bank_mask:0xf
	v_mul_f32_dpp v150, v150, v150 row_shr:2 row_mask:0xf bank_mask:0xf
	v_mul_f32_dpp v151, v151, v151 row_shr:2 row_mask:0xf bank_mask:0xf
	v_mul_f32_dpp v125, v125, v125 row_shr:2 row_mask:0xf bank_mask:0xf
	v_mul_f32_dpp v127, v127, v127 row_shr:2 row_mask:0xf bank_mask:0xf
	v_fmac_f32_dpp v120, v120, v150 row_shr:4 row_mask:0xf bank_mask:0xf
	v_fmac_f32_dpp v122, v122, v151 row_shr:4 row_mask:0xf bank_mask:0xf
	v_fmac_f32_dpp v124, v124, v125 row_shr:4 row_mask:0xf bank_mask:0xf
	v_fmac_f32_dpp v126, v126, v127 row_shr:4 row_mask:0xf bank_mask:0xf
	v_mul_f32_dpp v150, v150, v150 row_shr:4 row_mask:0xf bank_mask:0xf
	v_mul_f32_dpp v151, v151, v151 row_shr:4 row_mask:0xf bank_mask:0xf
	v_mul_f32_dpp v125, v125, v125 row_shr:4 row_mask:0xf bank_mask:0xf
	v_mul_f32_dpp v127, v127, v127 row_shr:4 row_mask:0xf bank_mask:0xf
	v_fmac_f32_dpp v120, v120, v150 row_shr:8 row_mask:0xf bank_mask:0xf
	v_fmac_f32_dpp v122, v122, v151 row_shr:8 row_mask:0xf bank_mask:0xf
	v_fmac_f32_dpp v124, v124, v125 row_shr:8 row_mask:0xf bank_mask:0xf
	v_fmac_f32_dpp v126, v126, v127 row_shr:8 row_mask:0xf bank_mask:0xf
	v_mul_f32_dpp v150, v150, v150 row_shr:8 row_mask:0xf bank_mask:0xf
	v_mul_f32_dpp v151, v151, v151 row_shr:8 row_mask:0xf bank_mask:0xf
	v_mul_f32_dpp v125, v125, v125 row_shr:8 row_mask:0xf bank_mask:0xf
	v_mul_f32_dpp v127, v127, v127 row_shr:8 row_mask:0xf bank_mask:0xf

; __device__ __forceinline__ float fexp(float x) { return __builtin_amdgcn_exp2f(x * 1.4426950408889634f); }
; #define LAS __attribute__((address_space(3)))
; __device__ __forceinline__ unsigned pk2(float lo, float hi) { return pg8::cvt_pk_bf16(lo, hi); }
; __device__ __forceinline__ float fexp(float x) { return __builtin_amdgcn_exp2f(x * 1.4426950408889634f); }
; __device__ __forceinline__ float fsigmoid(float x) { return __builtin_amdgcn_rcpf(1.0f + fexp(-x)); }
; template <int PASS>
; __device__ __forceinline__ void lru_unit(const LruP& P, const LruInv& V, int b, int c, LAS unsigned char* wl, LAS float* red, int wave, int lane, int pairpos) {
;     ...
;             const f32x4 br = V.br[n], bi = V.bi[n], sl = V.sl[n];
;             const v2u xw = *(const LAS v2u*)(xc + (16 * m + fr) * 72 + 16 * n + 4 * fq);
;             const float xv[4] = {bflo(xw.x), bfhi(xw.x), bflo(xw.y), bfhi(xw.y)};
;             const v2u gw = gcur[n];
;             const float gv[4] = {bflo(gw.x), bfhi(gw.x), bflo(gw.y), bfhi(gw.y)};
;             float av[4], bv[4], laraw[4], braw[4];
; #pragma unroll
;             for (int j = 0; j < 4; ++j) {
;                 const float r = fsigmoid(R[j] + br[j]), ig = fsigmoid(I[j] + bi[j]);
;                 const float la = r * sl[j];
;                 const float a = fexp(la);
;                 const float bt = __builtin_amdgcn_sqrtf(fmaxf(1.0f - a * a, 0.f)) * (ig * xv[j]);
;                 laraw[j] = la; braw[j] = bt;
;                 const float cin = row_ror1(hin[n][j]);
;                 bv[j] = fmaf(a, lane0 ? cin : 0.f, bt);
;                 if (PASS == 1) { const float ain = row_ror1(arun[n][j]); av[j] = lane0 ? a * ain : a; } else av[j] = a;
;             }
;             if (PASS == 1) { v4u w; w.x = pk2(laraw[0], laraw[1]); w.y = pk2(laraw[2], laraw[3]); w.z = pk2(braw[0], braw[1]); w.w = pk2(braw[2], braw[3]);
;                 ((v4u*)P.AB)[((((size_t)(b * NCH + c) * 8 + wave) * 4 + m) * 4 + n) * 64 + lane] = w; }
;             scan4(av, bv);
; #pragma unroll
;             for (int j = 0; j < 4; ++j) {
;                 hin[n][j] = bv[j];
;                 if (PASS == 1) arun[n][j] = av[j];
	ds_read_b64 v[134:135], v121 offset:32
	v_mov_b32_dpp v217, v128 row_ror:1 row_mask:0xf bank_mask:0xf
	v_cndmask_b32_e32 v128, 0, v214, vcc
	v_cndmask_b32_e32 v211, 0, v223, vcc
	v_cndmask_b32_e32 v214, 0, v224, vcc
	v_add_f32_e32 v163, 1.0, v163
	v_add_f32_e32 v181, 1.0, v181
	v_add_f32_e32 v183, 1.0, v183
	v_add_f32_e32 v185, 1.0, v185
	v_fma_f32 v223, -v219, v219, 1.0
	v_fma_f32 v224, -v142, v142, 1.0
	v_fma_f32 v225, -v152, v152, 1.0
	v_fma_f32 v226, -v153, v153, 1.0
	v_rcp_f32_e32 v163, v163
	v_rcp_f32_e32 v181, v181
	v_rcp_f32_e32 v183, v183
	v_rcp_f32_e32 v185, v185
	v_max_f32_e32 v223, 0, v223
	v_max_f32_e32 v224, 0, v224
	v_max_f32_e32 v225, 0, v225
	v_max_f32_e32 v226, 0, v226
	v_sqrt_f32_e32 v223, v223
	v_sqrt_f32_e32 v224, v224
	v_sqrt_f32_e32 v225, v225
	v_sqrt_f32_e32 v226, v226
	v_add_f32_e32 v137, v77, v137
	v_add_f32_e32 v139, v79, v139
	v_mul_f32_e32 v137, 0xbfb8aa3b, v137
	v_mul_f32_e32 v139, 0xbfb8aa3b, v139
	v_mul_f32_e32 v202, 0x3fb8aa3b, v160
	v_mul_f32_e32 v203, 0x3fb8aa3b, v161
	v_mul_f32_e32 v204, 0x3fb8aa3b, v162
	v_mul_f32_e32 v205, 0x3fb8aa3b, v180
	s_waitcnt lgkmcnt(0)
	v_lshlrev_b32_e32 v112, 16, v134
	v_and_b32_e32 v114, 0xffff0000, v134
	v_lshlrev_b32_e32 v116, 16, v135
	v_and_b32_e32 v118, 0xffff0000, v135
	v_mov_b32_e32 v218, 0
	v_exp_f32_e32 v137, v137
	v_exp_f32_e32 v139, v139
	v_exp_f32_e32 v202, v202
	v_exp_f32_e32 v203, v203
	v_exp_f32_e32 v204, v204
	v_exp_f32_e32 v205, v205
	v_mul_f32_e32 v112, v163, v112
	v_mul_f32_e32 v114, v181, v114
	v_mul_f32_e32 v116, v183, v116
	v_mul_f32_e32 v118, v185, v118
	v_mov_b32_dpp v218, v130 row_ror:1 row_mask:0xf bank_mask:0xf
	v_cndmask_b32_e32 v130, 0, v215, vcc
	v_cndmask_b32_e32 v192, 0, v216, vcc
	v_mul_f32_dpp v148, v148, v219 row_ror:1 row_mask:0xf bank_mask:0xf bound_ctrl:1
	v_mul_f32_dpp v149, v149, v142 row_ror:1 row_mask:0xf bank_mask:0xf bound_ctrl:1
	v_mul_f32_dpp v131, v131, v152 row_ror:1 row_mask:0xf bank_mask:0xf bound_ctrl:1
	v_mul_f32_dpp v129, v129, v153 row_ror:1 row_mask:0xf bank_mask:0xf bound_ctrl:1
	v_mul_f32_e32 v112, v112, v223
	v_mul_f32_e32 v114, v114, v224
	v_mul_f32_e32 v116, v116, v225
	v_mul_f32_e32 v118, v118, v226
	v_cndmask_b32_e32 v148, v219, v148, vcc
	v_cndmask_b32_e32 v149, v142, v149, vcc
	v_cndmask_b32_e32 v131, v152, v131, vcc
	v_cndmask_b32_e32 v129, v153, v129, vcc
	v_cvt_pk_bf16_f32 v132, v154, v155
	v_cvt_pk_bf16_f32 v133, v158, v159
	v_fma_f32 v136, v219, v123, v112
	v_fma_f32 v138, v142, v128, v114
	v_fma_f32 v140, v152, v130, v116
	v_fma_f32 v142, v153, v192, v118
	v_cvt_pk_bf16_f32 v134, v112, v114
	v_cvt_pk_bf16_f32 v135, v116, v118
	global_store_dwordx4 v[156:157], v[132:135], off offset:-1024 sc1
	s_nop 1
	v_fmac_f32_dpp v136, v136, v148 row_shr:1 row_mask:0xf bank_mask:0xf
	v_fmac_f32_dpp v138, v138, v149 row_shr:1 row_mask:0xf bank_mask:0xf
	v_fmac_f32_dpp v140, v140, v131 row_shr:1 row_mask:0xf bank_mask:0xf
	v_fmac_f32_dpp v142, v142, v129 row_shr:1 row_mask:0xf bank_mask:0xf
	v_mul_f32_dpp v148, v148, v148 row_shr:1 row_mask:0xf bank_mask:0xf
	v_mul_f32_dpp v149, v149, v149 row_shr:1 row_mask:0xf bank_mask:0xf
	v_mul_f32_dpp v131, v131, v131 row_shr:1 row_mask:0xf bank_mask:0xf
	v_mul_f32_dpp v129, v129, v129 row_shr:1 row_mask:0xf bank_mask:0xf
	v_fmac_f32_dpp v136, v136, v148 row_shr:2 row_mask:0xf bank_mask:0xf
	v_fmac_f32_dpp v138, v138, v149 row_shr:2 row_mask:0xf bank_mask:0xf
	v_fmac_f32_dpp v140, v140, v131 row_shr:2 row_mask:0xf bank_mask:0xf
	v_fmac_f32_dpp v142, v142, v129 row_shr:2 row_mask:0xf bank_mask:0xf
	v_mul_f32_dpp v148, v148, v148 row_shr:2 row_mask:0xf bank_mask:0xf
	v_mul_f32_dpp v149, v149, v149 row_shr:2 row_mask:0xf bank_mask:0xf
	v_mul_f32_dpp v131, v131, v131 row_shr:2 row_mask:0xf bank_mask:0xf
	v_mul_f32_dpp v129, v129, v129 row_shr:2 row_mask:0xf bank_mask:0xf
	v_fmac_f32_dpp v136, v136, v148 row_shr:4 row_mask:0xf bank_mask:0xf
	v_fmac_f32_dpp v138, v138, v149 row_shr:4 row_mask:0xf bank_mask:0xf
	v_fmac_f32_dpp v140, v140, v131 row_shr:4 row_mask:0xf bank_mask:0xf
	v_fmac_f32_dpp v142, v142, v129 row_shr:4 row_mask:0xf bank_mask:0xf
	v_mul_f32_dpp v148, v148, v148 row_shr:4 row_mask:0xf bank_mask:0xf
	v_mul_f32_dpp v149, v149, v149 row_shr:4 row_mask:0xf bank_mask:0xf
	v_mul_f32_dpp v131, v131, v131 row_shr:4 row_mask:0xf bank_mask:0xf
	v_mul_f32_dpp v129, v129, v129 row_shr:4 row_mask:0xf bank_mask:0xf
	v_fmac_f32_dpp v136, v136, v148 row_shr:8 row_mask:0xf bank_mask:0xf
	v_fmac_f32_dpp v138, v138, v149 row_shr:8 row_mask:0xf bank_mask:0xf
	v_fmac_f32_dpp v140, v140, v131 row_shr:8 row_mask:0xf bank_mask:0xf
	v_fmac_f32_dpp v142, v142, v129 row_shr:8 row_mask:0xf bank_mask:0xf
	v_mul_f32_dpp v148, v148, v148 row_shr:8 row_mask:0xf bank_mask:0xf
	v_mul_f32_dpp v149, v149, v149 row_shr:8 row_mask:0xf bank_mask:0xf
	v_mul_f32_dpp v131, v131, v131 row_shr:8 row_mask:0xf bank_mask:0xf
	v_mul_f32_dpp v129, v129, v129 row_shr:8 row_mask:0xf bank_mask:0xf

; __device__ __forceinline__ float fexp(float x) { return __builtin_amdgcn_exp2f(x * 1.4426950408889634f); }
; #define LAS __attribute__((address_space(3)))
; __device__ __forceinline__ unsigned pk2(float lo, float hi) { return pg8::cvt_pk_bf16(lo, hi); }
; __device__ __forceinline__ float fexp(float x) { return __builtin_amdgcn_exp2f(x * 1.4426950408889634f); }
; __device__ __forceinline__ float fsigmoid(float x) { return __builtin_amdgcn_rcpf(1.0f + fexp(-x)); }
; template <int PASS>
; __device__ __forceinline__ void lru_unit(const LruP& P, const LruInv& V, int b, int c, LAS unsigned char* wl, LAS float* red, int wave, int lane, int pairpos) {
;     ...
;             const f32x4 br = V.br[n], bi = V.bi[n], sl = V.sl[n];
;             const v2u xw = *(const LAS v2u*)(xc + (16 * m + fr) * 72 + 16 * n + 4 * fq);
;             const float xv[4] = {bflo(xw.x), bfhi(xw.x), bflo(xw.y), bfhi(xw.y)};
;             const v2u gw = gcur[n];
;             const float gv[4] = {bflo(gw.x), bfhi(gw.x), bflo(gw.y), bfhi(gw.y)};
;             float av[4], bv[4], laraw[4], braw[4];
; #pragma unroll
;             for (int j = 0; j < 4; ++j) {
;                 const float r = fsigmoid(R[j] + br[j]), ig = fsigmoid(I[j] + bi[j]);
;                 const float la = r * sl[j];
;                 const float a = fexp(la);
;                 const float bt = __builtin_amdgcn_sqrtf(fmaxf(1.0f - a * a, 0.f)) * (ig * xv[j]);
;                 laraw[j] = la; braw[j] = bt;
;                 const float cin = row_ror1(hin[n][j]);
;                 bv[j] = fmaf(a, lane0 ? cin : 0.f, bt);
;                 if (PASS == 1) { const float ain = row_ror1(arun[n][j]); av[j] = lane0 ? a * ain : a; } else av[j] = a;
;             }
;             if (PASS == 1) { v4u w; w.x = pk2(laraw[0], laraw[1]); w.y = pk2(laraw[2], laraw[3]); w.z = pk2(braw[0], braw[1]); w.w = pk2(braw[2], braw[3]);
;                 ((v4u*)P.AB)[((((size_t)(b * NCH + c) * 8 + wave) * 4 + m) * 4 + n) * 64 + lane] = w; }
;             scan4(av, bv);
; #pragma unroll
;             for (int j = 0; j < 4; ++j) {
;                 hin[n][j] = bv[j];
;                 if (PASS == 1) arun[n][j] = av[j];
	ds_read_b64 v[132:133], v121 offset:64
	v_add_f32_e32 v137, 1.0, v137
	v_add_f32_e32 v139, 1.0, v139
	v_fma_f32 v227, -v202, v202, 1.0
	v_fma_f32 v228, -v203, v203, 1.0
	v_fma_f32 v229, -v204, v204, 1.0
	v_fma_f32 v230, -v205, v205, 1.0
	v_rcp_f32_e32 v137, v137
	v_rcp_f32_e32 v139, v139
	v_max_f32_e32 v227, 0, v227
	v_max_f32_e32 v228, 0, v228
	v_max_f32_e32 v229, 0, v229
	v_max_f32_e32 v230, 0, v230
	v_sqrt_f32_e32 v227, v227
	v_sqrt_f32_e32 v228, v228
	v_sqrt_f32_e32 v229, v229
	v_sqrt_f32_e32 v230, v230
	v_cndmask_b32_e32 v193, 0, v217, vcc
	v_cndmask_b32_e32 v212, 0, v218, vcc
	v_mul_f32_e32 v215, 0x3fb8aa3b, v182
	v_mul_f32_e32 v216, 0x3fb8aa3b, v184
	v_mul_f32_e32 v217, 0x3fb8aa3b, v186
	v_mul_f32_e32 v218, 0x3fb8aa3b, v187
	s_waitcnt lgkmcnt(0)
	v_lshlrev_b32_e32 v112, 16, v132
	v_and_b32_e32 v114, 0xffff0000, v132
	v_lshlrev_b32_e32 v116, 16, v133
	v_and_b32_e32 v118, 0xffff0000, v133
	v_exp_f32_e32 v215, v215
	v_exp_f32_e32 v216, v216
	v_exp_f32_e32 v217, v217
	v_exp_f32_e32 v218, v218
	v_mul_f32_e32 v112, v190, v112
	v_mul_f32_e32 v114, v137, v114
	v_mul_f32_e32 v116, v188, v116
	v_mul_f32_e32 v118, v139, v118
	v_mul_f32_dpp v146, v146, v202 row_ror:1 row_mask:0xf bank_mask:0xf bound_ctrl:1
	v_mul_f32_dpp v147, v147, v203 row_ror:1 row_mask:0xf bank_mask:0xf bound_ctrl:1
	v_mul_f32_dpp v115, v115, v204 row_ror:1 row_mask:0xf bank_mask:0xf bound_ctrl:1
	v_mul_f32_dpp v113, v113, v205 row_ror:1 row_mask:0xf bank_mask:0xf bound_ctrl:1
	v_mul_f32_e32 v112, v112, v227
	v_mul_f32_e32 v114, v114, v228
	v_mul_f32_e32 v116, v116, v229
	v_mul_f32_e32 v118, v118, v230
	v_cndmask_b32_e32 v146, v202, v146, vcc
	v_cndmask_b32_e32 v147, v203, v147, vcc
	v_cndmask_b32_e32 v115, v204, v115, vcc
	v_cndmask_b32_e32 v113, v205, v113, vcc
	v_cvt_pk_bf16_f32 v152, v160, v161
	v_cvt_pk_bf16_f32 v153, v162, v180
	v_fma_f32 v128, v202, v193, v112
	v_fma_f32 v130, v203, v212, v114
	v_fma_f32 v132, v204, v213, v116
	v_fma_f32 v134, v205, v208, v118
	v_cvt_pk_bf16_f32 v154, v112, v114
	v_cvt_pk_bf16_f32 v155, v116, v118
	global_store_dwordx4 v[156:157], v[152:155], off sc1
	s_nop 1
	v_fmac_f32_dpp v128, v128, v146 row_shr:1 row_mask:0xf bank_mask:0xf
	v_fmac_f32_dpp v130, v130, v147 row_shr:1 row_mask:0xf bank_mask:0xf
	v_fmac_f32_dpp v132, v132, v115 row_shr:1 row_mask:0xf bank_mask:0xf
	v_fmac_f32_dpp v134, v134, v113 row_shr:1 row_mask:0xf bank_mask:0xf
	v_mul_f32_dpp v146, v146, v146 row_shr:1 row_mask:0xf bank_mask:0xf
	v_mul_f32_dpp v147, v147, v147 row_shr:1 row_mask:0xf bank_mask:0xf
	v_mul_f32_dpp v115, v115, v115 row_shr:1 row_mask:0xf bank_mask:0xf
	v_mul_f32_dpp v113, v113, v113 row_shr:1 row_mask:0xf bank_mask:0xf
	v_fmac_f32_dpp v128, v128, v146 row_shr:2 row_mask:0xf bank_mask:0xf
	v_fmac_f32_dpp v130, v130, v147 row_shr:2 row_mask:0xf bank_mask:0xf
	v_fmac_f32_dpp v132, v132, v115 row_shr:2 row_mask:0xf bank_mask:0xf
	v_fmac_f32_dpp v134, v134, v113 row_shr:2 row_mask:0xf bank_mask:0xf
	v_mul_f32_dpp v146, v146, v146 row_shr:2 row_mask:0xf bank_mask:0xf
	v_mul_f32_dpp v147, v147, v147 row_shr:2 row_mask:0xf bank_mask:0xf
	v_mul_f32_dpp v115, v115, v115 row_shr:2 row_mask:0xf bank_mask:0xf
	v_mul_f32_dpp v113, v113, v113 row_shr:2 row_mask:0xf bank_mask:0xf
	v_fmac_f32_dpp v128, v128, v146 row_shr:4 row_mask:0xf bank_mask:0xf
	v_fmac_f32_dpp v130, v130, v147 row_shr:4 row_mask:0xf bank_mask:0xf
	v_fmac_f32_dpp v132, v132, v115 row_shr:4 row_mask:0xf bank_mask:0xf
	v_fmac_f32_dpp v134, v134, v113 row_shr:4 row_mask:0xf bank_mask:0xf
	v_mul_f32_dpp v146, v146, v146 row_shr:4 row_mask:0xf bank_mask:0xf
	v_mul_f32_dpp v147, v147, v147 row_shr:4 row_mask:0xf bank_mask:0xf
	v_mul_f32_dpp v115, v115, v115 row_shr:4 row_mask:0xf bank_mask:0xf
	v_mul_f32_dpp v113, v113, v113 row_shr:4 row_mask:0xf bank_mask:0xf
	v_fmac_f32_dpp v128, v128, v146 row_shr:8 row_mask:0xf bank_mask:0xf
	v_fmac_f32_dpp v130, v130, v147 row_shr:8 row_mask:0xf bank_mask:0xf
	v_fmac_f32_dpp v132, v132, v115 row_shr:8 row_mask:0xf bank_mask:0xf
	v_fmac_f32_dpp v134, v134, v113 row_shr:8 row_mask:0xf bank_mask:0xf
	v_mul_f32_dpp v146, v146, v146 row_shr:8 row_mask:0xf bank_mask:0xf
	v_mul_f32_dpp v147, v147, v147 row_shr:8 row_mask:0xf bank_mask:0xf
	v_mul_f32_dpp v115, v115, v115 row_shr:8 row_mask:0xf bank_mask:0xf
	v_mul_f32_dpp v113, v113, v113 row_shr:8 row_mask:0xf bank_mask:0xf

; __device__ __forceinline__ float fexp(float x) { return __builtin_amdgcn_exp2f(x * 1.4426950408889634f); }
; #define LAS __attribute__((address_space(3)))
; __device__ __forceinline__ unsigned pk2(float lo, float hi) { return pg8::cvt_pk_bf16(lo, hi); }
; __device__ __forceinline__ float fexp(float x) { return __builtin_amdgcn_exp2f(x * 1.4426950408889634f); }
; __device__ __forceinline__ float fsigmoid(float x) { return __builtin_amdgcn_rcpf(1.0f + fexp(-x)); }
; template <int PASS>
; __device__ __forceinline__ void lru_unit(const LruP& P, const LruInv& V, int b, int c, LAS unsigned char* wl, LAS float* red, int wave, int lane, int pairpos) {
;     ...
;             const f32x4 br = V.br[n], bi = V.bi[n], sl = V.sl[n];
;             const v2u xw = *(const LAS v2u*)(xc + (16 * m + fr) * 72 + 16 * n + 4 * fq);
;             const float xv[4] = {bflo(xw.x), bfhi(xw.x), bflo(xw.y), bfhi(xw.y)};
;             const v2u gw = gcur[n];
;             const float gv[4] = {bflo(gw.x), bfhi(gw.x), bflo(gw.y), bfhi(gw.y)};
;             float av[4], bv[4], laraw[4], braw[4];
; #pragma unroll
;             for (int j = 0; j < 4; ++j) {
;                 const float r = fsigmoid(R[j] + br[j]), ig = fsigmoid(I[j] + bi[j]);
;                 const float la = r * sl[j];
;                 const float a = fexp(la);
;                 const float bt = __builtin_amdgcn_sqrtf(fmaxf(1.0f - a * a, 0.f)) * (ig * xv[j]);
;                 laraw[j] = la; braw[j] = bt;
;                 const float cin = row_ror1(hin[n][j]);
;                 bv[j] = fmaf(a, lane0 ? cin : 0.f, bt);
;                 if (PASS == 1) { const float ain = row_ror1(arun[n][j]); av[j] = lane0 ? a * ain : a; } else av[j] = a;
;             }
;             if (PASS == 1) { v4u w; w.x = pk2(laraw[0], laraw[1]); w.y = pk2(laraw[2], laraw[3]); w.z = pk2(braw[0], braw[1]); w.w = pk2(braw[2], braw[3]);
;                 ((v4u*)P.AB)[((((size_t)(b * NCH + c) * 8 + wave) * 4 + m) * 4 + n) * 64 + lane] = w; }
;             scan4(av, bv);
; #pragma unroll
;             for (int j = 0; j < 4; ++j) {
;                 hin[n][j] = bv[j];
;                 if (PASS == 1) arun[n][j] = av[j];
	ds_read_b64 v[154:155], v121 offset:96
	v_fma_f32 v231, -v215, v215, 1.0
	v_fma_f32 v232, -v216, v216, 1.0
	v_fma_f32 v233, -v217, v217, 1.0
	v_fma_f32 v234, -v218, v218, 1.0
	v_max_f32_e32 v231, 0, v231
	v_max_f32_e32 v232, 0, v232
	v_max_f32_e32 v233, 0, v233
	v_max_f32_e32 v234, 0, v234
	v_sqrt_f32_e32 v231, v231
	v_sqrt_f32_e32 v232, v232
	v_sqrt_f32_e32 v233, v233
	v_sqrt_f32_e32 v234, v234
	s_waitcnt lgkmcnt(0)
	v_lshlrev_b32_e32 v112, 16, v154
	v_and_b32_e32 v114, 0xffff0000, v154
	v_lshlrev_b32_e32 v116, 16, v155
	v_and_b32_e32 v118, 0xffff0000, v155
	v_mul_f32_e32 v112, v189, v112
	v_mul_f32_e32 v114, v141, v114
	v_mul_f32_e32 v116, v191, v116
	v_mul_f32_e32 v118, v143, v118
	s_addk_i32 s0, 0x900
	v_mul_f32_dpp v144, v144, v215 row_ror:1 row_mask:0xf bank_mask:0xf bound_ctrl:1
	v_mul_f32_dpp v145, v145, v216 row_ror:1 row_mask:0xf bank_mask:0xf bound_ctrl:1
	v_mul_f32_dpp v117, v117, v217 row_ror:1 row_mask:0xf bank_mask:0xf bound_ctrl:1
	v_mul_f32_dpp v119, v119, v218 row_ror:1 row_mask:0xf bank_mask:0xf bound_ctrl:1
	v_mul_f32_e32 v121, v112, v231
	v_mul_f32_e32 v123, v114, v232
	v_mul_f32_e32 v133, v116, v233
	v_mul_f32_e32 v135, v118, v234
	s_cmpk_lg_i32 s0, 0x2400
	v_cndmask_b32_e32 v144, v215, v144, vcc
	v_cndmask_b32_e32 v145, v216, v145, vcc
	v_cndmask_b32_e32 v117, v217, v117, vcc
	v_cndmask_b32_e32 v119, v218, v119, vcc
	v_cvt_pk_bf16_f32 v152, v182, v184
	v_cvt_pk_bf16_f32 v153, v186, v187
	v_fma_f32 v112, v215, v209, v121
	v_fma_f32 v114, v216, v210, v123
	v_fma_f32 v116, v217, v211, v133
	v_fma_f32 v118, v218, v214, v135
	v_cvt_pk_bf16_f32 v154, v121, v123
	v_cvt_pk_bf16_f32 v155, v133, v135
	global_store_dwordx4 v[156:157], v[152:155], off offset:1024 sc1
	v_lshl_add_u64 v[156:157], v[156:157], 0, s[12:13]
	s_nop 1
	v_fmac_f32_dpp v112, v112, v144 row_shr:1 row_mask:0xf bank_mask:0xf
	v_fmac_f32_dpp v114, v114, v145 row_shr:1 row_mask:0xf bank_mask:0xf
	v_fmac_f32_dpp v116, v116, v117 row_shr:1 row_mask:0xf bank_mask:0xf
	v_fmac_f32_dpp v118, v118, v119 row_shr:1 row_mask:0xf bank_mask:0xf
	v_mul_f32_dpp v144, v144, v144 row_shr:1 row_mask:0xf bank_mask:0xf
	v_mul_f32_dpp v145, v145, v145 row_shr:1 row_mask:0xf bank_mask:0xf
	v_mul_f32_dpp v117, v117, v117 row_shr:1 row_mask:0xf bank_mask:0xf
	v_mul_f32_dpp v119, v119, v119 row_shr:1 row_mask:0xf bank_mask:0xf
	v_fmac_f32_dpp v112, v112, v144 row_shr:2 row_mask:0xf bank_mask:0xf
	v_fmac_f32_dpp v114, v114, v145 row_shr:2 row_mask:0xf bank_mask:0xf
	v_fmac_f32_dpp v116, v116, v117 row_shr:2 row_mask:0xf bank_mask:0xf
	v_fmac_f32_dpp v118, v118, v119 row_shr:2 row_mask:0xf bank_mask:0xf
	v_mul_f32_dpp v144, v144, v144 row_shr:2 row_mask:0xf bank_mask:0xf
	v_mul_f32_dpp v145, v145, v145 row_shr:2 row_mask:0xf bank_mask:0xf
	v_mul_f32_dpp v117, v117, v117 row_shr:2 row_mask:0xf bank_mask:0xf
	v_mul_f32_dpp v119, v119, v119 row_shr:2 row_mask:0xf bank_mask:0xf
	v_fmac_f32_dpp v112, v112, v144 row_shr:4 row_mask:0xf bank_mask:0xf
	v_fmac_f32_dpp v114, v114, v145 row_shr:4 row_mask:0xf bank_mask:0xf
	v_fmac_f32_dpp v116, v116, v117 row_shr:4 row_mask:0xf bank_mask:0xf
	v_fmac_f32_dpp v118, v118, v119 row_shr:4 row_mask:0xf bank_mask:0xf
	v_mul_f32_dpp v144, v144, v144 row_shr:4 row_mask:0xf bank_mask:0xf
	v_mul_f32_dpp v145, v145, v145 row_shr:4 row_mask:0xf bank_mask:0xf
	v_mul_f32_dpp v117, v117, v117 row_shr:4 row_mask:0xf bank_mask:0xf
	v_mul_f32_dpp v119, v119, v119 row_shr:4 row_mask:0xf bank_mask:0xf
	v_fmac_f32_dpp v112, v112, v144 row_shr:8 row_mask:0xf bank_mask:0xf
	v_fmac_f32_dpp v114, v114, v145 row_shr:8 row_mask:0xf bank_mask:0xf
	v_fmac_f32_dpp v116, v116, v117 row_shr:8 row_mask:0xf bank_mask:0xf
	v_fmac_f32_dpp v118, v118, v119 row_shr:8 row_mask:0xf bank_mask:0xf
	v_mul_f32_dpp v144, v144, v144 row_shr:8 row_mask:0xf bank_mask:0xf
	v_mul_f32_dpp v145, v145, v145 row_shr:8 row_mask:0xf bank_mask:0xf
	v_mul_f32_dpp v117, v117, v117 row_shr:8 row_mask:0xf bank_mask:0xf
	v_mul_f32_dpp v119, v119, v119 row_shr:8 row_mask:0xf bank_mask:0xf

; template <int PASS>
; __device__ __forceinline__ void lru_unit(const LruP& P, const LruInv& V, int b, int c, LAS unsigned char* wl, LAS float* red, int wave, int lane, int pairpos) {
;     ...
;     if (PASS == 1) {
;         if (fr == 15) {
;             if (pairpos == 0) {
; #pragma unroll
;                 for (int n = 0; n < 4; ++n)
; #pragma unroll
;                     for (int j = 0; j < 4; ++j) { stash[(n * 4 + j) * 2] = hin[n][j]; stash[(n * 4 + j) * 2 + 1] = arun[n][j]; } }
; #pragma unroll
;             for (int n = 0; n < 4; ++n) { const size_t o = ((size_t)(b * NCH + c)) * 512 + chl + 16 * n;
;                 *(f32x4*)(P.AgA + o) = (f32x4){arun[n][0], arun[n][1], arun[n][2], arun[n][3]};
;                 *(f32x4*)(P.AgH + o) = (f32x4){hin[n][0], hin[n][1], hin[n][2], hin[n][3]}; }
	s_cbranch_scc1 .LBB0_338
	s_and_saveexec_b64 s[0:1], s[2:3]
	s_cbranch_execz .LBB0_332
	s_add_i32 s4, s18, s15
	s_ashr_i32 s5, s4, 31
	s_lshl_b64 s[4:5], s[4:5], 9
	v_lshl_add_u64 v[152:153], s[4:5], 0, v[164:165]
	v_lshlrev_b64 v[154:155], 2, v[152:153]
	v_lshl_add_u64 v[156:157], s[46:47], 0, v[154:155]
	v_mov_b32_e32 v152, v125
	v_mov_b32_e32 v153, v127
	global_store_dwordx4 v[156:157], v[150:153], off sc1
	v_mov_b32_e32 v121, v122
	v_mov_b32_e32 v122, v124
	v_lshl_add_u64 v[150:151], s[50:51], 0, v[154:155]
	v_mov_b32_e32 v123, v126
	global_store_dwordx4 v[150:151], v[120:123], off sc1
	v_mov_b32_e32 v137, v138
	v_mov_b32_e32 v138, v140
	v_or_b32_e32 v120, 64, v154
	v_mov_b32_e32 v121, v155
	v_lshl_add_u64 v[122:123], s[46:47], 0, v[120:121]
	v_lshl_add_u64 v[120:121], s[50:51], 0, v[120:121]
	v_mov_b32_e32 v139, v142
	v_mov_b32_e32 v150, v131
	v_mov_b32_e32 v151, v129
	global_store_dwordx4 v[120:121], v[136:139], off sc1
	v_or_b32_e32 v120, 0x80, v154
	v_mov_b32_e32 v121, v155
	global_store_dwordx4 v[122:123], v[148:151], off sc1
	v_lshl_add_u64 v[122:123], s[46:47], 0, v[120:121]
	v_lshl_add_u64 v[120:121], s[50:51], 0, v[120:121]
	v_mov_b32_e32 v148, v115
	v_mov_b32_e32 v149, v113
	v_mov_b32_e32 v129, v130
	v_mov_b32_e32 v130, v132
	v_mov_b32_e32 v131, v134
	v_or_b32_e32 v154, 0xc0, v154
	global_store_dwordx4 v[122:123], v[146:149], off sc1
	global_store_dwordx4 v[120:121], v[128:131], off sc1
	v_lshl_add_u64 v[120:121], s[46:47], 0, v[154:155]
	v_mov_b32_e32 v146, v117
	v_mov_b32_e32 v147, v119
	global_store_dwordx4 v[120:121], v[144:147], off sc1
	v_lshl_add_u64 v[120:121], s[50:51], 0, v[154:155]
	v_mov_b32_e32 v113, v114
	v_mov_b32_e32 v114, v116
	v_mov_b32_e32 v115, v118
	global_store_dwordx4 v[120:121], v[112:115], off sc1
	s_branch .LBB0_332

; __device__ __forceinline__ unsigned cvt_pk_bf16(float lo, float hi) { unsigned r; asm volatile("v_cvt_pk_bf16_f32 %0, %1, %2" : "=v"(r) : "v"(lo), "v"(hi)); return r; }
;     __device__ __forceinline__ void operator()(const f32x4 (&acc)[2][2][4][2], const Unit& u, int wr, int wc, int fr, int fq) const {
;     ...
;         float rs[8];
; #pragma unroll
;         for (int st = 0; st < 8; ++st) rs[st] = rs1[row0 + (st >> 2) * HALF + (st & 3) * 16];
;         u32x4 pre[2][2];
;         { const size_t off = (size_t)row0 * 1024 + col0; pre[0][0] = *(const u32x4*)(xb + off); pre[0][1] = *(const u32x4*)(xb + off + HALF); }
; #pragma unroll
;         for (int st = 0; st < 8; ++st) { const int ai = st >> 2, m = st & 3; const int row = row0 + ai * HALF + m * 16;
;             if (st < 7) { const int rn = row0 + ((st + 1) >> 2) * HALF + ((st + 1) & 3) * 16; const size_t off = (size_t)rn * 1024 + col0; u32x4* p = pre[(st + 1) & 1];
;                 p[0] = *(const u32x4*)(xb + off); p[1] = *(const u32x4*)(xb + off + HALF); }
;             __builtin_amdgcn_sched_barrier(0);
;             float s = 0.f; const float r = rs[st];
; #pragma unroll
;             for (int bj = 0; bj < 2; ++bj) { const size_t off = (size_t)row * 1024 + col0 + bj * HALF; const u32x4 h = pre[st & 1][bj];
;                 const f32x4 x0 = (f32x4){__uint_as_float(h.x << 16), __uint_as_float(h.x & 0xffff0000u), __uint_as_float(h.y << 16), __uint_as_float(h.y & 0xffff0000u)};
;                 const f32x4 x1v = (f32x4){__uint_as_float(h.z << 16), __uint_as_float(h.z & 0xffff0000u), __uint_as_float(h.w << 16), __uint_as_float(h.w & 0xffff0000u)};
;                 const f32x4 v0 = acc[ai][bj][m][0] + x0 * r, v1 = acc[ai][bj][m][1] + x1v * r;
;                 u32x4 w; w.x = cvt_pk_bf16(v0[0], v0[1]); w.y = cvt_pk_bf16(v0[2], v0[3]); w.z = cvt_pk_bf16(v1[0], v1[1]); w.w = cvt_pk_bf16(v1[2], v1[3]);
;                 *(u32x4*)(xb + off) = w;
;                 s += (v0[0] * v0[0] + v0[1] * v0[1]) + (v0[2] * v0[2] + v0[3] * v0[3]) + (v1[0] * v1[0] + v1[1] * v1[1]) + (v1[2] * v1[2] + v1[3] * v1[3]); }
;             s += __shfl_xor(s, 16); s += __shfl_xor(s, 32);
;             if (fq == 0) (void)__hip_atomic_fetch_add(racc + row, (1ull << 48) + (unsigned long long)(s * 65536.0f + 0.5f), __ATOMIC_RELAXED, __HIP_MEMORY_SCOPE_AGENT);
;             __builtin_amdgcn_sched_barrier(0); }
.LBB0_483:
	v_lshl_add_u32 v160, s52, 8, v155
	v_lshl_or_b32 v162, s50, 8, v165
	v_ashrrev_i32_e32 v161, 31, v160
	v_ashrrev_i32_e32 v163, 31, v162
	v_lshl_add_u64 v[180:181], v[160:161], 2, s[8:9]
	v_lshlrev_b64 v[172:173], 11, v[160:161]
	v_lshlrev_b64 v[162:163], 1, v[162:163]
	v_lshl_add_u64 v[172:173], s[36:37], 0, v[172:173]
	v_lshl_add_u64 v[178:179], v[160:161], 3, s[10:11]
	v_lshl_add_u64 v[172:173], v[172:173], 0, v[162:163]
	s_mov_b64 s[50:51], 0x8000
	v_mov_b64_e32 v[174:175], v[172:173]
	global_load_dwordx4 v[184:187], v[172:173], off
	global_load_dwordx4 v[188:191], v[172:173], off offset:256
	global_load_dword v164, v[180:181], off
	global_load_dword v166, v[180:181], off offset:64
	global_load_dword v170, v[180:181], off offset:128
	global_load_dword v176, v[180:181], off offset:192
	global_load_dword v182, v[180:181], off offset:512
	global_load_dword v152, v[180:181], off offset:576
	global_load_dword v154, v[180:181], off offset:640
	global_load_dword v158, v[180:181], off offset:704
	v_lshl_add_u64 v[172:173], v[172:173], 0, s[50:51]
	global_load_dwordx4 v[192:195], v[172:173], off
	global_load_dwordx4 v[196:199], v[172:173], off offset:256
	v_lshl_add_u64 v[172:173], v[172:173], 0, s[50:51]
	global_load_dwordx4 v[128:131], v[172:173], off
	global_load_dwordx4 v[132:135], v[172:173], off offset:256
	v_lshl_add_u64 v[172:173], v[172:173], 0, s[50:51]
	v_xor_b32_e32 v156, 16, v183
	v_xor_b32_e32 v157, 32, v183
	v_lshlrev_b32_e32 v156, 2, v156
	v_lshlrev_b32_e32 v157, 2, v157
	s_waitcnt vmcnt(4)
	v_lshlrev_b32_e32 v160, 16, v185
	v_and_b32_e32 v161, 0xffff0000, v185
	v_and_b32_e32 v185, 0xffff0000, v184
	v_lshlrev_b32_e32 v184, 16, v184
	v_lshlrev_b32_e32 v162, 16, v187
	v_and_b32_e32 v163, 0xffff0000, v187
	v_and_b32_e32 v187, 0xffff0000, v186
	v_lshlrev_b32_e32 v186, 16, v186
	v_pk_fma_f32 v[124:125], v[164:165], v[184:185], v[124:125] op_sel_hi:[0,1,1]
	v_pk_fma_f32 v[126:127], v[164:165], v[160:161], v[126:127] op_sel_hi:[0,1,1]
	v_pk_fma_f32 v[120:121], v[164:165], v[186:187], v[120:121] op_sel_hi:[0,1,1]
	v_pk_fma_f32 v[122:123], v[164:165], v[162:163], v[122:123] op_sel_hi:[0,1,1]
	v_mul_f32_e32 v168, v125, v125
	v_mul_f32_e32 v169, v127, v127
	v_fmac_f32_e32 v168, v124, v124
	v_fmac_f32_e32 v169, v126, v126
	v_add_f32_e32 v168, v168, v169
	v_mul_f32_e32 v169, v121, v121
	v_fmac_f32_e32 v169, v120, v120
	v_add_f32_e32 v168, v169, v168
	v_mul_f32_e32 v169, v123, v123
	v_fmac_f32_e32 v169, v122, v122
	v_add_f32_e32 v153, v169, v168
	v_cvt_pk_bf16_f32 v184, v124, v125
	v_cvt_pk_bf16_f32 v185, v126, v127
	v_cvt_pk_bf16_f32 v186, v120, v121
	v_cvt_pk_bf16_f32 v187, v122, v123
	global_store_dwordx4 v[174:175], v[184:187], off sc1
	v_lshlrev_b32_e32 v160, 16, v189
	v_and_b32_e32 v161, 0xffff0000, v189
	v_and_b32_e32 v189, 0xffff0000, v188
	v_lshlrev_b32_e32 v188, 16, v188
	v_lshlrev_b32_e32 v162, 16, v191
	v_and_b32_e32 v163, 0xffff0000, v191
	v_and_b32_e32 v191, 0xffff0000, v190
	v_lshlrev_b32_e32 v190, 16, v190
	v_pk_fma_f32 v[116:117], v[164:165], v[188:189], v[116:117] op_sel_hi:[0,1,1]
	v_pk_fma_f32 v[118:119], v[164:165], v[160:161], v[118:119] op_sel_hi:[0,1,1]
	v_pk_fma_f32 v[112:113], v[164:165], v[190:191], v[112:113] op_sel_hi:[0,1,1]
	v_pk_fma_f32 v[114:115], v[164:165], v[162:163], v[114:115] op_sel_hi:[0,1,1]
	v_mul_f32_e32 v168, v117, v117
	v_mul_f32_e32 v169, v119, v119
	v_fmac_f32_e32 v168, v116, v116
	v_fmac_f32_e32 v169, v118, v118
	v_add_f32_e32 v168, v168, v169
	v_mul_f32_e32 v169, v113, v113
	v_fmac_f32_e32 v169, v112, v112
	v_add_f32_e32 v168, v169, v168
	v_mul_f32_e32 v169, v115, v115
	v_fmac_f32_e32 v169, v114, v114
	v_add_f32_e32 v180, v169, v168
	v_cvt_pk_bf16_f32 v188, v116, v117
	v_cvt_pk_bf16_f32 v189, v118, v119
	v_cvt_pk_bf16_f32 v190, v112, v113
	v_cvt_pk_bf16_f32 v191, v114, v115
	global_store_dwordx4 v[174:175], v[188:191], off offset:256 sc1
	v_add_f32_e32 v180, v153, v180
	ds_bpermute_b32 v169, v156, v180
	global_load_dwordx4 v[124:127], v[172:173], off
	global_load_dwordx4 v[116:119], v[172:173], off offset:256
	s_mov_b64 s[50:51], 0x28000
	v_lshl_add_u64 v[172:173], v[172:173], 0, s[50:51]
	s_mov_b64 s[50:51], 0x8000
	v_lshl_add_u64 v[174:175], v[174:175], 0, s[50:51]
	s_waitcnt lgkmcnt(0)
	v_add_f32_e32 v180, v180, v169
	ds_bpermute_b32 v169, v157, v180
	s_waitcnt lgkmcnt(0)
	s_and_saveexec_b64 vcc, s[2:3]
	v_add_f32_e32 v180, v180, v169
	v_fma_f32 v180, v180, s66, 0.5
	v_trunc_f32_e32 v180, v180
	v_mul_f32_e32 v181, 0x2f800000, v180
	v_floor_f32_e32 v181, v181
	v_fmac_f32_e32 v180, 0xcf800000, v181
	v_cvt_u32_f32_e32 v181, v181
	v_cvt_u32_f32_e32 v180, v180
	v_add_u32_e32 v181, 0x10000, v181
	global_atomic_add_x2 v[178:179], v[180:181], off
	s_mov_b64 exec, vcc
	s_waitcnt vmcnt(7)
; __device__ __forceinline__ unsigned cvt_pk_bf16(float lo, float hi) { unsigned r; asm volatile("v_cvt_pk_bf16_f32 %0, %1, %2" : "=v"(r) : "v"(lo), "v"(hi)); return r; }
;     __device__ __forceinline__ void operator()(const f32x4 (&acc)[2][2][4][2], const Unit& u, int wr, int wc, int fr, int fq) const {
;     ...
;         for (int st = 0; st < 8; ++st) { const int ai = st >> 2, m = st & 3; const int row = row0 + ai * HALF + m * 16;
;             if (st < 7) { const int rn = row0 + ((st + 1) >> 2) * HALF + ((st + 1) & 3) * 16; const size_t off = (size_t)rn * 1024 + col0; u32x4* p = pre[(st + 1) & 1];
;                 p[0] = *(const u32x4*)(xb + off); p[1] = *(const u32x4*)(xb + off + HALF); }
;             __builtin_amdgcn_sched_barrier(0);
;             float s = 0.f; const float r = rs[st];
; #pragma unroll
;             for (int bj = 0; bj < 2; ++bj) { const size_t off = (size_t)row * 1024 + col0 + bj * HALF; const u32x4 h = pre[st & 1][bj];
;                 const f32x4 x0 = (f32x4){__uint_as_float(h.x << 16), __uint_as_float(h.x & 0xffff0000u), __uint_as_float(h.y << 16), __uint_as_float(h.y & 0xffff0000u)};
;                 const f32x4 x1v = (f32x4){__uint_as_float(h.z << 16), __uint_as_float(h.z & 0xffff0000u), __uint_as_float(h.w << 16), __uint_as_float(h.w & 0xffff0000u)};
;                 const f32x4 v0 = acc[ai][bj][m][0] + x0 * r, v1 = acc[ai][bj][m][1] + x1v * r;
;                 u32x4 w; w.x = cvt_pk_bf16(v0[0], v0[1]); w.y = cvt_pk_bf16(v0[2], v0[3]); w.z = cvt_pk_bf16(v1[0], v1[1]); w.w = cvt_pk_bf16(v1[2], v1[3]);
;                 *(u32x4*)(xb + off) = w;
;                 s += (v0[0] * v0[0] + v0[1] * v0[1]) + (v0[2] * v0[2] + v0[3] * v0[3]) + (v1[0] * v1[0] + v1[1] * v1[1]) + (v1[2] * v1[2] + v1[3] * v1[3]); }
;             s += __shfl_xor(s, 16); s += __shfl_xor(s, 32);
;             if (fq == 0) (void)__hip_atomic_fetch_add(racc + row, (1ull << 48) + (unsigned long long)(s * 65536.0f + 0.5f), __ATOMIC_RELAXED, __HIP_MEMORY_SCOPE_AGENT);
;             __builtin_amdgcn_sched_barrier(0); }
	v_lshlrev_b32_e32 v160, 16, v193
	v_and_b32_e32 v161, 0xffff0000, v193
	v_and_b32_e32 v193, 0xffff0000, v192
	v_lshlrev_b32_e32 v192, 16, v192
	v_lshlrev_b32_e32 v162, 16, v195
	v_and_b32_e32 v163, 0xffff0000, v195
	v_and_b32_e32 v195, 0xffff0000, v194
	v_lshlrev_b32_e32 v194, 16, v194
	v_pk_fma_f32 v[108:109], v[166:167], v[192:193], v[108:109] op_sel_hi:[0,1,1]
	v_pk_fma_f32 v[110:111], v[166:167], v[160:161], v[110:111] op_sel_hi:[0,1,1]
	v_pk_fma_f32 v[104:105], v[166:167], v[194:195], v[104:105] op_sel_hi:[0,1,1]
	v_pk_fma_f32 v[106:107], v[166:167], v[162:163], v[106:107] op_sel_hi:[0,1,1]
	v_mul_f32_e32 v168, v109, v109
	v_mul_f32_e32 v169, v111, v111
	v_fmac_f32_e32 v168, v108, v108
	v_fmac_f32_e32 v169, v110, v110
	v_add_f32_e32 v168, v168, v169
	v_mul_f32_e32 v169, v105, v105
	v_fmac_f32_e32 v169, v104, v104
	v_add_f32_e32 v168, v169, v168
	v_mul_f32_e32 v169, v107, v107
	v_fmac_f32_e32 v169, v106, v106
	v_add_f32_e32 v153, v169, v168
	v_cvt_pk_bf16_f32 v192, v108, v109
	v_cvt_pk_bf16_f32 v193, v110, v111
	v_cvt_pk_bf16_f32 v194, v104, v105
	v_cvt_pk_bf16_f32 v195, v106, v107
	global_store_dwordx4 v[174:175], v[192:195], off sc1
	v_lshlrev_b32_e32 v160, 16, v197
	v_and_b32_e32 v161, 0xffff0000, v197
	v_and_b32_e32 v197, 0xffff0000, v196
	v_lshlrev_b32_e32 v196, 16, v196
	v_lshlrev_b32_e32 v162, 16, v199
	v_and_b32_e32 v163, 0xffff0000, v199
	v_and_b32_e32 v199, 0xffff0000, v198
	v_lshlrev_b32_e32 v198, 16, v198
	v_pk_fma_f32 v[100:101], v[166:167], v[196:197], v[100:101] op_sel_hi:[0,1,1]
	v_pk_fma_f32 v[102:103], v[166:167], v[160:161], v[102:103] op_sel_hi:[0,1,1]
	v_pk_fma_f32 v[96:97], v[166:167], v[198:199], v[96:97] op_sel_hi:[0,1,1]
	v_pk_fma_f32 v[98:99], v[166:167], v[162:163], v[98:99] op_sel_hi:[0,1,1]
	v_mul_f32_e32 v168, v101, v101
	v_mul_f32_e32 v169, v103, v103
	v_fmac_f32_e32 v168, v100, v100
	v_fmac_f32_e32 v169, v102, v102
	v_add_f32_e32 v168, v168, v169
	v_mul_f32_e32 v169, v97, v97
	v_fmac_f32_e32 v169, v96, v96
	v_add_f32_e32 v168, v169, v168
	v_mul_f32_e32 v169, v99, v99
	v_fmac_f32_e32 v169, v98, v98
	v_add_f32_e32 v180, v169, v168
	v_cvt_pk_bf16_f32 v196, v100, v101
	v_cvt_pk_bf16_f32 v197, v102, v103
	v_cvt_pk_bf16_f32 v198, v96, v97
	v_cvt_pk_bf16_f32 v199, v98, v99
	global_store_dwordx4 v[174:175], v[196:199], off offset:256 sc1
	v_add_f32_e32 v180, v153, v180
	ds_bpermute_b32 v169, v156, v180
	global_load_dwordx4 v[108:111], v[172:173], off
	global_load_dwordx4 v[100:103], v[172:173], off offset:256
	v_lshl_add_u64 v[172:173], v[172:173], 0, s[50:51]
	v_lshl_add_u64 v[174:175], v[174:175], 0, s[50:51]
	s_waitcnt lgkmcnt(0)
	v_add_f32_e32 v180, v180, v169
	ds_bpermute_b32 v169, v157, v180
	s_waitcnt lgkmcnt(0)
	s_and_saveexec_b64 vcc, s[2:3]
	v_add_f32_e32 v180, v180, v169
	v_fma_f32 v180, v180, s66, 0.5
	v_trunc_f32_e32 v180, v180
	v_mul_f32_e32 v181, 0x2f800000, v180
	v_floor_f32_e32 v181, v181
	v_fmac_f32_e32 v180, 0xcf800000, v181
	v_cvt_u32_f32_e32 v181, v181
	v_cvt_u32_f32_e32 v180, v180
	v_add_u32_e32 v181, 0x10000, v181
	global_atomic_add_x2 v[178:179], v[180:181], off offset:128
	s_mov_b64 exec, vcc
	s_waitcnt vmcnt(10)
	v_lshlrev_b32_e32 v160, 16, v129
	v_and_b32_e32 v161, 0xffff0000, v129
	v_and_b32_e32 v129, 0xffff0000, v128
	v_lshlrev_b32_e32 v128, 16, v128
	v_lshlrev_b32_e32 v162, 16, v131
	v_and_b32_e32 v163, 0xffff0000, v131
	v_and_b32_e32 v131, 0xffff0000, v130
	v_lshlrev_b32_e32 v130, 16, v130
	v_pk_fma_f32 v[92:93], v[170:171], v[128:129], v[92:93] op_sel_hi:[0,1,1]
	v_pk_fma_f32 v[94:95], v[170:171], v[160:161], v[94:95] op_sel_hi:[0,1,1]
	v_pk_fma_f32 v[88:89], v[170:171], v[130:131], v[88:89] op_sel_hi:[0,1,1]
	v_pk_fma_f32 v[90:91], v[170:171], v[162:163], v[90:91] op_sel_hi:[0,1,1]
	v_mul_f32_e32 v168, v93, v93
	v_mul_f32_e32 v169, v95, v95
	v_fmac_f32_e32 v168, v92, v92
	v_fmac_f32_e32 v169, v94, v94
	v_add_f32_e32 v168, v168, v169
	v_mul_f32_e32 v169, v89, v89
	v_fmac_f32_e32 v169, v88, v88
	v_add_f32_e32 v168, v169, v168
	v_mul_f32_e32 v169, v91, v91
	v_fmac_f32_e32 v169, v90, v90
	v_add_f32_e32 v153, v169, v168
	v_cvt_pk_bf16_f32 v128, v92, v93
	v_cvt_pk_bf16_f32 v129, v94, v95
	v_cvt_pk_bf16_f32 v130, v88, v89
	v_cvt_pk_bf16_f32 v131, v90, v91
	global_store_dwordx4 v[174:175], v[128:131], off sc1
	v_lshlrev_b32_e32 v160, 16, v133
	v_and_b32_e32 v161, 0xffff0000, v133
	v_and_b32_e32 v133, 0xffff0000, v132
	v_lshlrev_b32_e32 v132, 16, v132
	v_lshlrev_b32_e32 v162, 16, v135
	v_and_b32_e32 v163, 0xffff0000, v135
	v_and_b32_e32 v135, 0xffff0000, v134
	v_lshlrev_b32_e32 v134, 16, v134
	v_pk_fma_f32 v[84:85], v[170:171], v[132:133], v[84:85] op_sel_hi:[0,1,1]
	v_pk_fma_f32 v[86:87], v[170:171], v[160:161], v[86:87] op_sel_hi:[0,1,1]
	v_pk_fma_f32 v[80:81], v[170:171], v[134:135], v[80:81] op_sel_hi:[0,1,1]
	v_pk_fma_f32 v[82:83], v[170:171], v[162:163], v[82:83] op_sel_hi:[0,1,1]
	v_mul_f32_e32 v168, v85, v85
	v_mul_f32_e32 v169, v87, v87
	v_fmac_f32_e32 v168, v84, v84
	v_fmac_f32_e32 v169, v86, v86
	v_add_f32_e32 v168, v168, v169
	v_mul_f32_e32 v169, v81, v81
	v_fmac_f32_e32 v169, v80, v80
	v_add_f32_e32 v168, v169, v168
	v_mul_f32_e32 v169, v83, v83
	v_fmac_f32_e32 v169, v82, v82
	v_add_f32_e32 v180, v169, v168
	v_cvt_pk_bf16_f32 v132, v84, v85
	v_cvt_pk_bf16_f32 v133, v86, v87
	v_cvt_pk_bf16_f32 v134, v80, v81
	v_cvt_pk_bf16_f32 v135, v82, v83
	global_store_dwordx4 v[174:175], v[132:135], off offset:256 sc1
	v_add_f32_e32 v180, v153, v180
	ds_bpermute_b32 v169, v156, v180
	global_load_dwordx4 v[92:95], v[172:173], off
	global_load_dwordx4 v[84:87], v[172:173], off offset:256
	v_lshl_add_u64 v[172:173], v[172:173], 0, s[50:51]
	v_lshl_add_u64 v[174:175], v[174:175], 0, s[50:51]
	s_waitcnt lgkmcnt(0)
; __device__ __forceinline__ unsigned cvt_pk_bf16(float lo, float hi) { unsigned r; asm volatile("v_cvt_pk_bf16_f32 %0, %1, %2" : "=v"(r) : "v"(lo), "v"(hi)); return r; }
;     __device__ __forceinline__ void operator()(const f32x4 (&acc)[2][2][4][2], const Unit& u, int wr, int wc, int fr, int fq) const {
;     ...
;         for (int st = 0; st < 8; ++st) { const int ai = st >> 2, m = st & 3; const int row = row0 + ai * HALF + m * 16;
;             if (st < 7) { const int rn = row0 + ((st + 1) >> 2) * HALF + ((st + 1) & 3) * 16; const size_t off = (size_t)rn * 1024 + col0; u32x4* p = pre[(st + 1) & 1];
;                 p[0] = *(const u32x4*)(xb + off); p[1] = *(const u32x4*)(xb + off + HALF); }
;             __builtin_amdgcn_sched_barrier(0);
;             float s = 0.f; const float r = rs[st];
; #pragma unroll
;             for (int bj = 0; bj < 2; ++bj) { const size_t off = (size_t)row * 1024 + col0 + bj * HALF; const u32x4 h = pre[st & 1][bj];
;                 const f32x4 x0 = (f32x4){__uint_as_float(h.x << 16), __uint_as_float(h.x & 0xffff0000u), __uint_as_float(h.y << 16), __uint_as_float(h.y & 0xffff0000u)};
;                 const f32x4 x1v = (f32x4){__uint_as_float(h.z << 16), __uint_as_float(h.z & 0xffff0000u), __uint_as_float(h.w << 16), __uint_as_float(h.w & 0xffff0000u)};
;                 const f32x4 v0 = acc[ai][bj][m][0] + x0 * r, v1 = acc[ai][bj][m][1] + x1v * r;
;                 u32x4 w; w.x = cvt_pk_bf16(v0[0], v0[1]); w.y = cvt_pk_bf16(v0[2], v0[3]); w.z = cvt_pk_bf16(v1[0], v1[1]); w.w = cvt_pk_bf16(v1[2], v1[3]);
;                 *(u32x4*)(xb + off) = w;
;                 s += (v0[0] * v0[0] + v0[1] * v0[1]) + (v0[2] * v0[2] + v0[3] * v0[3]) + (v1[0] * v1[0] + v1[1] * v1[1]) + (v1[2] * v1[2] + v1[3] * v1[3]); }
;             s += __shfl_xor(s, 16); s += __shfl_xor(s, 32);
;             if (fq == 0) (void)__hip_atomic_fetch_add(racc + row, (1ull << 48) + (unsigned long long)(s * 65536.0f + 0.5f), __ATOMIC_RELAXED, __HIP_MEMORY_SCOPE_AGENT);
	v_add_f32_e32 v180, v180, v169
	ds_bpermute_b32 v169, v157, v180
	s_waitcnt lgkmcnt(0)
	s_and_saveexec_b64 vcc, s[2:3]
	v_add_f32_e32 v180, v180, v169
	v_fma_f32 v180, v180, s66, 0.5
	v_trunc_f32_e32 v180, v180
	v_mul_f32_e32 v181, 0x2f800000, v180
	v_floor_f32_e32 v181, v181
	v_fmac_f32_e32 v180, 0xcf800000, v181
	v_cvt_u32_f32_e32 v181, v181
	v_cvt_u32_f32_e32 v180, v180
	v_add_u32_e32 v181, 0x10000, v181
	global_atomic_add_x2 v[178:179], v[180:181], off offset:256
	s_mov_b64 exec, vcc
	s_waitcnt vmcnt(11)
	v_lshlrev_b32_e32 v160, 16, v125
	v_and_b32_e32 v161, 0xffff0000, v125
	v_and_b32_e32 v125, 0xffff0000, v124
	v_lshlrev_b32_e32 v124, 16, v124
	v_lshlrev_b32_e32 v162, 16, v127
	v_and_b32_e32 v163, 0xffff0000, v127
	v_and_b32_e32 v127, 0xffff0000, v126
	v_lshlrev_b32_e32 v126, 16, v126
	v_pk_fma_f32 v[76:77], v[176:177], v[124:125], v[76:77] op_sel_hi:[0,1,1]
	v_pk_fma_f32 v[78:79], v[176:177], v[160:161], v[78:79] op_sel_hi:[0,1,1]
	v_pk_fma_f32 v[72:73], v[176:177], v[126:127], v[72:73] op_sel_hi:[0,1,1]
	v_pk_fma_f32 v[74:75], v[176:177], v[162:163], v[74:75] op_sel_hi:[0,1,1]
	v_mul_f32_e32 v168, v77, v77
	v_mul_f32_e32 v169, v79, v79
	v_fmac_f32_e32 v168, v76, v76
	v_fmac_f32_e32 v169, v78, v78
	v_add_f32_e32 v168, v168, v169
	v_mul_f32_e32 v169, v73, v73
	v_fmac_f32_e32 v169, v72, v72
	v_add_f32_e32 v168, v169, v168
	v_mul_f32_e32 v169, v75, v75
	v_fmac_f32_e32 v169, v74, v74
	v_add_f32_e32 v153, v169, v168
	v_cvt_pk_bf16_f32 v124, v76, v77
	v_cvt_pk_bf16_f32 v125, v78, v79
	v_cvt_pk_bf16_f32 v126, v72, v73
	v_cvt_pk_bf16_f32 v127, v74, v75
	global_store_dwordx4 v[174:175], v[124:127], off sc1
	v_lshlrev_b32_e32 v160, 16, v117
	v_and_b32_e32 v161, 0xffff0000, v117
	v_and_b32_e32 v117, 0xffff0000, v116
	v_lshlrev_b32_e32 v116, 16, v116
	v_lshlrev_b32_e32 v162, 16, v119
	v_and_b32_e32 v163, 0xffff0000, v119
	v_and_b32_e32 v119, 0xffff0000, v118
	v_lshlrev_b32_e32 v118, 16, v118
	v_pk_fma_f32 v[68:69], v[176:177], v[116:117], v[68:69] op_sel_hi:[0,1,1]
	v_pk_fma_f32 v[70:71], v[176:177], v[160:161], v[70:71] op_sel_hi:[0,1,1]
	v_pk_fma_f32 v[64:65], v[176:177], v[118:119], v[64:65] op_sel_hi:[0,1,1]
	v_pk_fma_f32 v[66:67], v[176:177], v[162:163], v[66:67] op_sel_hi:[0,1,1]
	v_mul_f32_e32 v168, v69, v69
	v_mul_f32_e32 v169, v71, v71
	v_fmac_f32_e32 v168, v68, v68
	v_fmac_f32_e32 v169, v70, v70
	v_add_f32_e32 v168, v168, v169
	v_mul_f32_e32 v169, v65, v65
	v_fmac_f32_e32 v169, v64, v64
	v_add_f32_e32 v168, v169, v168
	v_mul_f32_e32 v169, v67, v67
	v_fmac_f32_e32 v169, v66, v66
	v_add_f32_e32 v180, v169, v168
	v_cvt_pk_bf16_f32 v116, v68, v69
	v_cvt_pk_bf16_f32 v117, v70, v71
	v_cvt_pk_bf16_f32 v118, v64, v65
	v_cvt_pk_bf16_f32 v119, v66, v67
	global_store_dwordx4 v[174:175], v[116:119], off offset:256 sc1
	v_add_f32_e32 v180, v153, v180
	ds_bpermute_b32 v169, v156, v180
	global_load_dwordx4 v[76:79], v[172:173], off
	global_load_dwordx4 v[68:71], v[172:173], off offset:256
	v_lshl_add_u64 v[172:173], v[172:173], 0, s[50:51]
	s_mov_b64 s[50:51], 0x28000
	v_lshl_add_u64 v[174:175], v[174:175], 0, s[50:51]
	s_mov_b64 s[50:51], 0x8000
	s_waitcnt lgkmcnt(0)
	v_add_f32_e32 v180, v180, v169
	ds_bpermute_b32 v169, v157, v180
	s_waitcnt lgkmcnt(0)
	s_and_saveexec_b64 vcc, s[2:3]
	v_add_f32_e32 v180, v180, v169
	v_fma_f32 v180, v180, s66, 0.5
	v_trunc_f32_e32 v180, v180
	v_mul_f32_e32 v181, 0x2f800000, v180
	v_floor_f32_e32 v181, v181
	v_fmac_f32_e32 v180, 0xcf800000, v181
	v_cvt_u32_f32_e32 v181, v181
	v_cvt_u32_f32_e32 v180, v180
	v_add_u32_e32 v181, 0x10000, v181
	global_atomic_add_x2 v[178:179], v[180:181], off offset:384
	s_mov_b64 exec, vcc
	s_waitcnt vmcnt(11)
	v_lshlrev_b32_e32 v160, 16, v109
	v_and_b32_e32 v161, 0xffff0000, v109
	v_and_b32_e32 v109, 0xffff0000, v108
	v_lshlrev_b32_e32 v108, 16, v108
	v_lshlrev_b32_e32 v162, 16, v111
	v_and_b32_e32 v163, 0xffff0000, v111
	v_and_b32_e32 v111, 0xffff0000, v110
	v_lshlrev_b32_e32 v110, 16, v110
	v_pk_fma_f32 v[60:61], v[182:183], v[108:109], v[60:61] op_sel_hi:[0,1,1]
	v_pk_fma_f32 v[62:63], v[182:183], v[160:161], v[62:63] op_sel_hi:[0,1,1]
	v_pk_fma_f32 v[56:57], v[182:183], v[110:111], v[56:57] op_sel_hi:[0,1,1]
	v_pk_fma_f32 v[58:59], v[182:183], v[162:163], v[58:59] op_sel_hi:[0,1,1]
	v_mul_f32_e32 v168, v61, v61
	v_mul_f32_e32 v169, v63, v63
	v_fmac_f32_e32 v168, v60, v60
	v_fmac_f32_e32 v169, v62, v62
	v_add_f32_e32 v168, v168, v169
	v_mul_f32_e32 v169, v57, v57
	v_fmac_f32_e32 v169, v56, v56
	v_add_f32_e32 v168, v169, v168
	v_mul_f32_e32 v169, v59, v59
	v_fmac_f32_e32 v169, v58, v58
	v_add_f32_e32 v153, v169, v168
	v_cvt_pk_bf16_f32 v108, v60, v61
	v_cvt_pk_bf16_f32 v109, v62, v63
	v_cvt_pk_bf16_f32 v110, v56, v57
	v_cvt_pk_bf16_f32 v111, v58, v59
	global_store_dwordx4 v[174:175], v[108:111], off sc1
	v_lshlrev_b32_e32 v160, 16, v101
	v_and_b32_e32 v161, 0xffff0000, v101
	v_and_b32_e32 v101, 0xffff0000, v100
	v_lshlrev_b32_e32 v100, 16, v100
	v_lshlrev_b32_e32 v162, 16, v103
	v_and_b32_e32 v163, 0xffff0000, v103
	v_and_b32_e32 v103, 0xffff0000, v102
	v_lshlrev_b32_e32 v102, 16, v102
	v_pk_fma_f32 v[52:53], v[182:183], v[100:101], v[52:53] op_sel_hi:[0,1,1]
	v_pk_fma_f32 v[54:55], v[182:183], v[160:161], v[54:55] op_sel_hi:[0,1,1]
	v_pk_fma_f32 v[48:49], v[182:183], v[102:103], v[48:49] op_sel_hi:[0,1,1]
	v_pk_fma_f32 v[50:51], v[182:183], v[162:163], v[50:51] op_sel_hi:[0,1,1]
	v_mul_f32_e32 v168, v53, v53
	v_mul_f32_e32 v169, v55, v55
	v_fmac_f32_e32 v168, v52, v52
	v_fmac_f32_e32 v169, v54, v54
	v_add_f32_e32 v168, v168, v169
	v_mul_f32_e32 v169, v49, v49
	v_fmac_f32_e32 v169, v48, v48
	v_add_f32_e32 v168, v169, v168
	v_mul_f32_e32 v169, v51, v51
	v_fmac_f32_e32 v169, v50, v50
	v_add_f32_e32 v180, v169, v168
	v_cvt_pk_bf16_f32 v100, v52, v53
	v_cvt_pk_bf16_f32 v101, v54, v55
	v_cvt_pk_bf16_f32 v102, v48, v49
	v_cvt_pk_bf16_f32 v103, v50, v51
	global_store_dwordx4 v[174:175], v[100:103], off offset:256 sc1
	v_add_f32_e32 v180, v153, v180
	ds_bpermute_b32 v169, v156, v180
	global_load_dwordx4 v[60:63], v[172:173], off
	global_load_dwordx4 v[52:55], v[172:173], off offset:256
	v_lshl_add_u64 v[174:175], v[174:175], 0, s[50:51]
	s_waitcnt lgkmcnt(0)
; __device__ __forceinline__ unsigned cvt_pk_bf16(float lo, float hi) { unsigned r; asm volatile("v_cvt_pk_bf16_f32 %0, %1, %2" : "=v"(r) : "v"(lo), "v"(hi)); return r; }
;     __device__ __forceinline__ void operator()(const f32x4 (&acc)[2][2][4][2], const Unit& u, int wr, int wc, int fr, int fq) const {
;     ...
;         for (int st = 0; st < 8; ++st) { const int ai = st >> 2, m = st & 3; const int row = row0 + ai * HALF + m * 16;
;             if (st < 7) { const int rn = row0 + ((st + 1) >> 2) * HALF + ((st + 1) & 3) * 16; const size_t off = (size_t)rn * 1024 + col0; u32x4* p = pre[(st + 1) & 1];
;                 p[0] = *(const u32x4*)(xb + off); p[1] = *(const u32x4*)(xb + off + HALF); }
;             __builtin_amdgcn_sched_barrier(0);
;             float s = 0.f; const float r = rs[st];
; #pragma unroll
;             for (int bj = 0; bj < 2; ++bj) { const size_t off = (size_t)row * 1024 + col0 + bj * HALF; const u32x4 h = pre[st & 1][bj];
;                 const f32x4 x0 = (f32x4){__uint_as_float(h.x << 16), __uint_as_float(h.x & 0xffff0000u), __uint_as_float(h.y << 16), __uint_as_float(h.y & 0xffff0000u)};
;                 const f32x4 x1v = (f32x4){__uint_as_float(h.z << 16), __uint_as_float(h.z & 0xffff0000u), __uint_as_float(h.w << 16), __uint_as_float(h.w & 0xffff0000u)};
;                 const f32x4 v0 = acc[ai][bj][m][0] + x0 * r, v1 = acc[ai][bj][m][1] + x1v * r;
;                 u32x4 w; w.x = cvt_pk_bf16(v0[0], v0[1]); w.y = cvt_pk_bf16(v0[2], v0[3]); w.z = cvt_pk_bf16(v1[0], v1[1]); w.w = cvt_pk_bf16(v1[2], v1[3]);
;                 *(u32x4*)(xb + off) = w;
;                 s += (v0[0] * v0[0] + v0[1] * v0[1]) + (v0[2] * v0[2] + v0[3] * v0[3]) + (v1[0] * v1[0] + v1[1] * v1[1]) + (v1[2] * v1[2] + v1[3] * v1[3]); }
;             s += __shfl_xor(s, 16); s += __shfl_xor(s, 32);
;             if (fq == 0) (void)__hip_atomic_fetch_add(racc + row, (1ull << 48) + (unsigned long long)(s * 65536.0f + 0.5f), __ATOMIC_RELAXED, __HIP_MEMORY_SCOPE_AGENT);
	v_add_f32_e32 v180, v180, v169
	ds_bpermute_b32 v169, v157, v180
	s_waitcnt lgkmcnt(0)
	s_and_saveexec_b64 vcc, s[2:3]
	v_add_f32_e32 v180, v180, v169
	v_fma_f32 v180, v180, s66, 0.5
	v_trunc_f32_e32 v180, v180
	v_mul_f32_e32 v181, 0x2f800000, v180
	v_floor_f32_e32 v181, v181
	v_fmac_f32_e32 v180, 0xcf800000, v181
	v_cvt_u32_f32_e32 v181, v181
	v_cvt_u32_f32_e32 v180, v180
	v_add_u32_e32 v181, 0x10000, v181
	global_atomic_add_x2 v[178:179], v[180:181], off offset:1024
	s_mov_b64 exec, vcc
	s_waitcnt vmcnt(11)
	v_lshlrev_b32_e32 v160, 16, v93
	v_and_b32_e32 v161, 0xffff0000, v93
	v_and_b32_e32 v93, 0xffff0000, v92
	v_lshlrev_b32_e32 v92, 16, v92
	v_lshlrev_b32_e32 v162, 16, v95
	v_and_b32_e32 v163, 0xffff0000, v95
	v_and_b32_e32 v95, 0xffff0000, v94
	v_lshlrev_b32_e32 v94, 16, v94
	v_pk_fma_f32 v[44:45], v[152:153], v[92:93], v[44:45] op_sel_hi:[0,1,1]
	v_pk_fma_f32 v[46:47], v[152:153], v[160:161], v[46:47] op_sel_hi:[0,1,1]
	v_pk_fma_f32 v[40:41], v[152:153], v[94:95], v[40:41] op_sel_hi:[0,1,1]
	v_pk_fma_f32 v[42:43], v[152:153], v[162:163], v[42:43] op_sel_hi:[0,1,1]
	v_mul_f32_e32 v168, v45, v45
	v_mul_f32_e32 v169, v47, v47
	v_fmac_f32_e32 v168, v44, v44
	v_fmac_f32_e32 v169, v46, v46
	v_add_f32_e32 v168, v168, v169
	v_mul_f32_e32 v169, v41, v41
	v_fmac_f32_e32 v169, v40, v40
	v_add_f32_e32 v168, v169, v168
	v_mul_f32_e32 v169, v43, v43
	v_fmac_f32_e32 v169, v42, v42
	v_add_f32_e32 v153, v169, v168
	v_cvt_pk_bf16_f32 v92, v44, v45
	v_cvt_pk_bf16_f32 v93, v46, v47
	v_cvt_pk_bf16_f32 v94, v40, v41
	v_cvt_pk_bf16_f32 v95, v42, v43
	global_store_dwordx4 v[174:175], v[92:95], off sc1
	v_lshlrev_b32_e32 v160, 16, v85
	v_and_b32_e32 v161, 0xffff0000, v85
	v_and_b32_e32 v85, 0xffff0000, v84
	v_lshlrev_b32_e32 v84, 16, v84
	v_lshlrev_b32_e32 v162, 16, v87
	v_and_b32_e32 v163, 0xffff0000, v87
	v_and_b32_e32 v87, 0xffff0000, v86
	v_lshlrev_b32_e32 v86, 16, v86
	v_pk_fma_f32 v[36:37], v[152:153], v[84:85], v[36:37] op_sel_hi:[0,1,1]
	v_pk_fma_f32 v[38:39], v[152:153], v[160:161], v[38:39] op_sel_hi:[0,1,1]
	v_pk_fma_f32 v[32:33], v[152:153], v[86:87], v[32:33] op_sel_hi:[0,1,1]
	v_pk_fma_f32 v[34:35], v[152:153], v[162:163], v[34:35] op_sel_hi:[0,1,1]
	v_mul_f32_e32 v168, v37, v37
	v_mul_f32_e32 v169, v39, v39
	v_fmac_f32_e32 v168, v36, v36
	v_fmac_f32_e32 v169, v38, v38
	v_add_f32_e32 v168, v168, v169
	v_mul_f32_e32 v169, v33, v33
	v_fmac_f32_e32 v169, v32, v32
	v_add_f32_e32 v168, v169, v168
	v_mul_f32_e32 v169, v35, v35
	v_fmac_f32_e32 v169, v34, v34
	v_add_f32_e32 v180, v169, v168
	v_cvt_pk_bf16_f32 v84, v36, v37
	v_cvt_pk_bf16_f32 v85, v38, v39
	v_cvt_pk_bf16_f32 v86, v32, v33
	v_cvt_pk_bf16_f32 v87, v34, v35
	global_store_dwordx4 v[174:175], v[84:87], off offset:256 sc1
	v_add_f32_e32 v180, v153, v180
	ds_bpermute_b32 v169, v156, v180
	v_lshl_add_u64 v[174:175], v[174:175], 0, s[50:51]
	s_waitcnt lgkmcnt(0)
	v_add_f32_e32 v180, v180, v169
	ds_bpermute_b32 v169, v157, v180
	s_waitcnt lgkmcnt(0)
	s_and_saveexec_b64 vcc, s[2:3]
	v_add_f32_e32 v180, v180, v169
	v_fma_f32 v180, v180, s66, 0.5
	v_trunc_f32_e32 v180, v180
	v_mul_f32_e32 v181, 0x2f800000, v180
	v_floor_f32_e32 v181, v181
	v_fmac_f32_e32 v180, 0xcf800000, v181
	v_cvt_u32_f32_e32 v181, v181
	v_cvt_u32_f32_e32 v180, v180
	v_add_u32_e32 v181, 0x10000, v181
	global_atomic_add_x2 v[178:179], v[180:181], off offset:1152
	s_mov_b64 exec, vcc
	s_waitcnt vmcnt(9)
	v_lshlrev_b32_e32 v160, 16, v77
	v_and_b32_e32 v161, 0xffff0000, v77
	v_and_b32_e32 v77, 0xffff0000, v76
	v_lshlrev_b32_e32 v76, 16, v76
	v_lshlrev_b32_e32 v162, 16, v79
	v_and_b32_e32 v163, 0xffff0000, v79
	v_and_b32_e32 v79, 0xffff0000, v78
	v_lshlrev_b32_e32 v78, 16, v78
	v_pk_fma_f32 v[28:29], v[154:155], v[76:77], v[28:29] op_sel_hi:[0,1,1]
	v_pk_fma_f32 v[30:31], v[154:155], v[160:161], v[30:31] op_sel_hi:[0,1,1]
	v_pk_fma_f32 v[24:25], v[154:155], v[78:79], v[24:25] op_sel_hi:[0,1,1]
	v_pk_fma_f32 v[26:27], v[154:155], v[162:163], v[26:27] op_sel_hi:[0,1,1]
	v_mul_f32_e32 v168, v29, v29
	v_mul_f32_e32 v169, v31, v31
	v_fmac_f32_e32 v168, v28, v28
	v_fmac_f32_e32 v169, v30, v30
	v_add_f32_e32 v168, v168, v169
	v_mul_f32_e32 v169, v25, v25
	v_fmac_f32_e32 v169, v24, v24
	v_add_f32_e32 v168, v169, v168
	v_mul_f32_e32 v169, v27, v27
	v_fmac_f32_e32 v169, v26, v26
	v_add_f32_e32 v153, v169, v168
	v_cvt_pk_bf16_f32 v76, v28, v29
	v_cvt_pk_bf16_f32 v77, v30, v31
	v_cvt_pk_bf16_f32 v78, v24, v25
	v_cvt_pk_bf16_f32 v79, v26, v27
	global_store_dwordx4 v[174:175], v[76:79], off sc1
	v_lshlrev_b32_e32 v160, 16, v69
	v_and_b32_e32 v161, 0xffff0000, v69
	v_and_b32_e32 v69, 0xffff0000, v68
	v_lshlrev_b32_e32 v68, 16, v68
	v_lshlrev_b32_e32 v162, 16, v71
	v_and_b32_e32 v163, 0xffff0000, v71
	v_and_b32_e32 v71, 0xffff0000, v70
	v_lshlrev_b32_e32 v70, 16, v70
	v_pk_fma_f32 v[20:21], v[154:155], v[68:69], v[20:21] op_sel_hi:[0,1,1]
	v_pk_fma_f32 v[22:23], v[154:155], v[160:161], v[22:23] op_sel_hi:[0,1,1]
	v_pk_fma_f32 v[16:17], v[154:155], v[70:71], v[16:17] op_sel_hi:[0,1,1]
	v_pk_fma_f32 v[18:19], v[154:155], v[162:163], v[18:19] op_sel_hi:[0,1,1]
	v_mul_f32_e32 v168, v21, v21
	v_mul_f32_e32 v169, v23, v23
	v_fmac_f32_e32 v168, v20, v20
	v_fmac_f32_e32 v169, v22, v22
	v_add_f32_e32 v168, v168, v169
	v_mul_f32_e32 v169, v17, v17
	v_fmac_f32_e32 v169, v16, v16
	v_add_f32_e32 v168, v169, v168
	v_mul_f32_e32 v169, v19, v19
	v_fmac_f32_e32 v169, v18, v18
	v_add_f32_e32 v180, v169, v168
	v_cvt_pk_bf16_f32 v68, v20, v21
	v_cvt_pk_bf16_f32 v69, v22, v23
	v_cvt_pk_bf16_f32 v70, v16, v17
	v_cvt_pk_bf16_f32 v71, v18, v19
	global_store_dwordx4 v[174:175], v[68:71], off offset:256 sc1
	v_add_f32_e32 v180, v153, v180
	ds_bpermute_b32 v169, v156, v180
	v_lshl_add_u64 v[174:175], v[174:175], 0, s[50:51]
	s_waitcnt lgkmcnt(0)
; #define PG8_BAR __builtin_amdgcn_s_barrier()
; template <class Epi, class Sched, bool ALIGN_EPI = false, bool SP2 = false>
; __device__ __forceinline__ void gemm_phase(PG8_LAS unsigned char* lds, const Gemm g, const Sched& S, const Epi& E) {
;     ...
;         cur = nxt; cA = nA; cB = nB; ++ui;
;         if constexpr (epi_prefetches<Epi>::value) E.prefetch(cur, ui, wid);
;         if constexpr (ALIGN_EPI) { if (wr == 1) PG8_BAR; }
;     __device__ __forceinline__ void operator()(const f32x4 (&acc)[2][2][4][2], const Unit& u, int wr, int wc, int fr, int fq) const {
;     ...
;         for (int st = 0; st < 8; ++st) { const int ai = st >> 2, m = st & 3; const int row = row0 + ai * HALF + m * 16;
;             if (st < 7) { const int rn = row0 + ((st + 1) >> 2) * HALF + ((st + 1) & 3) * 16; const size_t off = (size_t)rn * 1024 + col0; u32x4* p = pre[(st + 1) & 1];
;                 p[0] = *(const u32x4*)(xb + off); p[1] = *(const u32x4*)(xb + off + HALF); }
;             __builtin_amdgcn_sched_barrier(0);
;             float s = 0.f; const float r = rs[st];
; #pragma unroll
;             for (int bj = 0; bj < 2; ++bj) { const size_t off = (size_t)row * 1024 + col0 + bj * HALF; const u32x4 h = pre[st & 1][bj];
;                 const f32x4 x0 = (f32x4){__uint_as_float(h.x << 16), __uint_as_float(h.x & 0xffff0000u), __uint_as_float(h.y << 16), __uint_as_float(h.y & 0xffff0000u)};
;                 const f32x4 x1v = (f32x4){__uint_as_float(h.z << 16), __uint_as_float(h.z & 0xffff0000u), __uint_as_float(h.w << 16), __uint_as_float(h.w & 0xffff0000u)};
;                 const f32x4 v0 = acc[ai][bj][m][0] + x0 * r, v1 = acc[ai][bj][m][1] + x1v * r;
;                 u32x4 w; w.x = cvt_pk_bf16(v0[0], v0[1]); w.y = cvt_pk_bf16(v0[2], v0[3]); w.z = cvt_pk_bf16(v1[0], v1[1]); w.w = cvt_pk_bf16(v1[2], v1[3]);
;                 *(u32x4*)(xb + off) = w;
;                 s += (v0[0] * v0[0] + v0[1] * v0[1]) + (v0[2] * v0[2] + v0[3] * v0[3]) + (v1[0] * v1[0] + v1[1] * v1[1]) + (v1[2] * v1[2] + v1[3] * v1[3]); }
;             s += __shfl_xor(s, 16); s += __shfl_xor(s, 32);
;             if (fq == 0) (void)__hip_atomic_fetch_add(racc + row, (1ull << 48) + (unsigned long long)(s * 65536.0f + 0.5f), __ATOMIC_RELAXED, __HIP_MEMORY_SCOPE_AGENT);
;             __builtin_amdgcn_sched_barrier(0); }
	v_add_f32_e32 v180, v180, v169
	ds_bpermute_b32 v169, v157, v180
	s_waitcnt lgkmcnt(0)
	s_and_saveexec_b64 vcc, s[2:3]
	v_add_f32_e32 v180, v180, v169
	v_fma_f32 v180, v180, s66, 0.5
	v_trunc_f32_e32 v180, v180
	v_mul_f32_e32 v181, 0x2f800000, v180
	v_floor_f32_e32 v181, v181
	v_fmac_f32_e32 v180, 0xcf800000, v181
	v_cvt_u32_f32_e32 v181, v181
	v_cvt_u32_f32_e32 v180, v180
	v_add_u32_e32 v181, 0x10000, v181
	global_atomic_add_x2 v[178:179], v[180:181], off offset:1280
	s_mov_b64 exec, vcc
	s_waitcnt vmcnt(7)
	v_lshlrev_b32_e32 v160, 16, v61
	v_and_b32_e32 v161, 0xffff0000, v61
	v_and_b32_e32 v61, 0xffff0000, v60
	v_lshlrev_b32_e32 v60, 16, v60
	v_lshlrev_b32_e32 v162, 16, v63
	v_and_b32_e32 v163, 0xffff0000, v63
	v_and_b32_e32 v63, 0xffff0000, v62
	v_lshlrev_b32_e32 v62, 16, v62
	v_pk_fma_f32 v[12:13], v[158:159], v[60:61], v[12:13] op_sel_hi:[0,1,1]
	v_pk_fma_f32 v[14:15], v[158:159], v[160:161], v[14:15] op_sel_hi:[0,1,1]
	v_pk_fma_f32 v[8:9], v[158:159], v[62:63], v[8:9] op_sel_hi:[0,1,1]
	v_pk_fma_f32 v[10:11], v[158:159], v[162:163], v[10:11] op_sel_hi:[0,1,1]
	v_mul_f32_e32 v168, v13, v13
	v_mul_f32_e32 v169, v15, v15
	v_fmac_f32_e32 v168, v12, v12
	v_fmac_f32_e32 v169, v14, v14
	v_add_f32_e32 v168, v168, v169
	v_mul_f32_e32 v169, v9, v9
	v_fmac_f32_e32 v169, v8, v8
	v_add_f32_e32 v168, v169, v168
	v_mul_f32_e32 v169, v11, v11
	v_fmac_f32_e32 v169, v10, v10
	v_add_f32_e32 v153, v169, v168
	v_cvt_pk_bf16_f32 v60, v12, v13
	v_cvt_pk_bf16_f32 v61, v14, v15
	v_cvt_pk_bf16_f32 v62, v8, v9
	v_cvt_pk_bf16_f32 v63, v10, v11
	global_store_dwordx4 v[174:175], v[60:63], off sc1
	v_lshlrev_b32_e32 v160, 16, v53
	v_and_b32_e32 v161, 0xffff0000, v53
	v_and_b32_e32 v53, 0xffff0000, v52
	v_lshlrev_b32_e32 v52, 16, v52
	v_lshlrev_b32_e32 v162, 16, v55
	v_and_b32_e32 v163, 0xffff0000, v55
	v_and_b32_e32 v55, 0xffff0000, v54
	v_lshlrev_b32_e32 v54, 16, v54
	v_pk_fma_f32 v[4:5], v[158:159], v[52:53], v[4:5] op_sel_hi:[0,1,1]
	v_pk_fma_f32 v[6:7], v[158:159], v[160:161], v[6:7] op_sel_hi:[0,1,1]
	v_pk_fma_f32 v[0:1], v[158:159], v[54:55], v[0:1] op_sel_hi:[0,1,1]
	v_pk_fma_f32 v[2:3], v[158:159], v[162:163], v[2:3] op_sel_hi:[0,1,1]
	v_mul_f32_e32 v168, v5, v5
	v_mul_f32_e32 v169, v7, v7
	v_fmac_f32_e32 v168, v4, v4
	v_fmac_f32_e32 v169, v6, v6
	v_add_f32_e32 v168, v168, v169
	v_mul_f32_e32 v169, v1, v1
	v_fmac_f32_e32 v169, v0, v0
	v_add_f32_e32 v168, v169, v168
	v_mul_f32_e32 v169, v3, v3
	v_fmac_f32_e32 v169, v2, v2
	v_add_f32_e32 v180, v169, v168
	v_cvt_pk_bf16_f32 v52, v4, v5
	v_cvt_pk_bf16_f32 v53, v6, v7
	v_cvt_pk_bf16_f32 v54, v0, v1
	v_cvt_pk_bf16_f32 v55, v2, v3
	global_store_dwordx4 v[174:175], v[52:55], off offset:256 sc1
	v_add_f32_e32 v180, v153, v180
	ds_bpermute_b32 v169, v156, v180
	s_waitcnt lgkmcnt(0)
	v_add_f32_e32 v180, v180, v169
	ds_bpermute_b32 v169, v157, v180
	s_waitcnt lgkmcnt(0)
	s_and_saveexec_b64 vcc, s[2:3]
	v_add_f32_e32 v180, v180, v169
	v_fma_f32 v180, v180, s66, 0.5
	v_trunc_f32_e32 v180, v180
	v_mul_f32_e32 v181, 0x2f800000, v180
	v_floor_f32_e32 v181, v181
	v_fmac_f32_e32 v180, 0xcf800000, v181
	v_cvt_u32_f32_e32 v181, v181
	v_cvt_u32_f32_e32 v180, v180
	v_add_u32_e32 v181, 0x10000, v181
	global_atomic_add_x2 v[178:179], v[180:181], off offset:1408
	s_mov_b64 exec, vcc
	s_andn2_b64 vcc, exec, s[4:5]
	s_mov_b64 s[4:5], -1
	s_cbranch_vccnz .LBB0_472
	s_andn2_b64 vcc, exec, s[6:7]
	s_cbranch_vccnz .LBB0_471
	s_barrier
	s_branch .LBB0_471

; #define PG8_LAS __attribute__((address_space(3)))
; __device__ __forceinline__ unsigned cvt_pk_bf16(float lo, float hi) { unsigned r; asm volatile("v_cvt_pk_bf16_f32 %0, %1, %2" : "=v"(r) : "v"(lo), "v"(hi)); return r; }
;     __device__ __forceinline__ void operator()(const f32x4 (&acc)[2][2][4][2], const Unit& u, int wr, int wc, int fr, int fq, int ui) const {
;         const int row0 = u.pm * BM + wr * 64 + fr, col0 = u.pn * HALF + wc * 32 + 8 * fq;
;         const PG8_LAS unsigned long long* rs = (const PG8_LAS unsigned long long*)(spare + (ui & 1) * 2048) + wr * 64 + fr;
; #pragma unroll
;         for (int st = 0; st < 8; ++st) { const int ai = st >> 2, m = st & 3; const int row = row0 + ai * HALF + m * 16;
;             const float tot = (float)(rs[ai * HALF + m * 16] & 0xffffffffffffull) * (1.0f / 65536.0f);
;             const float rstd = 1.0f / sqrtf(tot * (1.0f / 1024.0f) + 1e-6f);
;             const float kq = -1.4426950408889634f * rstd, r2 = rstd * rstd;
;             unsigned wv[4];
; #pragma unroll
;             for (int h = 0; h < 4; ++h) { const int n = h >> 1, e = 2 * (h & 1);
;                 const f32x2 a2 = (f32x2){acc[ai][0][m][n][e], acc[ai][0][m][n][e + 1]}, b2 = (f32x2){acc[ai][1][m][n][e], acc[ai][1][m][n][e + 1]};
;                 const f32x2 t2 = a2 * kq; f32x2 d2; d2.x = __builtin_amdgcn_exp2f(t2.x); d2.y = __builtin_amdgcn_exp2f(t2.y); d2 = d2 + 1.0f;
;                 f32x2 q2; q2.x = __builtin_amdgcn_rcpf(d2.x); q2.y = __builtin_amdgcn_rcpf(d2.y);
;                 const f32x2 o2 = ((a2 * b2) * r2) * q2;
;                 wv[h] = cvt_pk_bf16(o2.x, o2.y); }
;             u32x4 w; w.x = wv[0]; w.y = wv[1]; w.z = wv[2]; w.w = wv[3];
;             *(u32x4*)(act + (size_t)row * 2816 + col0) = w; }
.LBB0_570:
	s_lshl_b32 s0, s61, 11
	s_and_b32 s0, s0, 0x800
	v_add_u32_e32 v155, s0, v148
	ds_read_b64 v[160:161], v155
	ds_read_b64 v[162:163], v155 offset:128
	ds_read_b64 v[164:165], v155 offset:256
	ds_read_b64 v[166:167], v155 offset:384
	ds_read_b64 v[168:169], v155 offset:1024
	ds_read_b64 v[170:171], v155 offset:1152
	ds_read_b64 v[172:173], v155 offset:1280
	ds_read_b64 v[174:175], v155 offset:1408
	v_lshl_add_u32 v214, s44, 8, v146
	v_mov_b64_e32 v[216:217], s[38:39]
	v_lshl_or_b32 v218, s60, 7, v149
	v_ashrrev_i32_e32 v219, 31, v218
	v_mad_i64_i32 v[212:213], s[0:1], v214, s58, v[216:217]
	v_lshlrev_b64 v[218:219], 1, v[218:219]
	v_lshl_add_u64 v[212:213], v[212:213], 0, v[218:219]
	s_waitcnt lgkmcnt(0)
	v_and_b32_e32 v161, 0xffff, v161
	v_and_b32_e32 v163, 0xffff, v163
	v_and_b32_e32 v165, 0xffff, v165
	v_and_b32_e32 v167, 0xffff, v167
	v_and_b32_e32 v169, 0xffff, v169
	v_and_b32_e32 v171, 0xffff, v171
	v_and_b32_e32 v173, 0xffff, v173
	v_and_b32_e32 v175, 0xffff, v175
	v_cvt_f32_u32_e32 v160, v160
	v_cvt_f32_u32_e32 v162, v162
	v_cvt_f32_u32_e32 v164, v164
	v_cvt_f32_u32_e32 v166, v166
	v_cvt_f32_u32_e32 v168, v168
	v_cvt_f32_u32_e32 v170, v170
	v_cvt_f32_u32_e32 v172, v172
	v_cvt_f32_u32_e32 v174, v174
	v_cvt_f32_u32_e32 v161, v161
	v_cvt_f32_u32_e32 v163, v163
	v_cvt_f32_u32_e32 v165, v165
	v_cvt_f32_u32_e32 v167, v167
	v_cvt_f32_u32_e32 v169, v169
	v_cvt_f32_u32_e32 v171, v171
	v_cvt_f32_u32_e32 v173, v173
	v_cvt_f32_u32_e32 v175, v175
	v_fmamk_f32 v160, v161, 0x4f800000, v160
	v_fmamk_f32 v162, v163, 0x4f800000, v162
	v_fmamk_f32 v164, v165, 0x4f800000, v164
	v_fmamk_f32 v166, v167, 0x4f800000, v166
	v_fmamk_f32 v168, v169, 0x4f800000, v168
	v_fmamk_f32 v170, v171, 0x4f800000, v170
	v_fmamk_f32 v172, v173, 0x4f800000, v172
	v_fmamk_f32 v174, v175, 0x4f800000, v174
	v_fmamk_f32 v177, v160, 0x32800000, v153
	v_fmamk_f32 v179, v162, 0x32800000, v153
	v_fmamk_f32 v181, v164, 0x32800000, v153
	v_fmamk_f32 v183, v166, 0x32800000, v153
	v_fmamk_f32 v185, v168, 0x32800000, v153
	v_fmamk_f32 v187, v170, 0x32800000, v153
	v_fmamk_f32 v189, v172, 0x32800000, v153
	v_fmamk_f32 v191, v174, 0x32800000, v153
	v_rsq_f32_e32 v160, v177
	v_rsq_f32_e32 v162, v179
	v_rsq_f32_e32 v164, v181
	v_rsq_f32_e32 v166, v183
	v_rsq_f32_e32 v168, v185
	v_rsq_f32_e32 v170, v187
	v_rsq_f32_e32 v172, v189
	v_rsq_f32_e32 v174, v191
	v_mul_f32_e32 v161, v177, v160
	v_mul_f32_e32 v163, v179, v162
	v_mul_f32_e32 v165, v181, v164
	v_mul_f32_e32 v167, v183, v166
	v_mul_f32_e32 v169, v185, v168
	v_mul_f32_e32 v171, v187, v170
	v_mul_f32_e32 v173, v189, v172
	v_mul_f32_e32 v175, v191, v174
	v_fma_f32 v161, -v161, v160, 1.0
	v_fma_f32 v163, -v163, v162, 1.0
	v_fma_f32 v165, -v165, v164, 1.0
	v_fma_f32 v167, -v167, v166, 1.0
	v_fma_f32 v169, -v169, v168, 1.0
	v_fma_f32 v171, -v171, v170, 1.0
	v_fma_f32 v173, -v173, v172, 1.0
	v_fma_f32 v175, -v175, v174, 1.0
	v_mul_f32_e32 v176, 0.5, v160
	v_mul_f32_e32 v178, 0.5, v162
	v_mul_f32_e32 v180, 0.5, v164
	v_mul_f32_e32 v182, 0.5, v166
	v_mul_f32_e32 v184, 0.5, v168
	v_mul_f32_e32 v186, 0.5, v170
	v_mul_f32_e32 v188, 0.5, v172
	v_mul_f32_e32 v190, 0.5, v174
	v_fmac_f32_e32 v160, v161, v176
	v_fmac_f32_e32 v162, v163, v178
	v_fmac_f32_e32 v164, v165, v180
	v_fmac_f32_e32 v166, v167, v182
	v_fmac_f32_e32 v168, v169, v184
	v_fmac_f32_e32 v170, v171, v186
	v_fmac_f32_e32 v172, v173, v188
	v_fmac_f32_e32 v174, v175, v190
	v_mul_f32_e32 v176, 0xbfb8aa3b, v160
	v_mul_f32_e32 v178, 0xbfb8aa3b, v162
	v_mul_f32_e32 v180, 0xbfb8aa3b, v164
	v_mul_f32_e32 v182, 0xbfb8aa3b, v166
	v_mul_f32_e32 v184, 0xbfb8aa3b, v168
	v_mul_f32_e32 v186, 0xbfb8aa3b, v170
	v_mul_f32_e32 v188, 0xbfb8aa3b, v172
	v_mul_f32_e32 v190, 0xbfb8aa3b, v174
	v_pk_mul_f32 v[192:193], v[124:125], v[176:177] op_sel_hi:[1,0]
	v_pk_mul_f32 v[194:195], v[126:127], v[176:177] op_sel_hi:[1,0]
	v_pk_mul_f32 v[196:197], v[116:117], v[176:177] op_sel_hi:[1,0]
	v_pk_mul_f32 v[198:199], v[118:119], v[176:177] op_sel_hi:[1,0]
	v_exp_f32_e32 v192, v192
	v_exp_f32_e32 v193, v193
	v_exp_f32_e32 v194, v194
	v_exp_f32_e32 v195, v195
	v_exp_f32_e32 v196, v196
	v_exp_f32_e32 v197, v197
	v_exp_f32_e32 v198, v198
	v_exp_f32_e32 v199, v199
	v_pk_mul_f32 v[120:121], v[124:125], v[120:121]
	v_pk_mul_f32 v[122:123], v[126:127], v[122:123]
	v_pk_mul_f32 v[112:113], v[116:117], v[112:113]
	v_pk_mul_f32 v[114:115], v[118:119], v[114:115]
	v_pk_fma_f32 v[192:193], v[192:193], v[176:177], v[176:177] op_sel:[0,1,1] op_sel_hi:[1,1,1]
	v_pk_fma_f32 v[194:195], v[194:195], v[176:177], v[176:177] op_sel:[0,1,1] op_sel_hi:[1,1,1]
	v_pk_fma_f32 v[196:197], v[196:197], v[176:177], v[176:177] op_sel:[0,1,1] op_sel_hi:[1,1,1]
	v_pk_fma_f32 v[198:199], v[198:199], v[176:177], v[176:177] op_sel:[0,1,1] op_sel_hi:[1,1,1]
	s_mov_b64 s[0:1], 0x16000
	v_rcp_f32_e32 v192, v192
	v_rcp_f32_e32 v193, v193
	v_rcp_f32_e32 v194, v194
	v_rcp_f32_e32 v195, v195
	v_rcp_f32_e32 v196, v196
	v_rcp_f32_e32 v197, v197
	v_rcp_f32_e32 v198, v198
	v_rcp_f32_e32 v199, v199
	v_pk_mul_f32 v[120:121], v[120:121], v[192:193]
	v_pk_mul_f32 v[122:123], v[122:123], v[194:195]
	v_pk_mul_f32 v[112:113], v[112:113], v[196:197]
	v_pk_mul_f32 v[114:115], v[114:115], v[198:199]
	v_cvt_pk_bf16_f32 v200, v120, v121
	v_cvt_pk_bf16_f32 v201, v122, v123
	v_cvt_pk_bf16_f32 v202, v112, v113
	v_cvt_pk_bf16_f32 v203, v114, v115
	global_store_dwordx4 v[212:213], v[200:203], off sc1
	v_pk_mul_f32 v[192:193], v[108:109], v[178:179] op_sel_hi:[1,0]
	v_pk_mul_f32 v[194:195], v[110:111], v[178:179] op_sel_hi:[1,0]
	v_pk_mul_f32 v[196:197], v[100:101], v[178:179] op_sel_hi:[1,0]
	v_pk_mul_f32 v[198:199], v[102:103], v[178:179] op_sel_hi:[1,0]
; __device__ __forceinline__ unsigned cvt_pk_bf16(float lo, float hi) { unsigned r; asm volatile("v_cvt_pk_bf16_f32 %0, %1, %2" : "=v"(r) : "v"(lo), "v"(hi)); return r; }
;     __device__ __forceinline__ void operator()(const f32x4 (&acc)[2][2][4][2], const Unit& u, int wr, int wc, int fr, int fq, int ui) const {
;     ...
;         for (int st = 0; st < 8; ++st) { const int ai = st >> 2, m = st & 3; const int row = row0 + ai * HALF + m * 16;
;             const float tot = (float)(rs[ai * HALF + m * 16] & 0xffffffffffffull) * (1.0f / 65536.0f);
;             const float rstd = 1.0f / sqrtf(tot * (1.0f / 1024.0f) + 1e-6f);
;             const float kq = -1.4426950408889634f * rstd, r2 = rstd * rstd;
;             unsigned wv[4];
; #pragma unroll
;             for (int h = 0; h < 4; ++h) { const int n = h >> 1, e = 2 * (h & 1);
;                 const f32x2 a2 = (f32x2){acc[ai][0][m][n][e], acc[ai][0][m][n][e + 1]}, b2 = (f32x2){acc[ai][1][m][n][e], acc[ai][1][m][n][e + 1]};
;                 const f32x2 t2 = a2 * kq; f32x2 d2; d2.x = __builtin_amdgcn_exp2f(t2.x); d2.y = __builtin_amdgcn_exp2f(t2.y); d2 = d2 + 1.0f;
;                 f32x2 q2; q2.x = __builtin_amdgcn_rcpf(d2.x); q2.y = __builtin_amdgcn_rcpf(d2.y);
;                 const f32x2 o2 = ((a2 * b2) * r2) * q2;
;                 wv[h] = cvt_pk_bf16(o2.x, o2.y); }
;             u32x4 w; w.x = wv[0]; w.y = wv[1]; w.z = wv[2]; w.w = wv[3];
;             *(u32x4*)(act + (size_t)row * 2816 + col0) = w; }
	v_exp_f32_e32 v192, v192
	v_exp_f32_e32 v193, v193
	v_exp_f32_e32 v194, v194
	v_exp_f32_e32 v195, v195
	v_exp_f32_e32 v196, v196
	v_exp_f32_e32 v197, v197
	v_exp_f32_e32 v198, v198
	v_exp_f32_e32 v199, v199
	v_pk_mul_f32 v[104:105], v[108:109], v[104:105]
	v_pk_mul_f32 v[106:107], v[110:111], v[106:107]
	v_pk_mul_f32 v[96:97], v[100:101], v[96:97]
	v_pk_mul_f32 v[98:99], v[102:103], v[98:99]
	v_pk_fma_f32 v[192:193], v[192:193], v[178:179], v[178:179] op_sel:[0,1,1] op_sel_hi:[1,1,1]
	v_pk_fma_f32 v[194:195], v[194:195], v[178:179], v[178:179] op_sel:[0,1,1] op_sel_hi:[1,1,1]
	v_pk_fma_f32 v[196:197], v[196:197], v[178:179], v[178:179] op_sel:[0,1,1] op_sel_hi:[1,1,1]
	v_pk_fma_f32 v[198:199], v[198:199], v[178:179], v[178:179] op_sel:[0,1,1] op_sel_hi:[1,1,1]
	v_lshl_add_u64 v[212:213], v[212:213], 0, s[0:1]
	v_rcp_f32_e32 v192, v192
	v_rcp_f32_e32 v193, v193
	v_rcp_f32_e32 v194, v194
	v_rcp_f32_e32 v195, v195
	v_rcp_f32_e32 v196, v196
	v_rcp_f32_e32 v197, v197
	v_rcp_f32_e32 v198, v198
	v_rcp_f32_e32 v199, v199
	v_pk_mul_f32 v[104:105], v[104:105], v[192:193]
	v_pk_mul_f32 v[106:107], v[106:107], v[194:195]
	v_pk_mul_f32 v[96:97], v[96:97], v[196:197]
	v_pk_mul_f32 v[98:99], v[98:99], v[198:199]
	v_cvt_pk_bf16_f32 v208, v104, v105
	v_cvt_pk_bf16_f32 v209, v106, v107
	v_cvt_pk_bf16_f32 v210, v96, v97
	v_cvt_pk_bf16_f32 v211, v98, v99
	global_store_dwordx4 v[212:213], v[208:211], off sc1
	v_pk_mul_f32 v[192:193], v[92:93], v[180:181] op_sel_hi:[1,0]
	v_pk_mul_f32 v[194:195], v[94:95], v[180:181] op_sel_hi:[1,0]
	v_pk_mul_f32 v[196:197], v[84:85], v[180:181] op_sel_hi:[1,0]
	v_pk_mul_f32 v[198:199], v[86:87], v[180:181] op_sel_hi:[1,0]
	v_exp_f32_e32 v192, v192
	v_exp_f32_e32 v193, v193
	v_exp_f32_e32 v194, v194
	v_exp_f32_e32 v195, v195
	v_exp_f32_e32 v196, v196
	v_exp_f32_e32 v197, v197
	v_exp_f32_e32 v198, v198
	v_exp_f32_e32 v199, v199
	v_pk_mul_f32 v[88:89], v[92:93], v[88:89]
	v_pk_mul_f32 v[90:91], v[94:95], v[90:91]
	v_pk_mul_f32 v[80:81], v[84:85], v[80:81]
	v_pk_mul_f32 v[82:83], v[86:87], v[82:83]
	v_pk_fma_f32 v[192:193], v[192:193], v[180:181], v[180:181] op_sel:[0,1,1] op_sel_hi:[1,1,1]
	v_pk_fma_f32 v[194:195], v[194:195], v[180:181], v[180:181] op_sel:[0,1,1] op_sel_hi:[1,1,1]
	v_pk_fma_f32 v[196:197], v[196:197], v[180:181], v[180:181] op_sel:[0,1,1] op_sel_hi:[1,1,1]
	v_pk_fma_f32 v[198:199], v[198:199], v[180:181], v[180:181] op_sel:[0,1,1] op_sel_hi:[1,1,1]
	v_lshl_add_u64 v[212:213], v[212:213], 0, s[0:1]
	v_rcp_f32_e32 v192, v192
	v_rcp_f32_e32 v193, v193
	v_rcp_f32_e32 v194, v194
	v_rcp_f32_e32 v195, v195
	v_rcp_f32_e32 v196, v196
	v_rcp_f32_e32 v197, v197
	v_rcp_f32_e32 v198, v198
	v_rcp_f32_e32 v199, v199
	v_pk_mul_f32 v[88:89], v[88:89], v[192:193]
	v_pk_mul_f32 v[90:91], v[90:91], v[194:195]
	v_pk_mul_f32 v[80:81], v[80:81], v[196:197]
	v_pk_mul_f32 v[82:83], v[82:83], v[198:199]
	v_cvt_pk_bf16_f32 v200, v88, v89
	v_cvt_pk_bf16_f32 v201, v90, v91
	v_cvt_pk_bf16_f32 v202, v80, v81
	v_cvt_pk_bf16_f32 v203, v82, v83
	global_store_dwordx4 v[212:213], v[200:203], off sc1
	v_pk_mul_f32 v[192:193], v[76:77], v[182:183] op_sel_hi:[1,0]
	v_pk_mul_f32 v[194:195], v[78:79], v[182:183] op_sel_hi:[1,0]
	v_pk_mul_f32 v[196:197], v[68:69], v[182:183] op_sel_hi:[1,0]
	v_pk_mul_f32 v[198:199], v[70:71], v[182:183] op_sel_hi:[1,0]
	v_exp_f32_e32 v192, v192
	v_exp_f32_e32 v193, v193
	v_exp_f32_e32 v194, v194
	v_exp_f32_e32 v195, v195
	v_exp_f32_e32 v196, v196
	v_exp_f32_e32 v197, v197
	v_exp_f32_e32 v198, v198
	v_exp_f32_e32 v199, v199
	v_pk_mul_f32 v[72:73], v[76:77], v[72:73]
	v_pk_mul_f32 v[74:75], v[78:79], v[74:75]
	v_pk_mul_f32 v[64:65], v[68:69], v[64:65]
	v_pk_mul_f32 v[66:67], v[70:71], v[66:67]
	v_pk_fma_f32 v[192:193], v[192:193], v[182:183], v[182:183] op_sel:[0,1,1] op_sel_hi:[1,1,1]
	v_pk_fma_f32 v[194:195], v[194:195], v[182:183], v[182:183] op_sel:[0,1,1] op_sel_hi:[1,1,1]
	v_pk_fma_f32 v[196:197], v[196:197], v[182:183], v[182:183] op_sel:[0,1,1] op_sel_hi:[1,1,1]
	v_pk_fma_f32 v[198:199], v[198:199], v[182:183], v[182:183] op_sel:[0,1,1] op_sel_hi:[1,1,1]
	v_lshl_add_u64 v[212:213], v[212:213], 0, s[0:1]
	v_rcp_f32_e32 v192, v192
	v_rcp_f32_e32 v193, v193
	v_rcp_f32_e32 v194, v194
	v_rcp_f32_e32 v195, v195
	v_rcp_f32_e32 v196, v196
	v_rcp_f32_e32 v197, v197
	v_rcp_f32_e32 v198, v198
	v_rcp_f32_e32 v199, v199
	v_pk_mul_f32 v[72:73], v[72:73], v[192:193]
	v_pk_mul_f32 v[74:75], v[74:75], v[194:195]
	v_pk_mul_f32 v[64:65], v[64:65], v[196:197]
	v_pk_mul_f32 v[66:67], v[66:67], v[198:199]
	v_cvt_pk_bf16_f32 v208, v72, v73
	v_cvt_pk_bf16_f32 v209, v74, v75
	v_cvt_pk_bf16_f32 v210, v64, v65
	v_cvt_pk_bf16_f32 v211, v66, v67
	global_store_dwordx4 v[212:213], v[208:211], off sc1
	v_pk_mul_f32 v[192:193], v[60:61], v[184:185] op_sel_hi:[1,0]
	v_pk_mul_f32 v[194:195], v[62:63], v[184:185] op_sel_hi:[1,0]
	v_pk_mul_f32 v[196:197], v[52:53], v[184:185] op_sel_hi:[1,0]
	v_pk_mul_f32 v[198:199], v[54:55], v[184:185] op_sel_hi:[1,0]
	v_exp_f32_e32 v192, v192
	v_exp_f32_e32 v193, v193
	v_exp_f32_e32 v194, v194
	v_exp_f32_e32 v195, v195
	v_exp_f32_e32 v196, v196
	v_exp_f32_e32 v197, v197
	v_exp_f32_e32 v198, v198
	v_exp_f32_e32 v199, v199
	v_pk_mul_f32 v[56:57], v[60:61], v[56:57]
	v_pk_mul_f32 v[58:59], v[62:63], v[58:59]
	v_pk_mul_f32 v[48:49], v[52:53], v[48:49]
	v_pk_mul_f32 v[50:51], v[54:55], v[50:51]
	v_pk_fma_f32 v[192:193], v[192:193], v[184:185], v[184:185] op_sel:[0,1,1] op_sel_hi:[1,1,1]
	v_pk_fma_f32 v[194:195], v[194:195], v[184:185], v[184:185] op_sel:[0,1,1] op_sel_hi:[1,1,1]
	v_pk_fma_f32 v[196:197], v[196:197], v[184:185], v[184:185] op_sel:[0,1,1] op_sel_hi:[1,1,1]
; #define PG8_LAS __attribute__((address_space(3)))
; __device__ __forceinline__ unsigned cvt_pk_bf16(float lo, float hi) { unsigned r; asm volatile("v_cvt_pk_bf16_f32 %0, %1, %2" : "=v"(r) : "v"(lo), "v"(hi)); return r; }
;     __device__ __forceinline__ void prefetch(const Unit& u, int ui, int wid) const {
;         __builtin_amdgcn_global_load_lds((const unsigned*)(racc + (size_t)u.pm * BM) + threadIdx.x, (PG8_LAS unsigned*)(spare + (ui & 1) * 2048 + wid * 256), 4, 0, 0);
;     }
;     __device__ __forceinline__ void operator()(const f32x4 (&acc)[2][2][4][2], const Unit& u, int wr, int wc, int fr, int fq, int ui) const {
;     ...
;         for (int st = 0; st < 8; ++st) { const int ai = st >> 2, m = st & 3; const int row = row0 + ai * HALF + m * 16;
;             const float tot = (float)(rs[ai * HALF + m * 16] & 0xffffffffffffull) * (1.0f / 65536.0f);
;             const float rstd = 1.0f / sqrtf(tot * (1.0f / 1024.0f) + 1e-6f);
;             const float kq = -1.4426950408889634f * rstd, r2 = rstd * rstd;
;             unsigned wv[4];
; #pragma unroll
;             for (int h = 0; h < 4; ++h) { const int n = h >> 1, e = 2 * (h & 1);
;                 const f32x2 a2 = (f32x2){acc[ai][0][m][n][e], acc[ai][0][m][n][e + 1]}, b2 = (f32x2){acc[ai][1][m][n][e], acc[ai][1][m][n][e + 1]};
;                 const f32x2 t2 = a2 * kq; f32x2 d2; d2.x = __builtin_amdgcn_exp2f(t2.x); d2.y = __builtin_amdgcn_exp2f(t2.y); d2 = d2 + 1.0f;
;                 f32x2 q2; q2.x = __builtin_amdgcn_rcpf(d2.x); q2.y = __builtin_amdgcn_rcpf(d2.y);
;                 const f32x2 o2 = ((a2 * b2) * r2) * q2;
;                 wv[h] = cvt_pk_bf16(o2.x, o2.y); }
;             u32x4 w; w.x = wv[0]; w.y = wv[1]; w.z = wv[2]; w.w = wv[3];
;             *(u32x4*)(act + (size_t)row * 2816 + col0) = w; }
	v_pk_fma_f32 v[198:199], v[198:199], v[184:185], v[184:185] op_sel:[0,1,1] op_sel_hi:[1,1,1]
	s_mov_b64 s[0:1], 0x6e000
	v_lshl_add_u64 v[212:213], v[212:213], 0, s[0:1]
	s_mov_b64 s[0:1], 0x16000
	v_rcp_f32_e32 v192, v192
	v_rcp_f32_e32 v193, v193
	v_rcp_f32_e32 v194, v194
	v_rcp_f32_e32 v195, v195
	v_rcp_f32_e32 v196, v196
	v_rcp_f32_e32 v197, v197
	v_rcp_f32_e32 v198, v198
	v_rcp_f32_e32 v199, v199
	v_pk_mul_f32 v[56:57], v[56:57], v[192:193]
	v_pk_mul_f32 v[58:59], v[58:59], v[194:195]
	v_pk_mul_f32 v[48:49], v[48:49], v[196:197]
	v_pk_mul_f32 v[50:51], v[50:51], v[198:199]
	v_cvt_pk_bf16_f32 v200, v56, v57
	v_cvt_pk_bf16_f32 v201, v58, v59
	v_cvt_pk_bf16_f32 v202, v48, v49
	v_cvt_pk_bf16_f32 v203, v50, v51
	global_store_dwordx4 v[212:213], v[200:203], off sc1
	v_pk_mul_f32 v[192:193], v[44:45], v[186:187] op_sel_hi:[1,0]
	v_pk_mul_f32 v[194:195], v[46:47], v[186:187] op_sel_hi:[1,0]
	v_pk_mul_f32 v[196:197], v[36:37], v[186:187] op_sel_hi:[1,0]
	v_pk_mul_f32 v[198:199], v[38:39], v[186:187] op_sel_hi:[1,0]
	v_exp_f32_e32 v192, v192
	v_exp_f32_e32 v193, v193
	v_exp_f32_e32 v194, v194
	v_exp_f32_e32 v195, v195
	v_exp_f32_e32 v196, v196
	v_exp_f32_e32 v197, v197
	v_exp_f32_e32 v198, v198
	v_exp_f32_e32 v199, v199
	v_pk_mul_f32 v[40:41], v[44:45], v[40:41]
	v_pk_mul_f32 v[42:43], v[46:47], v[42:43]
	v_pk_mul_f32 v[32:33], v[36:37], v[32:33]
	v_pk_mul_f32 v[34:35], v[38:39], v[34:35]
	v_pk_fma_f32 v[192:193], v[192:193], v[186:187], v[186:187] op_sel:[0,1,1] op_sel_hi:[1,1,1]
	v_pk_fma_f32 v[194:195], v[194:195], v[186:187], v[186:187] op_sel:[0,1,1] op_sel_hi:[1,1,1]
	v_pk_fma_f32 v[196:197], v[196:197], v[186:187], v[186:187] op_sel:[0,1,1] op_sel_hi:[1,1,1]
	v_pk_fma_f32 v[198:199], v[198:199], v[186:187], v[186:187] op_sel:[0,1,1] op_sel_hi:[1,1,1]
	v_lshl_add_u64 v[212:213], v[212:213], 0, s[0:1]
	v_rcp_f32_e32 v192, v192
	v_rcp_f32_e32 v193, v193
	v_rcp_f32_e32 v194, v194
	v_rcp_f32_e32 v195, v195
	v_rcp_f32_e32 v196, v196
	v_rcp_f32_e32 v197, v197
	v_rcp_f32_e32 v198, v198
	v_rcp_f32_e32 v199, v199
	v_pk_mul_f32 v[40:41], v[40:41], v[192:193]
	v_pk_mul_f32 v[42:43], v[42:43], v[194:195]
	v_pk_mul_f32 v[32:33], v[32:33], v[196:197]
	v_pk_mul_f32 v[34:35], v[34:35], v[198:199]
	v_cvt_pk_bf16_f32 v208, v40, v41
	v_cvt_pk_bf16_f32 v209, v42, v43
	v_cvt_pk_bf16_f32 v210, v32, v33
	v_cvt_pk_bf16_f32 v211, v34, v35
	global_store_dwordx4 v[212:213], v[208:211], off sc1
	v_pk_mul_f32 v[192:193], v[28:29], v[188:189] op_sel_hi:[1,0]
	v_pk_mul_f32 v[194:195], v[30:31], v[188:189] op_sel_hi:[1,0]
	v_pk_mul_f32 v[196:197], v[20:21], v[188:189] op_sel_hi:[1,0]
	v_pk_mul_f32 v[198:199], v[22:23], v[188:189] op_sel_hi:[1,0]
	v_exp_f32_e32 v192, v192
	v_exp_f32_e32 v193, v193
	v_exp_f32_e32 v194, v194
	v_exp_f32_e32 v195, v195
	v_exp_f32_e32 v196, v196
	v_exp_f32_e32 v197, v197
	v_exp_f32_e32 v198, v198
	v_exp_f32_e32 v199, v199
	v_pk_mul_f32 v[24:25], v[28:29], v[24:25]
	v_pk_mul_f32 v[26:27], v[30:31], v[26:27]
	v_pk_mul_f32 v[16:17], v[20:21], v[16:17]
	v_pk_mul_f32 v[18:19], v[22:23], v[18:19]
	v_pk_fma_f32 v[192:193], v[192:193], v[188:189], v[188:189] op_sel:[0,1,1] op_sel_hi:[1,1,1]
	v_pk_fma_f32 v[194:195], v[194:195], v[188:189], v[188:189] op_sel:[0,1,1] op_sel_hi:[1,1,1]
	v_pk_fma_f32 v[196:197], v[196:197], v[188:189], v[188:189] op_sel:[0,1,1] op_sel_hi:[1,1,1]
	v_pk_fma_f32 v[198:199], v[198:199], v[188:189], v[188:189] op_sel:[0,1,1] op_sel_hi:[1,1,1]
	v_lshl_add_u64 v[212:213], v[212:213], 0, s[0:1]
	v_rcp_f32_e32 v192, v192
	v_rcp_f32_e32 v193, v193
	v_rcp_f32_e32 v194, v194
	v_rcp_f32_e32 v195, v195
	v_rcp_f32_e32 v196, v196
	v_rcp_f32_e32 v197, v197
	v_rcp_f32_e32 v198, v198
	v_rcp_f32_e32 v199, v199
	v_pk_mul_f32 v[24:25], v[24:25], v[192:193]
	v_pk_mul_f32 v[26:27], v[26:27], v[194:195]
	v_pk_mul_f32 v[16:17], v[16:17], v[196:197]
	v_pk_mul_f32 v[18:19], v[18:19], v[198:199]
	v_cvt_pk_bf16_f32 v200, v24, v25
	v_cvt_pk_bf16_f32 v201, v26, v27
	v_cvt_pk_bf16_f32 v202, v16, v17
	v_cvt_pk_bf16_f32 v203, v18, v19
	global_store_dwordx4 v[212:213], v[200:203], off sc1
	v_pk_mul_f32 v[192:193], v[12:13], v[190:191] op_sel_hi:[1,0]
	v_pk_mul_f32 v[194:195], v[14:15], v[190:191] op_sel_hi:[1,0]
	v_pk_mul_f32 v[196:197], v[4:5], v[190:191] op_sel_hi:[1,0]
	v_pk_mul_f32 v[198:199], v[6:7], v[190:191] op_sel_hi:[1,0]
	v_exp_f32_e32 v192, v192
	v_exp_f32_e32 v193, v193
	v_exp_f32_e32 v194, v194
	v_exp_f32_e32 v195, v195
	v_exp_f32_e32 v196, v196
	v_exp_f32_e32 v197, v197
	v_exp_f32_e32 v198, v198
	v_exp_f32_e32 v199, v199
	v_pk_mul_f32 v[8:9], v[12:13], v[8:9]
	v_pk_mul_f32 v[10:11], v[14:15], v[10:11]
	v_pk_mul_f32 v[0:1], v[4:5], v[0:1]
	v_pk_mul_f32 v[2:3], v[6:7], v[2:3]
	v_pk_fma_f32 v[192:193], v[192:193], v[190:191], v[190:191] op_sel:[0,1,1] op_sel_hi:[1,1,1]
	v_pk_fma_f32 v[194:195], v[194:195], v[190:191], v[190:191] op_sel:[0,1,1] op_sel_hi:[1,1,1]
	v_pk_fma_f32 v[196:197], v[196:197], v[190:191], v[190:191] op_sel:[0,1,1] op_sel_hi:[1,1,1]
	v_pk_fma_f32 v[198:199], v[198:199], v[190:191], v[190:191] op_sel:[0,1,1] op_sel_hi:[1,1,1]
	v_lshl_add_u64 v[212:213], v[212:213], 0, s[0:1]
	v_rcp_f32_e32 v192, v192
	v_rcp_f32_e32 v193, v193
	v_rcp_f32_e32 v194, v194
	v_rcp_f32_e32 v195, v195
	v_rcp_f32_e32 v196, v196
	v_rcp_f32_e32 v197, v197
	v_rcp_f32_e32 v198, v198
	v_rcp_f32_e32 v199, v199
	v_pk_mul_f32 v[8:9], v[8:9], v[192:193]
	v_pk_mul_f32 v[10:11], v[10:11], v[194:195]
	v_pk_mul_f32 v[0:1], v[0:1], v[196:197]
	v_pk_mul_f32 v[2:3], v[2:3], v[198:199]
	v_cvt_pk_bf16_f32 v208, v8, v9
	v_cvt_pk_bf16_f32 v209, v10, v11
	v_cvt_pk_bf16_f32 v210, v0, v1
	v_cvt_pk_bf16_f32 v211, v2, v3
	global_store_dwordx4 v[212:213], v[208:211], off sc1
	s_andn2_b64 vcc, exec, s[2:3]
	s_mov_b64 s[0:1], -1
	s_cbranch_vccnz .LBB0_563
	s_lshl_b64 s[0:1], s[16:17], 11
	v_lshl_add_u64 v[0:1], v[136:137], 0, s[0:1]
	s_lshl_b32 s0, s59, 11
	s_and_b32 s0, s0, 0x800
	s_add_i32 m0, s23, s0
	s_andn2_b64 vcc, exec, s[6:7]
	global_load_lds_dword v[0:1], off
	s_cbranch_vccnz .LBB0_562
	s_barrier
	s_branch .LBB0_562
